# prologue weight/x/p conversion: streaming f32 reads marked nt (read once, keeps them from displacing the bf16 outputs in L2)
# speedup vs baseline: 1.0162x; 1.0050x over previous
.LBB0_10:
	s_ashr_i32 s3, s1, 31
	s_lshr_b32 s3, s3, 26
	s_add_i32 s4, s1, s3
	s_ashr_i32 s3, s4, 6
	s_lshl_b32 s3, s3, 13
	v_subrev_u32_e32 v42, s3, v152
	s_and_b32 s36, s4, 0xffffffc0
	v_ashrrev_i32_e32 v43, 31, v42
	s_ashr_i32 s37, s36, 31
	v_lshl_add_u64 v[2:3], v[42:43], 2, s[30:31]
	s_lshl_b64 s[4:5], s[36:37], 15
	v_lshl_add_u64 v[4:5], v[2:3], 0, s[4:5]
	s_or_b32 s4, s36, 1
	s_ashr_i32 s5, s4, 31
	s_lshl_b64 s[4:5], s[4:5], 15
	v_lshl_add_u64 v[6:7], v[2:3], 0, s[4:5]
	s_or_b32 s4, s36, 2
	s_ashr_i32 s5, s4, 31
	s_lshl_b64 s[4:5], s[4:5], 15
	v_lshl_add_u64 v[8:9], v[2:3], 0, s[4:5]
	s_or_b32 s4, s36, 3
	s_ashr_i32 s5, s4, 31
	s_lshl_b64 s[4:5], s[4:5], 15
	v_lshl_add_u64 v[10:11], v[2:3], 0, s[4:5]
	s_or_b32 s4, s36, 4
	s_ashr_i32 s5, s4, 31
	s_lshl_b64 s[4:5], s[4:5], 15
	global_load_dwordx2 v[18:19], v[4:5], off nt
	global_load_dwordx2 v[22:23], v[6:7], off nt
	global_load_dwordx2 v[20:21], v[8:9], off nt
	global_load_dwordx2 v[24:25], v[10:11], off nt
	v_lshl_add_u64 v[4:5], v[2:3], 0, s[4:5]
	s_or_b32 s4, s36, 5
	s_ashr_i32 s5, s4, 31
	s_lshl_b64 s[4:5], s[4:5], 15
	v_lshl_add_u64 v[6:7], v[2:3], 0, s[4:5]
	s_or_b32 s4, s36, 6
	s_ashr_i32 s5, s4, 31
	s_lshl_b64 s[4:5], s[4:5], 15
	v_lshl_add_u64 v[8:9], v[2:3], 0, s[4:5]
	s_or_b32 s4, s36, 7
	s_ashr_i32 s5, s4, 31
	s_lshl_b64 s[4:5], s[4:5], 15
	v_lshl_add_u64 v[10:11], v[2:3], 0, s[4:5]
	s_or_b32 s4, s36, 8
	s_ashr_i32 s5, s4, 31
	s_lshl_b64 s[4:5], s[4:5], 15
	global_load_dwordx2 v[26:27], v[4:5], off nt
	global_load_dwordx2 v[30:31], v[6:7], off nt
	global_load_dwordx2 v[28:29], v[8:9], off nt
	global_load_dwordx2 v[32:33], v[10:11], off nt
	v_lshl_add_u64 v[4:5], v[2:3], 0, s[4:5]
	s_or_b32 s4, s36, 9
	s_ashr_i32 s5, s4, 31
	s_lshl_b64 s[4:5], s[4:5], 15
	v_lshl_add_u64 v[6:7], v[2:3], 0, s[4:5]
	s_or_b32 s4, s36, 10
	s_ashr_i32 s5, s4, 31
	s_lshl_b64 s[4:5], s[4:5], 15
	v_lshl_add_u64 v[8:9], v[2:3], 0, s[4:5]
	s_or_b32 s4, s36, 11
	s_ashr_i32 s5, s4, 31
	s_lshl_b64 s[4:5], s[4:5], 15
	v_lshl_add_u64 v[10:11], v[2:3], 0, s[4:5]
	s_or_b32 s4, s36, 12
	s_ashr_i32 s5, s4, 31
	s_lshl_b64 s[4:5], s[4:5], 15
	global_load_dwordx2 v[34:35], v[4:5], off nt
	global_load_dwordx2 v[38:39], v[6:7], off nt
	global_load_dwordx2 v[36:37], v[8:9], off nt
	global_load_dwordx2 v[40:41], v[10:11], off nt
	v_lshl_add_u64 v[4:5], v[2:3], 0, s[4:5]
	s_or_b32 s4, s36, 13
	s_ashr_i32 s5, s4, 31
	s_lshl_b64 s[4:5], s[4:5], 15
	v_lshl_add_u64 v[6:7], v[2:3], 0, s[4:5]
	s_or_b32 s4, s36, 14
	s_ashr_i32 s5, s4, 31
	s_lshl_b64 s[4:5], s[4:5], 15
	v_lshl_add_u64 v[8:9], v[2:3], 0, s[4:5]
	s_or_b32 s4, s36, 15
	s_ashr_i32 s5, s4, 31
	s_lshl_b64 s[4:5], s[4:5], 15
	v_lshl_add_u64 v[10:11], v[2:3], 0, s[4:5]
	s_or_b32 s4, s36, 16
	s_ashr_i32 s5, s4, 31
	s_lshl_b64 s[4:5], s[4:5], 15
	global_load_dwordx2 v[44:45], v[4:5], off nt
	global_load_dwordx2 v[48:49], v[6:7], off nt
	global_load_dwordx2 v[46:47], v[8:9], off nt
	global_load_dwordx2 v[50:51], v[10:11], off nt
	v_lshl_add_u64 v[4:5], v[2:3], 0, s[4:5]
	s_or_b32 s4, s36, 17
	s_ashr_i32 s5, s4, 31
	s_lshl_b64 s[4:5], s[4:5], 15
	v_lshl_add_u64 v[6:7], v[2:3], 0, s[4:5]
	s_or_b32 s4, s36, 18
	s_ashr_i32 s5, s4, 31
	s_lshl_b64 s[4:5], s[4:5], 15
	v_lshl_add_u64 v[8:9], v[2:3], 0, s[4:5]
	s_or_b32 s4, s36, 19
	s_ashr_i32 s5, s4, 31
	s_lshl_b64 s[4:5], s[4:5], 15
	v_lshl_add_u64 v[10:11], v[2:3], 0, s[4:5]
	s_or_b32 s4, s36, 20
	s_ashr_i32 s5, s4, 31
	s_lshl_b64 s[4:5], s[4:5], 15
	global_load_dwordx2 v[52:53], v[4:5], off nt
	global_load_dwordx2 v[56:57], v[6:7], off nt
	global_load_dwordx2 v[54:55], v[8:9], off nt
	global_load_dwordx2 v[58:59], v[10:11], off nt
	v_lshl_add_u64 v[4:5], v[2:3], 0, s[4:5]
	s_or_b32 s4, s36, 21
	s_ashr_i32 s5, s4, 31
	s_lshl_b64 s[4:5], s[4:5], 15
	v_lshl_add_u64 v[6:7], v[2:3], 0, s[4:5]
	s_or_b32 s4, s36, 22
	s_ashr_i32 s5, s4, 31
	s_lshl_b64 s[4:5], s[4:5], 15
	v_lshl_add_u64 v[8:9], v[2:3], 0, s[4:5]
	s_or_b32 s4, s36, 23
	s_ashr_i32 s5, s4, 31
	s_lshl_b64 s[4:5], s[4:5], 15
	v_lshl_add_u64 v[10:11], v[2:3], 0, s[4:5]
	s_or_b32 s4, s36, 24
	s_ashr_i32 s5, s4, 31
	s_lshl_b64 s[4:5], s[4:5], 15
	global_load_dwordx2 v[60:61], v[4:5], off nt
	global_load_dwordx2 v[64:65], v[6:7], off nt
	global_load_dwordx2 v[62:63], v[8:9], off nt
	global_load_dwordx2 v[66:67], v[10:11], off nt
	v_lshl_add_u64 v[4:5], v[2:3], 0, s[4:5]
	s_or_b32 s4, s36, 25
	s_ashr_i32 s5, s4, 31
	s_lshl_b64 s[4:5], s[4:5], 15
	v_lshl_add_u64 v[6:7], v[2:3], 0, s[4:5]
	s_or_b32 s4, s36, 26
	s_ashr_i32 s5, s4, 31
	s_lshl_b64 s[4:5], s[4:5], 15
	v_lshl_add_u64 v[8:9], v[2:3], 0, s[4:5]
	s_or_b32 s4, s36, 27
	s_ashr_i32 s5, s4, 31
	s_lshl_b64 s[4:5], s[4:5], 15
	v_lshl_add_u64 v[10:11], v[2:3], 0, s[4:5]
	s_or_b32 s4, s36, 28
	s_ashr_i32 s5, s4, 31
	s_lshl_b64 s[4:5], s[4:5], 15
	global_load_dwordx2 v[68:69], v[4:5], off nt
	global_load_dwordx2 v[72:73], v[6:7], off nt
	global_load_dwordx2 v[70:71], v[8:9], off nt
	global_load_dwordx2 v[74:75], v[10:11], off nt
	v_lshl_add_u64 v[4:5], v[2:3], 0, s[4:5]
	s_or_b32 s4, s36, 29
	s_ashr_i32 s5, s4, 31
	s_lshl_b64 s[4:5], s[4:5], 15
	v_lshl_add_u64 v[6:7], v[2:3], 0, s[4:5]
	s_or_b32 s4, s36, 30
	s_ashr_i32 s5, s4, 31
	s_lshl_b64 s[4:5], s[4:5], 15
	v_lshl_add_u64 v[8:9], v[2:3], 0, s[4:5]
	s_or_b32 s4, s36, 31
	s_ashr_i32 s5, s4, 31
	s_lshl_b64 s[4:5], s[4:5], 15
	v_lshl_add_u64 v[10:11], v[2:3], 0, s[4:5]
	s_or_b32 s4, s36, 32
	s_ashr_i32 s5, s4, 31
	s_lshl_b64 s[4:5], s[4:5], 15
	global_load_dwordx2 v[76:77], v[4:5], off nt
	global_load_dwordx2 v[80:81], v[6:7], off nt
	global_load_dwordx2 v[78:79], v[8:9], off nt
	global_load_dwordx2 v[82:83], v[10:11], off nt
	v_lshl_add_u64 v[4:5], v[2:3], 0, s[4:5]
	s_or_b32 s4, s36, 33
	s_ashr_i32 s5, s4, 31
	s_lshl_b64 s[4:5], s[4:5], 15
	v_lshl_add_u64 v[6:7], v[2:3], 0, s[4:5]
	s_or_b32 s4, s36, 34
	s_ashr_i32 s5, s4, 31
	s_lshl_b64 s[4:5], s[4:5], 15
	v_lshl_add_u64 v[8:9], v[2:3], 0, s[4:5]
	s_or_b32 s4, s36, 35
	s_ashr_i32 s5, s4, 31
	s_lshl_b64 s[4:5], s[4:5], 15
	v_lshl_add_u64 v[10:11], v[2:3], 0, s[4:5]
	s_or_b32 s4, s36, 36
	s_ashr_i32 s5, s4, 31
	s_lshl_b64 s[4:5], s[4:5], 15
	global_load_dwordx2 v[84:85], v[4:5], off nt
	global_load_dwordx2 v[88:89], v[6:7], off nt
	global_load_dwordx2 v[86:87], v[8:9], off nt
	global_load_dwordx2 v[90:91], v[10:11], off nt
	v_lshl_add_u64 v[4:5], v[2:3], 0, s[4:5]
	s_or_b32 s4, s36, 37
	s_ashr_i32 s5, s4, 31
	s_lshl_b64 s[4:5], s[4:5], 15
	v_lshl_add_u64 v[6:7], v[2:3], 0, s[4:5]
	s_or_b32 s4, s36, 38
	s_ashr_i32 s5, s4, 31
	s_lshl_b64 s[4:5], s[4:5], 15
	v_lshl_add_u64 v[8:9], v[2:3], 0, s[4:5]
	s_or_b32 s4, s36, 39
	s_ashr_i32 s5, s4, 31
	s_lshl_b64 s[4:5], s[4:5], 15
	v_lshl_add_u64 v[10:11], v[2:3], 0, s[4:5]
	s_or_b32 s4, s36, 40
	s_ashr_i32 s5, s4, 31
	s_lshl_b64 s[4:5], s[4:5], 15
	global_load_dwordx2 v[92:93], v[4:5], off nt
	global_load_dwordx2 v[96:97], v[6:7], off nt
	global_load_dwordx2 v[94:95], v[8:9], off nt
	global_load_dwordx2 v[98:99], v[10:11], off nt
	v_lshl_add_u64 v[4:5], v[2:3], 0, s[4:5]
	s_or_b32 s4, s36, 41
	s_ashr_i32 s5, s4, 31
	s_lshl_b64 s[4:5], s[4:5], 15
	v_lshl_add_u64 v[6:7], v[2:3], 0, s[4:5]
	s_or_b32 s4, s36, 42
	s_ashr_i32 s5, s4, 31
	s_lshl_b64 s[4:5], s[4:5], 15
	v_lshl_add_u64 v[8:9], v[2:3], 0, s[4:5]
	s_or_b32 s4, s36, 43
	s_ashr_i32 s5, s4, 31
	s_lshl_b64 s[4:5], s[4:5], 15
	v_lshl_add_u64 v[10:11], v[2:3], 0, s[4:5]
	s_or_b32 s4, s36, 44
	s_ashr_i32 s5, s4, 31
	s_lshl_b64 s[4:5], s[4:5], 15
	global_load_dwordx2 v[100:101], v[4:5], off nt
	global_load_dwordx2 v[104:105], v[6:7], off nt
	global_load_dwordx2 v[102:103], v[8:9], off nt
	global_load_dwordx2 v[106:107], v[10:11], off nt
	v_lshl_add_u64 v[4:5], v[2:3], 0, s[4:5]
	s_or_b32 s4, s36, 45
	s_ashr_i32 s5, s4, 31
	s_lshl_b64 s[4:5], s[4:5], 15
	v_lshl_add_u64 v[6:7], v[2:3], 0, s[4:5]
	s_or_b32 s4, s36, 46
	s_ashr_i32 s5, s4, 31
	s_lshl_b64 s[4:5], s[4:5], 15
	v_lshl_add_u64 v[8:9], v[2:3], 0, s[4:5]
	s_or_b32 s4, s36, 47
	s_ashr_i32 s5, s4, 31
	s_lshl_b64 s[4:5], s[4:5], 15
	v_lshl_add_u64 v[10:11], v[2:3], 0, s[4:5]
	s_or_b32 s4, s36, 48
	s_ashr_i32 s5, s4, 31
	s_lshl_b64 s[4:5], s[4:5], 15
	global_load_dwordx2 v[108:109], v[4:5], off nt
	global_load_dwordx2 v[112:113], v[6:7], off nt
	global_load_dwordx2 v[110:111], v[8:9], off nt
	global_load_dwordx2 v[114:115], v[10:11], off nt
	v_lshl_add_u64 v[4:5], v[2:3], 0, s[4:5]
	s_or_b32 s4, s36, 49
	s_ashr_i32 s5, s4, 31
	s_lshl_b64 s[4:5], s[4:5], 15
	v_lshl_add_u64 v[6:7], v[2:3], 0, s[4:5]
	s_or_b32 s4, s36, 50
	s_ashr_i32 s5, s4, 31
	s_lshl_b64 s[4:5], s[4:5], 15
	v_lshl_add_u64 v[8:9], v[2:3], 0, s[4:5]
	s_or_b32 s4, s36, 51
	s_ashr_i32 s5, s4, 31
	s_lshl_b64 s[4:5], s[4:5], 15
	v_lshl_add_u64 v[10:11], v[2:3], 0, s[4:5]
	s_or_b32 s4, s36, 52
	s_ashr_i32 s5, s4, 31
	s_lshl_b64 s[4:5], s[4:5], 15
	global_load_dwordx2 v[116:117], v[4:5], off nt
	global_load_dwordx2 v[120:121], v[6:7], off nt
	global_load_dwordx2 v[118:119], v[8:9], off nt
	global_load_dwordx2 v[122:123], v[10:11], off nt
	v_lshl_add_u64 v[4:5], v[2:3], 0, s[4:5]
	s_or_b32 s4, s36, 53
	s_ashr_i32 s5, s4, 31
	s_lshl_b64 s[4:5], s[4:5], 15
	v_lshl_add_u64 v[6:7], v[2:3], 0, s[4:5]
	s_or_b32 s4, s36, 54
	s_ashr_i32 s5, s4, 31
	s_lshl_b64 s[4:5], s[4:5], 15
	v_lshl_add_u64 v[8:9], v[2:3], 0, s[4:5]
	s_or_b32 s4, s36, 55
	s_ashr_i32 s5, s4, 31
	s_lshl_b64 s[4:5], s[4:5], 15
	v_lshl_add_u64 v[10:11], v[2:3], 0, s[4:5]
	s_or_b32 s4, s36, 56
	s_ashr_i32 s5, s4, 31
	s_lshl_b64 s[4:5], s[4:5], 15
	global_load_dwordx2 v[124:125], v[4:5], off nt
	global_load_dwordx2 v[128:129], v[6:7], off nt
	global_load_dwordx2 v[126:127], v[8:9], off nt
	global_load_dwordx2 v[130:131], v[10:11], off nt
	v_lshl_add_u64 v[4:5], v[2:3], 0, s[4:5]
	s_or_b32 s4, s36, 57
	s_ashr_i32 s5, s4, 31
	s_lshl_b64 s[4:5], s[4:5], 15
	v_lshl_add_u64 v[6:7], v[2:3], 0, s[4:5]
	s_or_b32 s4, s36, 58
	s_ashr_i32 s5, s4, 31
	s_lshl_b64 s[4:5], s[4:5], 15
	v_lshl_add_u64 v[8:9], v[2:3], 0, s[4:5]
	s_or_b32 s4, s36, 59
	s_ashr_i32 s5, s4, 31
	s_lshl_b64 s[4:5], s[4:5], 15
	v_lshl_add_u64 v[10:11], v[2:3], 0, s[4:5]
	s_or_b32 s4, s36, 60
	s_ashr_i32 s5, s4, 31
	s_or_b32 s6, s36, 61
	s_or_b32 s12, s36, 62
	s_or_b32 s14, s36, 63
	s_lshl_b64 s[4:5], s[4:5], 15
	s_ashr_i32 s7, s6, 31
	s_ashr_i32 s13, s12, 31
	s_ashr_i32 s15, s14, 31
	global_load_dwordx2 v[132:133], v[4:5], off nt
	global_load_dwordx2 v[136:137], v[6:7], off nt
	global_load_dwordx2 v[134:135], v[8:9], off nt
	global_load_dwordx2 v[138:139], v[10:11], off nt
	s_lshl_b64 s[6:7], s[6:7], 15
	s_lshl_b64 s[12:13], s[12:13], 15
	s_lshl_b64 s[14:15], s[14:15], 15
	v_lshl_add_u64 v[4:5], v[2:3], 0, s[4:5]
	v_lshl_add_u64 v[6:7], v[2:3], 0, s[6:7]
	v_lshl_add_u64 v[8:9], v[2:3], 0, s[12:13]
	v_lshl_add_u64 v[2:3], v[2:3], 0, s[14:15]
	global_load_dwordx2 v[140:141], v[4:5], off nt
	global_load_dwordx2 v[144:145], v[6:7], off nt
	global_load_dwordx2 v[142:143], v[8:9], off nt
	global_load_dwordx2 v[146:147], v[2:3], off nt
	s_andn2_b64 vcc, exec, s[16:17]
	s_cbranch_vccnz .LBB0_9
	s_lshl_b64 s[4:5], s[36:37], 2
	s_add_u32 s6, s9, s4
	s_addc_u32 s7, s10, s5
	global_load_dwordx4 v[2:5], v149, s[6:7] offset:48
	global_load_dwordx4 v[6:9], v149, s[6:7] offset:32
	global_load_dwordx4 v[10:13], v149, s[6:7] offset:16
	global_load_dwordx4 v[154:157], v149, s[6:7]
	s_waitcnt vmcnt(3)
	v_pk_mul_f32 v[44:45], v[44:45], v[2:3] op_sel_hi:[1,0]
	s_waitcnt vmcnt(2)
	v_pk_mul_f32 v[34:35], v[34:35], v[6:7] op_sel_hi:[1,0]
	s_waitcnt vmcnt(1)
	v_pk_mul_f32 v[26:27], v[26:27], v[10:11] op_sel_hi:[1,0]
	s_waitcnt vmcnt(0)
	v_pk_mul_f32 v[18:19], v[18:19], v[154:155] op_sel_hi:[1,0]
	v_pk_mul_f32 v[22:23], v[22:23], v[154:155] op_sel:[0,1]
	v_mov_b32_e32 v154, v157
	v_pk_mul_f32 v[30:31], v[30:31], v[10:11] op_sel:[0,1]
	v_mov_b32_e32 v10, v13
	v_pk_mul_f32 v[38:39], v[38:39], v[6:7] op_sel:[0,1]
	v_mov_b32_e32 v6, v9
	v_pk_mul_f32 v[48:49], v[48:49], v[2:3] op_sel:[0,1]
	v_mov_b32_e32 v2, v5
	v_pk_mul_f32 v[20:21], v[20:21], v[156:157] op_sel_hi:[1,0]
	v_pk_mul_f32 v[24:25], v[24:25], v[154:155] op_sel_hi:[1,0]
	v_pk_mul_f32 v[28:29], v[28:29], v[12:13] op_sel_hi:[1,0]
	v_pk_mul_f32 v[32:33], v[32:33], v[10:11] op_sel_hi:[1,0]
	v_pk_mul_f32 v[36:37], v[36:37], v[8:9] op_sel_hi:[1,0]
	v_pk_mul_f32 v[40:41], v[40:41], v[6:7] op_sel_hi:[1,0]
	v_pk_mul_f32 v[46:47], v[46:47], v[4:5] op_sel_hi:[1,0]
	v_pk_mul_f32 v[50:51], v[50:51], v[2:3] op_sel_hi:[1,0]
	global_load_dwordx4 v[2:5], v149, s[6:7] offset:112
	global_load_dwordx4 v[6:9], v149, s[6:7] offset:96
	global_load_dwordx4 v[10:13], v149, s[6:7] offset:80
	global_load_dwordx4 v[154:157], v149, s[6:7] offset:64
	s_waitcnt vmcnt(3)
	v_pk_mul_f32 v[76:77], v[76:77], v[2:3] op_sel_hi:[1,0]
	s_waitcnt vmcnt(2)
	v_pk_mul_f32 v[68:69], v[68:69], v[6:7] op_sel_hi:[1,0]
	s_waitcnt vmcnt(1)
	v_pk_mul_f32 v[60:61], v[60:61], v[10:11] op_sel_hi:[1,0]
	s_waitcnt vmcnt(0)
	v_pk_mul_f32 v[52:53], v[52:53], v[154:155] op_sel_hi:[1,0]
	v_pk_mul_f32 v[56:57], v[56:57], v[154:155] op_sel:[0,1]
	v_mov_b32_e32 v154, v157
	v_pk_mul_f32 v[64:65], v[64:65], v[10:11] op_sel:[0,1]
	v_mov_b32_e32 v10, v13
	v_pk_mul_f32 v[72:73], v[72:73], v[6:7] op_sel:[0,1]
	v_mov_b32_e32 v6, v9
	v_pk_mul_f32 v[80:81], v[80:81], v[2:3] op_sel:[0,1]
	v_mov_b32_e32 v2, v5
	v_pk_mul_f32 v[54:55], v[54:55], v[156:157] op_sel_hi:[1,0]
	v_pk_mul_f32 v[58:59], v[58:59], v[154:155] op_sel_hi:[1,0]
	v_pk_mul_f32 v[62:63], v[62:63], v[12:13] op_sel_hi:[1,0]
	v_pk_mul_f32 v[66:67], v[66:67], v[10:11] op_sel_hi:[1,0]
	v_pk_mul_f32 v[70:71], v[70:71], v[8:9] op_sel_hi:[1,0]
	v_pk_mul_f32 v[74:75], v[74:75], v[6:7] op_sel_hi:[1,0]
	v_pk_mul_f32 v[78:79], v[78:79], v[4:5] op_sel_hi:[1,0]
	v_pk_mul_f32 v[82:83], v[82:83], v[2:3] op_sel_hi:[1,0]
	global_load_dwordx4 v[2:5], v149, s[6:7] offset:176
	global_load_dwordx4 v[6:9], v149, s[6:7] offset:160
	global_load_dwordx4 v[10:13], v149, s[6:7] offset:144
	global_load_dwordx4 v[154:157], v149, s[6:7] offset:128
	s_waitcnt vmcnt(3)
	v_pk_mul_f32 v[108:109], v[108:109], v[2:3] op_sel_hi:[1,0]
	s_waitcnt vmcnt(2)
	v_pk_mul_f32 v[100:101], v[100:101], v[6:7] op_sel_hi:[1,0]
	s_waitcnt vmcnt(1)
	v_pk_mul_f32 v[92:93], v[92:93], v[10:11] op_sel_hi:[1,0]
	s_waitcnt vmcnt(0)
	v_pk_mul_f32 v[84:85], v[84:85], v[154:155] op_sel_hi:[1,0]
	v_pk_mul_f32 v[88:89], v[88:89], v[154:155] op_sel:[0,1]
	v_mov_b32_e32 v154, v157
	v_pk_mul_f32 v[96:97], v[96:97], v[10:11] op_sel:[0,1]
	v_mov_b32_e32 v10, v13
	v_pk_mul_f32 v[104:105], v[104:105], v[6:7] op_sel:[0,1]
	v_mov_b32_e32 v6, v9
	v_pk_mul_f32 v[112:113], v[112:113], v[2:3] op_sel:[0,1]
	v_mov_b32_e32 v2, v5
	v_pk_mul_f32 v[86:87], v[86:87], v[156:157] op_sel_hi:[1,0]
	v_pk_mul_f32 v[90:91], v[90:91], v[154:155] op_sel_hi:[1,0]
	v_pk_mul_f32 v[94:95], v[94:95], v[12:13] op_sel_hi:[1,0]
	v_pk_mul_f32 v[98:99], v[98:99], v[10:11] op_sel_hi:[1,0]
	v_pk_mul_f32 v[102:103], v[102:103], v[8:9] op_sel_hi:[1,0]
	v_pk_mul_f32 v[106:107], v[106:107], v[6:7] op_sel_hi:[1,0]
	v_pk_mul_f32 v[110:111], v[110:111], v[4:5] op_sel_hi:[1,0]
	v_pk_mul_f32 v[114:115], v[114:115], v[2:3] op_sel_hi:[1,0]
	global_load_dwordx4 v[2:5], v149, s[6:7] offset:240
	global_load_dwordx4 v[6:9], v149, s[6:7] offset:224
	global_load_dwordx4 v[10:13], v149, s[6:7] offset:208
	global_load_dwordx4 v[154:157], v149, s[6:7] offset:192
	s_waitcnt vmcnt(3)
	v_pk_mul_f32 v[140:141], v[140:141], v[2:3] op_sel_hi:[1,0]
	s_waitcnt vmcnt(2)
	v_pk_mul_f32 v[132:133], v[132:133], v[6:7] op_sel_hi:[1,0]
	s_waitcnt vmcnt(1)
	v_pk_mul_f32 v[124:125], v[124:125], v[10:11] op_sel_hi:[1,0]
	s_waitcnt vmcnt(0)
	v_pk_mul_f32 v[116:117], v[116:117], v[154:155] op_sel_hi:[1,0]
	v_pk_mul_f32 v[120:121], v[120:121], v[154:155] op_sel:[0,1]
	v_mov_b32_e32 v154, v157
	v_pk_mul_f32 v[128:129], v[128:129], v[10:11] op_sel:[0,1]
	v_mov_b32_e32 v10, v13
	v_pk_mul_f32 v[136:137], v[136:137], v[6:7] op_sel:[0,1]
	v_mov_b32_e32 v6, v9
	v_pk_mul_f32 v[144:145], v[144:145], v[2:3] op_sel:[0,1]
	v_mov_b32_e32 v2, v5
	v_pk_mul_f32 v[118:119], v[118:119], v[156:157] op_sel_hi:[1,0]
	v_pk_mul_f32 v[122:123], v[122:123], v[154:155] op_sel_hi:[1,0]
	v_pk_mul_f32 v[126:127], v[126:127], v[12:13] op_sel_hi:[1,0]
	v_pk_mul_f32 v[130:131], v[130:131], v[10:11] op_sel_hi:[1,0]
	v_pk_mul_f32 v[134:135], v[134:135], v[8:9] op_sel_hi:[1,0]
	v_pk_mul_f32 v[138:139], v[138:139], v[6:7] op_sel_hi:[1,0]
	v_pk_mul_f32 v[142:143], v[142:143], v[4:5] op_sel_hi:[1,0]
	v_pk_mul_f32 v[146:147], v[146:147], v[2:3] op_sel_hi:[1,0]
	s_branch .LBB0_9

.LBB0_15:
	s_ashr_i32 s5, s3, 31
	s_lshr_b32 s5, s5, 29
	s_add_i32 s5, s3, s5
	s_ashr_i32 s5, s5, 3
	s_lshl_b32 s6, s5, 10
	s_lshl_b32 s38, s5, 6
	v_subrev_u32_e32 v2, s6, v56
	s_or_b32 s92, s38, 1
	s_or_b32 s94, s38, 2
	s_or_b32 vcc_lo, s38, 3
	s_or_b32 s6, s38, 4
	s_or_b32 s8, s38, 5
	s_or_b32 s10, s38, 6
	s_or_b32 s12, s38, 7
	s_or_b32 s14, s38, 8
	s_or_b32 s16, s38, 9
	s_or_b32 s18, s38, 10
	s_or_b32 s20, s38, 11
	s_or_b32 s22, s38, 12
	s_or_b32 s48, s38, 13
	s_or_b32 s54, s38, 14
	s_or_b32 s58, s38, 15
	s_or_b32 s34, s38, 16
	s_or_b32 s30, s38, 17
	s_or_b32 s62, s38, 18
	s_or_b32 s60, s38, 19
	s_or_b32 s56, s38, 20
	s_or_b32 s52, s38, 21
	s_or_b32 s50, s38, 22
	s_or_b32 s78, s38, 23
	s_ashr_i32 s39, s38, 31
	s_or_b32 s76, s38, 24
	v_ashrrev_i32_e32 v3, 31, v2
	s_ashr_i32 s93, s92, 31
	s_ashr_i32 s95, s94, 31
	s_ashr_i32 vcc_hi, vcc_lo, 31
	s_ashr_i32 s7, s6, 31
	s_ashr_i32 s9, s8, 31
	s_ashr_i32 s11, s10, 31
	s_ashr_i32 s13, s12, 31
	s_ashr_i32 s15, s14, 31
	s_ashr_i32 s17, s16, 31
	s_ashr_i32 s19, s18, 31
	s_ashr_i32 s21, s20, 31
	s_ashr_i32 s23, s22, 31
	s_ashr_i32 s49, s48, 31
	s_ashr_i32 s55, s54, 31
	s_ashr_i32 s59, s58, 31
	s_ashr_i32 s35, s34, 31
	s_ashr_i32 s31, s30, 31
	s_ashr_i32 s63, s62, 31
	s_ashr_i32 s61, s60, 31
	s_ashr_i32 s57, s56, 31
	s_ashr_i32 s53, s52, 31
	s_ashr_i32 s51, s50, 31
	s_ashr_i32 s79, s78, 31
	s_lshl_b64 s[90:91], s[38:39], 12
	v_lshl_add_u64 v[6:7], v[2:3], 2, s[36:37]
	s_lshl_b64 s[92:93], s[92:93], 12
	s_lshl_b64 s[94:95], s[94:95], 12
	s_lshl_b64 vcc, vcc, 12
	s_lshl_b64 s[6:7], s[6:7], 12
	s_lshl_b64 s[8:9], s[8:9], 12
	s_lshl_b64 s[10:11], s[10:11], 12
	s_lshl_b64 s[12:13], s[12:13], 12
	s_lshl_b64 s[14:15], s[14:15], 12
	s_lshl_b64 s[16:17], s[16:17], 12
	s_lshl_b64 s[18:19], s[18:19], 12
	s_lshl_b64 s[20:21], s[20:21], 12
	s_lshl_b64 s[22:23], s[22:23], 12
	s_lshl_b64 s[48:49], s[48:49], 12
	s_lshl_b64 s[54:55], s[54:55], 12
	s_lshl_b64 s[58:59], s[58:59], 12
	s_lshl_b64 s[34:35], s[34:35], 12
	s_lshl_b64 s[30:31], s[30:31], 12
	s_lshl_b64 s[62:63], s[62:63], 12
	s_lshl_b64 s[60:61], s[60:61], 12
	s_lshl_b64 s[56:57], s[56:57], 12
	s_lshl_b64 s[52:53], s[52:53], 12
	s_lshl_b64 s[50:51], s[50:51], 12
	s_lshl_b64 s[78:79], s[78:79], 12
	s_ashr_i32 s77, s76, 31
	s_or_b32 s40, s38, 25
	s_or_b32 s42, s38, 26
	s_or_b32 s44, s38, 27
	s_or_b32 s64, s38, 28
	s_or_b32 s66, s38, 29
	s_or_b32 s68, s38, 30
	s_or_b32 s70, s38, 31
	s_or_b32 s72, s38, 32
	s_or_b32 s74, s38, 33
	s_or_b32 s80, s38, 34
	s_or_b32 s82, s38, 35
	s_or_b32 s84, s38, 36
	s_or_b32 s86, s38, 37
	s_or_b32 s88, s38, 38
	v_lshl_add_u64 v[4:5], v[6:7], 0, s[90:91]
	s_or_b32 s90, s38, 39
	v_lshl_add_u64 v[8:9], v[6:7], 0, s[92:93]
	s_or_b32 s92, s38, 40
	v_lshl_add_u64 v[10:11], v[6:7], 0, s[94:95]
	s_or_b32 s94, s38, 41
	v_lshl_add_u64 v[12:13], v[6:7], 0, vcc
	s_or_b32 vcc_lo, s38, 42
	v_lshl_add_u64 v[18:19], v[6:7], 0, s[6:7]
	s_or_b32 s6, s38, 43
	v_lshl_add_u64 v[20:21], v[6:7], 0, s[8:9]
	s_or_b32 s8, s38, 44
	v_lshl_add_u64 v[22:23], v[6:7], 0, s[10:11]
	s_or_b32 s10, s38, 45
	v_lshl_add_u64 v[24:25], v[6:7], 0, s[12:13]
	s_or_b32 s12, s38, 46
	v_lshl_add_u64 v[26:27], v[6:7], 0, s[14:15]
	s_or_b32 s14, s38, 47
	v_lshl_add_u64 v[28:29], v[6:7], 0, s[16:17]
	s_or_b32 s16, s38, 48
	v_lshl_add_u64 v[30:31], v[6:7], 0, s[18:19]
	s_or_b32 s18, s38, 49
	v_lshl_add_u64 v[32:33], v[6:7], 0, s[20:21]
	s_or_b32 s20, s38, 50
	v_lshl_add_u64 v[34:35], v[6:7], 0, s[22:23]
	s_or_b32 s22, s38, 51
	v_lshl_add_u64 v[36:37], v[6:7], 0, s[48:49]
	s_or_b32 s48, s38, 52
	v_lshl_add_u64 v[38:39], v[6:7], 0, s[54:55]
	s_or_b32 s54, s38, 53
	v_lshl_add_u64 v[40:41], v[6:7], 0, s[58:59]
	s_or_b32 s58, s38, 54
	v_lshl_add_u64 v[42:43], v[6:7], 0, s[34:35]
	s_or_b32 s34, s38, 55
	v_lshl_add_u64 v[44:45], v[6:7], 0, s[30:31]
	s_or_b32 s30, s38, 56
	v_lshl_add_u64 v[46:47], v[6:7], 0, s[62:63]
	s_or_b32 s62, s38, 57
	v_lshl_add_u64 v[48:49], v[6:7], 0, s[60:61]
	s_or_b32 s60, s38, 58
	v_lshl_add_u64 v[50:51], v[6:7], 0, s[56:57]
	s_or_b32 s56, s38, 59
	v_lshl_add_u64 v[52:53], v[6:7], 0, s[52:53]
	s_or_b32 s52, s38, 60
	v_lshl_add_u64 v[54:55], v[6:7], 0, s[50:51]
	s_or_b32 s50, s38, 61
	v_lshl_add_u64 v[58:59], v[6:7], 0, s[78:79]
	s_or_b32 s78, s38, 62
	s_lshl_b64 s[76:77], s[76:77], 12
	v_lshl_add_u64 v[60:61], v[6:7], 0, s[76:77]
	s_or_b32 s76, s38, 63
	s_ashr_i32 s41, s40, 31
	s_ashr_i32 s43, s42, 31
	s_ashr_i32 s45, s44, 31
	s_ashr_i32 s65, s64, 31
	s_ashr_i32 s67, s66, 31
	s_ashr_i32 s69, s68, 31
	s_ashr_i32 s71, s70, 31
	s_ashr_i32 s73, s72, 31
	s_ashr_i32 s75, s74, 31
	s_ashr_i32 s81, s80, 31
	s_ashr_i32 s83, s82, 31
	s_ashr_i32 s85, s84, 31
	s_ashr_i32 s87, s86, 31
	s_ashr_i32 s89, s88, 31
	s_ashr_i32 s91, s90, 31
	s_ashr_i32 s93, s92, 31
	s_ashr_i32 s95, s94, 31
	s_ashr_i32 vcc_hi, vcc_lo, 31
	s_ashr_i32 s7, s6, 31
	s_ashr_i32 s9, s8, 31
	s_ashr_i32 s11, s10, 31
	s_ashr_i32 s13, s12, 31
	s_ashr_i32 s15, s14, 31
	s_ashr_i32 s17, s16, 31
	s_ashr_i32 s19, s18, 31
	s_ashr_i32 s21, s20, 31
	s_ashr_i32 s23, s22, 31
	s_ashr_i32 s49, s48, 31
	s_ashr_i32 s55, s54, 31
	s_ashr_i32 s59, s58, 31
	s_ashr_i32 s35, s34, 31
	s_ashr_i32 s31, s30, 31
	s_ashr_i32 s63, s62, 31
	s_ashr_i32 s61, s60, 31
	s_ashr_i32 s57, s56, 31
	s_ashr_i32 s53, s52, 31
	s_ashr_i32 s51, s50, 31
	s_ashr_i32 s79, s78, 31
	s_ashr_i32 s77, s76, 31
	s_lshl_b64 s[40:41], s[40:41], 12
	s_lshl_b64 s[42:43], s[42:43], 12
	s_lshl_b64 s[44:45], s[44:45], 12
	s_lshl_b64 s[64:65], s[64:65], 12
	s_lshl_b64 s[66:67], s[66:67], 12
	s_lshl_b64 s[68:69], s[68:69], 12
	s_lshl_b64 s[70:71], s[70:71], 12
	s_lshl_b64 s[72:73], s[72:73], 12
	s_lshl_b64 s[74:75], s[74:75], 12
	s_lshl_b64 s[80:81], s[80:81], 12
	s_lshl_b64 s[82:83], s[82:83], 12
	s_lshl_b64 s[84:85], s[84:85], 12
	s_lshl_b64 s[86:87], s[86:87], 12
	s_lshl_b64 s[88:89], s[88:89], 12
	s_lshl_b64 s[90:91], s[90:91], 12
	s_lshl_b64 s[92:93], s[92:93], 12
	s_lshl_b64 s[94:95], s[94:95], 12
	s_lshl_b64 vcc, vcc, 12
	s_lshl_b64 s[6:7], s[6:7], 12
	s_lshl_b64 s[8:9], s[8:9], 12
	s_lshl_b64 s[10:11], s[10:11], 12
	s_lshl_b64 s[12:13], s[12:13], 12
	s_lshl_b64 s[14:15], s[14:15], 12
	s_lshl_b64 s[16:17], s[16:17], 12
	s_lshl_b64 s[18:19], s[18:19], 12
	s_lshl_b64 s[20:21], s[20:21], 12
	s_lshl_b64 s[22:23], s[22:23], 12
	s_lshl_b64 s[48:49], s[48:49], 12
	s_lshl_b64 s[54:55], s[54:55], 12
	s_lshl_b64 s[58:59], s[58:59], 12
	s_lshl_b64 s[34:35], s[34:35], 12
	s_lshl_b64 s[30:31], s[30:31], 12
	s_lshl_b64 s[62:63], s[62:63], 12
	s_lshl_b64 s[60:61], s[60:61], 12
	s_lshl_b64 s[56:57], s[56:57], 12
	s_lshl_b64 s[52:53], s[52:53], 12
	s_lshl_b64 s[50:51], s[50:51], 12
	s_lshl_b64 s[78:79], s[78:79], 12
	s_lshl_b64 s[76:77], s[76:77], 12
	v_lshl_add_u64 v[64:65], v[6:7], 0, s[40:41]
	v_lshl_add_u64 v[66:67], v[6:7], 0, s[42:43]
	v_lshl_add_u64 v[68:69], v[6:7], 0, s[44:45]
	v_lshl_add_u64 v[70:71], v[6:7], 0, s[64:65]
	v_lshl_add_u64 v[72:73], v[6:7], 0, s[66:67]
	v_lshl_add_u64 v[74:75], v[6:7], 0, s[68:69]
	v_lshl_add_u64 v[76:77], v[6:7], 0, s[70:71]
	v_lshl_add_u64 v[78:79], v[6:7], 0, s[72:73]
	v_lshl_add_u64 v[80:81], v[6:7], 0, s[74:75]
	v_lshl_add_u64 v[82:83], v[6:7], 0, s[80:81]
	v_lshl_add_u64 v[84:85], v[6:7], 0, s[82:83]
	v_lshl_add_u64 v[86:87], v[6:7], 0, s[84:85]
	v_lshl_add_u64 v[88:89], v[6:7], 0, s[86:87]
	v_lshl_add_u64 v[90:91], v[6:7], 0, s[88:89]
	v_lshl_add_u64 v[92:93], v[6:7], 0, s[90:91]
	v_lshl_add_u64 v[94:95], v[6:7], 0, s[92:93]
	v_lshl_add_u64 v[96:97], v[6:7], 0, s[94:95]
	v_lshl_add_u64 v[98:99], v[6:7], 0, vcc
	v_lshl_add_u64 v[100:101], v[6:7], 0, s[6:7]
	v_lshl_add_u64 v[102:103], v[6:7], 0, s[8:9]
	v_lshl_add_u64 v[104:105], v[6:7], 0, s[10:11]
	v_lshl_add_u64 v[106:107], v[6:7], 0, s[12:13]
	v_lshl_add_u64 v[108:109], v[6:7], 0, s[14:15]
	v_lshl_add_u64 v[110:111], v[6:7], 0, s[16:17]
	v_lshl_add_u64 v[112:113], v[6:7], 0, s[18:19]
	v_lshl_add_u64 v[114:115], v[6:7], 0, s[20:21]
	v_lshl_add_u64 v[116:117], v[6:7], 0, s[22:23]
	v_lshl_add_u64 v[118:119], v[6:7], 0, s[48:49]
	v_lshl_add_u64 v[120:121], v[6:7], 0, s[54:55]
	v_lshl_add_u64 v[122:123], v[6:7], 0, s[58:59]
	v_lshl_add_u64 v[124:125], v[6:7], 0, s[34:35]
	v_lshl_add_u64 v[126:127], v[6:7], 0, s[30:31]
	v_lshl_add_u64 v[128:129], v[6:7], 0, s[62:63]
	v_lshl_add_u64 v[130:131], v[6:7], 0, s[60:61]
	v_lshl_add_u64 v[132:133], v[6:7], 0, s[56:57]
	v_lshl_add_u64 v[134:135], v[6:7], 0, s[52:53]
	v_lshl_add_u64 v[136:137], v[6:7], 0, s[50:51]
	v_lshl_add_u64 v[138:139], v[6:7], 0, s[78:79]
	v_lshl_add_u64 v[6:7], v[6:7], 0, s[76:77]
	global_load_dwordx2 v[140:141], v[4:5], off nt
	global_load_dwordx2 v[142:143], v[8:9], off nt
	global_load_dwordx2 v[144:145], v[10:11], off nt
	global_load_dwordx2 v[146:147], v[12:13], off nt
	global_load_dwordx2 v[152:153], v[18:19], off nt
	global_load_dwordx2 v[154:155], v[20:21], off nt
	global_load_dwordx2 v[156:157], v[22:23], off nt
	global_load_dwordx2 v[158:159], v[24:25], off nt
	global_load_dwordx2 v[160:161], v[26:27], off nt
	global_load_dwordx2 v[162:163], v[28:29], off nt
	global_load_dwordx2 v[164:165], v[30:31], off nt
	global_load_dwordx2 v[166:167], v[32:33], off nt
	global_load_dwordx2 v[168:169], v[34:35], off nt
	global_load_dwordx2 v[170:171], v[36:37], off nt
	global_load_dwordx2 v[172:173], v[38:39], off nt
	global_load_dwordx2 v[174:175], v[40:41], off nt
	global_load_dwordx2 v[176:177], v[42:43], off nt
	global_load_dwordx2 v[178:179], v[44:45], off nt
	s_nop 0
	global_load_dwordx2 v[46:47], v[46:47], off nt
	s_nop 0
	global_load_dwordx2 v[48:49], v[48:49], off nt
	s_nop 0
	global_load_dwordx2 v[50:51], v[50:51], off nt
	s_nop 0
	global_load_dwordx2 v[52:53], v[52:53], off nt
	s_nop 0
	global_load_dwordx2 v[54:55], v[54:55], off nt
	s_nop 0
	global_load_dwordx2 v[58:59], v[58:59], off nt
	s_nop 0
	global_load_dwordx2 v[60:61], v[60:61], off nt
	s_nop 0
	global_load_dwordx2 v[64:65], v[64:65], off nt
	s_nop 0
	global_load_dwordx2 v[66:67], v[66:67], off nt
	s_nop 0
	global_load_dwordx2 v[68:69], v[68:69], off nt
	s_nop 0
	global_load_dwordx2 v[70:71], v[70:71], off nt
	s_nop 0
	global_load_dwordx2 v[72:73], v[72:73], off nt
	s_nop 0
	global_load_dwordx2 v[74:75], v[74:75], off nt
	s_nop 0
	global_load_dwordx2 v[76:77], v[76:77], off nt
	s_nop 0
	global_load_dwordx2 v[78:79], v[78:79], off nt
	s_nop 0
	global_load_dwordx2 v[80:81], v[80:81], off nt
	s_nop 0
	global_load_dwordx2 v[82:83], v[82:83], off nt
	s_nop 0
	global_load_dwordx2 v[84:85], v[84:85], off nt
	s_nop 0
	global_load_dwordx2 v[86:87], v[86:87], off nt
	s_nop 0
	global_load_dwordx2 v[88:89], v[88:89], off nt
	s_nop 0
	global_load_dwordx2 v[90:91], v[90:91], off nt
	s_nop 0
	global_load_dwordx2 v[92:93], v[92:93], off nt
	s_nop 0
	global_load_dwordx2 v[94:95], v[94:95], off nt
	s_nop 0
	global_load_dwordx2 v[96:97], v[96:97], off nt
	s_nop 0
	global_load_dwordx2 v[98:99], v[98:99], off nt
	s_nop 0
	global_load_dwordx2 v[100:101], v[100:101], off nt
	s_nop 0
	global_load_dwordx2 v[102:103], v[102:103], off nt
	s_nop 0
	global_load_dwordx2 v[104:105], v[104:105], off nt
	s_nop 0
	global_load_dwordx2 v[106:107], v[106:107], off nt
	s_nop 0
	global_load_dwordx2 v[108:109], v[108:109], off nt
	s_nop 0
	global_load_dwordx2 v[110:111], v[110:111], off nt
	s_nop 0
	global_load_dwordx2 v[112:113], v[112:113], off nt
	s_nop 0
	global_load_dwordx2 v[114:115], v[114:115], off nt
	s_nop 0
	global_load_dwordx2 v[116:117], v[116:117], off nt
	s_nop 0
	global_load_dwordx2 v[118:119], v[118:119], off nt
	s_nop 0
	global_load_dwordx2 v[120:121], v[120:121], off nt
	s_nop 0
	global_load_dwordx2 v[122:123], v[122:123], off nt
	s_nop 0
	global_load_dwordx2 v[124:125], v[124:125], off nt
	s_nop 0
	global_load_dwordx2 v[126:127], v[126:127], off nt
	s_nop 0
	global_load_dwordx2 v[128:129], v[128:129], off nt
	s_nop 0
	global_load_dwordx2 v[130:131], v[130:131], off nt
	s_nop 0
	global_load_dwordx2 v[132:133], v[132:133], off nt
	s_nop 0
	global_load_dwordx2 v[134:135], v[134:135], off nt
	s_nop 0
	global_load_dwordx2 v[136:137], v[136:137], off nt
	s_nop 0
	global_load_dwordx2 v[138:139], v[138:139], off nt
	s_nop 0
	global_load_dwordx2 v[180:181], v[6:7], off nt
	s_lshl_b64 s[38:39], s[38:39], 1
	v_add_u32_e32 v62, 1, v2
	v_readlane_b32 s40, v250, 58
	s_add_u32 s6, s28, s38
	v_lshlrev_b64 v[2:3], 13, v[2:3]
	v_ashrrev_i32_e32 v63, 31, v62
	s_addc_u32 s7, s29, s39
	s_add_i32 s3, s3, s40
	v_add_u32_e32 v56, s4, v56
	v_lshlrev_b64 v[62:63], 13, v[62:63]
	v_lshl_add_u64 v[182:183], s[6:7], 0, v[2:3]
	s_cmpk_lt_i32 s3, 0x200
	v_readlane_b32 s41, v250, 59
	v_lshl_add_u64 v[184:185], s[6:7], 0, v[62:63]
	s_waitcnt vmcnt(62)
	v_cvt_pk_bf16_f32 v2, v140, v142
	v_cvt_pk_bf16_f32 v34, v141, v143
	s_waitcnt vmcnt(60)
	v_cvt_pk_bf16_f32 v3, v144, v146
	v_cvt_pk_bf16_f32 v35, v145, v147
	s_waitcnt vmcnt(58)
	v_cvt_pk_bf16_f32 v4, v152, v154
	v_cvt_pk_bf16_f32 v36, v153, v155
	s_waitcnt vmcnt(56)
	v_cvt_pk_bf16_f32 v5, v156, v158
	v_cvt_pk_bf16_f32 v37, v157, v159
	s_waitcnt vmcnt(54)
	v_cvt_pk_bf16_f32 v6, v160, v162
	v_cvt_pk_bf16_f32 v42, v161, v163
	s_waitcnt vmcnt(52)
	v_cvt_pk_bf16_f32 v7, v164, v166
	v_cvt_pk_bf16_f32 v43, v165, v167
	s_waitcnt vmcnt(50)
	v_cvt_pk_bf16_f32 v8, v168, v170
	v_cvt_pk_bf16_f32 v44, v169, v171
	s_waitcnt vmcnt(48)
	v_cvt_pk_bf16_f32 v9, v172, v174
	v_cvt_pk_bf16_f32 v45, v173, v175
	s_waitcnt vmcnt(46)
	v_cvt_pk_bf16_f32 v10, v176, v178
	s_waitcnt vmcnt(44)
	v_cvt_pk_bf16_f32 v11, v46, v48
	v_cvt_pk_bf16_f32 v46, v177, v179
	s_waitcnt vmcnt(42)
	v_cvt_pk_bf16_f32 v12, v50, v52
	v_cvt_pk_bf16_f32 v47, v47, v49
	s_waitcnt vmcnt(40)
	v_cvt_pk_bf16_f32 v13, v54, v58
	v_cvt_pk_bf16_f32 v48, v51, v53
	s_waitcnt vmcnt(38)
	v_cvt_pk_bf16_f32 v18, v60, v64
	v_cvt_pk_bf16_f32 v49, v55, v59
	s_waitcnt vmcnt(36)
	v_cvt_pk_bf16_f32 v19, v66, v68
	v_cvt_pk_bf16_f32 v50, v61, v65
	s_waitcnt vmcnt(34)
	v_cvt_pk_bf16_f32 v20, v70, v72
	v_cvt_pk_bf16_f32 v51, v67, v69
	s_waitcnt vmcnt(32)
	v_cvt_pk_bf16_f32 v21, v74, v76
	v_cvt_pk_bf16_f32 v52, v71, v73
	s_waitcnt vmcnt(30)
	v_cvt_pk_bf16_f32 v22, v78, v80
	v_cvt_pk_bf16_f32 v53, v75, v77
	s_waitcnt vmcnt(28)
	v_cvt_pk_bf16_f32 v23, v82, v84
	v_cvt_pk_bf16_f32 v58, v79, v81
	s_waitcnt vmcnt(26)
	v_cvt_pk_bf16_f32 v24, v86, v88
	v_cvt_pk_bf16_f32 v59, v83, v85
	s_waitcnt vmcnt(24)
	v_cvt_pk_bf16_f32 v25, v90, v92
	v_cvt_pk_bf16_f32 v60, v87, v89
	s_waitcnt vmcnt(22)
	v_cvt_pk_bf16_f32 v26, v94, v96
	v_cvt_pk_bf16_f32 v61, v91, v93
	s_waitcnt vmcnt(20)
	v_cvt_pk_bf16_f32 v27, v98, v100
	v_cvt_pk_bf16_f32 v62, v95, v97
	s_waitcnt vmcnt(18)
	v_cvt_pk_bf16_f32 v28, v102, v104
	v_cvt_pk_bf16_f32 v63, v99, v101
	s_waitcnt vmcnt(16)
	v_cvt_pk_bf16_f32 v29, v106, v108
	v_cvt_pk_bf16_f32 v64, v103, v105
	s_waitcnt vmcnt(14)
	v_cvt_pk_bf16_f32 v30, v110, v112
	v_cvt_pk_bf16_f32 v65, v107, v109
	s_waitcnt vmcnt(12)
	v_cvt_pk_bf16_f32 v31, v114, v116
	v_cvt_pk_bf16_f32 v66, v111, v113
	s_waitcnt vmcnt(10)
	v_cvt_pk_bf16_f32 v32, v118, v120
	v_cvt_pk_bf16_f32 v67, v115, v117
	s_waitcnt vmcnt(8)
	v_cvt_pk_bf16_f32 v33, v122, v124
	v_cvt_pk_bf16_f32 v68, v119, v121
	s_waitcnt vmcnt(6)
	v_cvt_pk_bf16_f32 v38, v126, v128
	v_cvt_pk_bf16_f32 v69, v123, v125
	s_waitcnt vmcnt(4)
	v_cvt_pk_bf16_f32 v39, v130, v132
	v_cvt_pk_bf16_f32 v70, v127, v129
	s_waitcnt vmcnt(2)
	v_cvt_pk_bf16_f32 v40, v134, v136
	v_cvt_pk_bf16_f32 v71, v131, v133
	s_waitcnt vmcnt(0)
	v_cvt_pk_bf16_f32 v41, v138, v180
	v_cvt_pk_bf16_f32 v72, v135, v137
	v_cvt_pk_bf16_f32 v73, v139, v181
	global_store_dwordx4 v[182:183], v[2:5], off
	global_store_dwordx4 v[182:183], v[6:9], off offset:16
	global_store_dwordx4 v[182:183], v[10:13], off offset:32
	global_store_dwordx4 v[182:183], v[18:21], off offset:48
	global_store_dwordx4 v[182:183], v[22:25], off offset:64
	global_store_dwordx4 v[182:183], v[26:29], off offset:80
	global_store_dwordx4 v[182:183], v[30:33], off offset:96
	global_store_dwordx4 v[182:183], v[38:41], off offset:112
	global_store_dwordx4 v[184:185], v[34:37], off
	global_store_dwordx4 v[184:185], v[42:45], off offset:16
	global_store_dwordx4 v[184:185], v[46:49], off offset:32
	global_store_dwordx4 v[184:185], v[50:53], off offset:48
	global_store_dwordx4 v[184:185], v[58:61], off offset:64
	global_store_dwordx4 v[184:185], v[62:65], off offset:80
	global_store_dwordx4 v[184:185], v[66:69], off offset:96
	global_store_dwordx4 v[184:185], v[70:73], off offset:112
	s_cbranch_scc1 .LBB0_15
	v_readlane_b32 s38, v251, 12
	v_readlane_b32 s70, v250, 56
	v_readlane_b32 s48, v250, 60
	v_readlane_b32 s76, v250, 3
	v_readlane_b32 s39, v251, 13
	v_readlane_b32 s16, v251, 18
	v_readlane_b32 s18, v251, 20
	v_readlane_b32 s20, v251, 32
	v_readlane_b32 s22, v251, 34
	v_readlane_b32 s14, v251, 36
	v_readlane_b32 s28, v251, 38
	v_readlane_b32 s72, v250, 54
	v_readlane_b32 s71, v250, 57
	v_readlane_b32 s49, v250, 61
	v_readlane_b32 s50, v250, 62
	v_readlane_b32 s51, v250, 63
	v_readlane_b32 s52, v251, 0
	v_readlane_b32 s53, v251, 1
	v_readlane_b32 s54, v251, 2
	v_readlane_b32 s55, v251, 3
	v_readlane_b32 s56, v251, 4
	v_readlane_b32 s57, v251, 5
	v_readlane_b32 s58, v251, 6
	v_readlane_b32 s59, v251, 7
	v_readlane_b32 s60, v251, 8
	v_readlane_b32 s61, v251, 9
	v_readlane_b32 s62, v251, 10
	v_readlane_b32 s63, v251, 11
	v_readlane_b32 s77, v250, 4
	v_readlane_b32 s78, v250, 5
	v_readlane_b32 s79, v250, 6
	v_readlane_b32 s80, v250, 7
	v_readlane_b32 s81, v250, 8
	v_readlane_b32 s82, v250, 9
	v_readlane_b32 s83, v250, 10
	v_readlane_b32 s84, v250, 11
	v_readlane_b32 s85, v250, 12
	v_readlane_b32 s86, v250, 13
	v_readlane_b32 s87, v250, 14
	v_readlane_b32 s88, v250, 15
	v_readlane_b32 s89, v250, 16
	v_readlane_b32 s90, v250, 17
	v_readlane_b32 s91, v250, 18
	v_readlane_b32 s39, v251, 14
	v_readlane_b32 s41, v251, 16
	v_readlane_b32 s17, v251, 19
	v_readlane_b32 s19, v251, 21
	v_readlane_b32 s21, v251, 33
	v_readlane_b32 s23, v251, 35
	v_readlane_b32 s15, v251, 37
	v_readlane_b32 s29, v251, 39
	v_readlane_b32 s73, v250, 55

.LBB0_20:
	s_ashr_i32 s3, s8, 31
	s_lshr_b32 s3, s3, 26
	s_add_i32 s4, s8, s3
	s_ashr_i32 s3, s4, 6
	s_lshl_b32 s3, s3, 13
	v_subrev_u32_e32 v42, s3, v152
	s_and_b32 s36, s4, 0xffffffc0
	v_ashrrev_i32_e32 v43, 31, v42
	s_ashr_i32 s37, s36, 31
	v_lshl_add_u64 v[2:3], v[42:43], 2, s[34:35]
	s_lshl_b64 s[4:5], s[36:37], 15
	v_lshl_add_u64 v[4:5], v[2:3], 0, s[4:5]
	s_or_b32 s4, s36, 1
	s_ashr_i32 s5, s4, 31
	s_lshl_b64 s[4:5], s[4:5], 15
	v_lshl_add_u64 v[6:7], v[2:3], 0, s[4:5]
	s_or_b32 s4, s36, 2
	s_ashr_i32 s5, s4, 31
	s_lshl_b64 s[4:5], s[4:5], 15
	v_lshl_add_u64 v[8:9], v[2:3], 0, s[4:5]
	s_or_b32 s4, s36, 3
	s_ashr_i32 s5, s4, 31
	s_lshl_b64 s[4:5], s[4:5], 15
	v_lshl_add_u64 v[10:11], v[2:3], 0, s[4:5]
	s_or_b32 s4, s36, 4
	s_ashr_i32 s5, s4, 31
	s_lshl_b64 s[4:5], s[4:5], 15
	global_load_dwordx2 v[18:19], v[4:5], off nt
	global_load_dwordx2 v[22:23], v[6:7], off nt
	global_load_dwordx2 v[20:21], v[8:9], off nt
	global_load_dwordx2 v[24:25], v[10:11], off nt
	v_lshl_add_u64 v[4:5], v[2:3], 0, s[4:5]
	s_or_b32 s4, s36, 5
	s_ashr_i32 s5, s4, 31
	s_lshl_b64 s[4:5], s[4:5], 15
	v_lshl_add_u64 v[6:7], v[2:3], 0, s[4:5]
	s_or_b32 s4, s36, 6
	s_ashr_i32 s5, s4, 31
	s_lshl_b64 s[4:5], s[4:5], 15
	v_lshl_add_u64 v[8:9], v[2:3], 0, s[4:5]
	s_or_b32 s4, s36, 7
	s_ashr_i32 s5, s4, 31
	s_lshl_b64 s[4:5], s[4:5], 15
	v_lshl_add_u64 v[10:11], v[2:3], 0, s[4:5]
	s_or_b32 s4, s36, 8
	s_ashr_i32 s5, s4, 31
	s_lshl_b64 s[4:5], s[4:5], 15
	global_load_dwordx2 v[26:27], v[4:5], off nt
	global_load_dwordx2 v[30:31], v[6:7], off nt
	global_load_dwordx2 v[28:29], v[8:9], off nt
	global_load_dwordx2 v[32:33], v[10:11], off nt
	v_lshl_add_u64 v[4:5], v[2:3], 0, s[4:5]
	s_or_b32 s4, s36, 9
	s_ashr_i32 s5, s4, 31
	s_lshl_b64 s[4:5], s[4:5], 15
	v_lshl_add_u64 v[6:7], v[2:3], 0, s[4:5]
	s_or_b32 s4, s36, 10
	s_ashr_i32 s5, s4, 31
	s_lshl_b64 s[4:5], s[4:5], 15
	v_lshl_add_u64 v[8:9], v[2:3], 0, s[4:5]
	s_or_b32 s4, s36, 11
	s_ashr_i32 s5, s4, 31
	s_lshl_b64 s[4:5], s[4:5], 15
	v_lshl_add_u64 v[10:11], v[2:3], 0, s[4:5]
	s_or_b32 s4, s36, 12
	s_ashr_i32 s5, s4, 31
	s_lshl_b64 s[4:5], s[4:5], 15
	global_load_dwordx2 v[34:35], v[4:5], off nt
	global_load_dwordx2 v[38:39], v[6:7], off nt
	global_load_dwordx2 v[36:37], v[8:9], off nt
	global_load_dwordx2 v[40:41], v[10:11], off nt
	v_lshl_add_u64 v[4:5], v[2:3], 0, s[4:5]
	s_or_b32 s4, s36, 13
	s_ashr_i32 s5, s4, 31
	s_lshl_b64 s[4:5], s[4:5], 15
	v_lshl_add_u64 v[6:7], v[2:3], 0, s[4:5]
	s_or_b32 s4, s36, 14
	s_ashr_i32 s5, s4, 31
	s_lshl_b64 s[4:5], s[4:5], 15
	v_lshl_add_u64 v[8:9], v[2:3], 0, s[4:5]
	s_or_b32 s4, s36, 15
	s_ashr_i32 s5, s4, 31
	s_lshl_b64 s[4:5], s[4:5], 15
	v_lshl_add_u64 v[10:11], v[2:3], 0, s[4:5]
	s_or_b32 s4, s36, 16
	s_ashr_i32 s5, s4, 31
	s_lshl_b64 s[4:5], s[4:5], 15
	global_load_dwordx2 v[44:45], v[4:5], off nt
	global_load_dwordx2 v[48:49], v[6:7], off nt
	global_load_dwordx2 v[46:47], v[8:9], off nt
	global_load_dwordx2 v[50:51], v[10:11], off nt
	v_lshl_add_u64 v[4:5], v[2:3], 0, s[4:5]
	s_or_b32 s4, s36, 17
	s_ashr_i32 s5, s4, 31
	s_lshl_b64 s[4:5], s[4:5], 15
	v_lshl_add_u64 v[6:7], v[2:3], 0, s[4:5]
	s_or_b32 s4, s36, 18
	s_ashr_i32 s5, s4, 31
	s_lshl_b64 s[4:5], s[4:5], 15
	v_lshl_add_u64 v[8:9], v[2:3], 0, s[4:5]
	s_or_b32 s4, s36, 19
	s_ashr_i32 s5, s4, 31
	s_lshl_b64 s[4:5], s[4:5], 15
	v_lshl_add_u64 v[10:11], v[2:3], 0, s[4:5]
	s_or_b32 s4, s36, 20
	s_ashr_i32 s5, s4, 31
	s_lshl_b64 s[4:5], s[4:5], 15
	global_load_dwordx2 v[52:53], v[4:5], off nt
	global_load_dwordx2 v[56:57], v[6:7], off nt
	global_load_dwordx2 v[54:55], v[8:9], off nt
	global_load_dwordx2 v[58:59], v[10:11], off nt
	v_lshl_add_u64 v[4:5], v[2:3], 0, s[4:5]
	s_or_b32 s4, s36, 21
	s_ashr_i32 s5, s4, 31
	s_lshl_b64 s[4:5], s[4:5], 15
	v_lshl_add_u64 v[6:7], v[2:3], 0, s[4:5]
	s_or_b32 s4, s36, 22
	s_ashr_i32 s5, s4, 31
	s_lshl_b64 s[4:5], s[4:5], 15
	v_lshl_add_u64 v[8:9], v[2:3], 0, s[4:5]
	s_or_b32 s4, s36, 23
	s_ashr_i32 s5, s4, 31
	s_lshl_b64 s[4:5], s[4:5], 15
	v_lshl_add_u64 v[10:11], v[2:3], 0, s[4:5]
	s_or_b32 s4, s36, 24
	s_ashr_i32 s5, s4, 31
	s_lshl_b64 s[4:5], s[4:5], 15
	global_load_dwordx2 v[60:61], v[4:5], off nt
	global_load_dwordx2 v[64:65], v[6:7], off nt
	global_load_dwordx2 v[62:63], v[8:9], off nt
	global_load_dwordx2 v[66:67], v[10:11], off nt
	v_lshl_add_u64 v[4:5], v[2:3], 0, s[4:5]
	s_or_b32 s4, s36, 25
	s_ashr_i32 s5, s4, 31
	s_lshl_b64 s[4:5], s[4:5], 15
	v_lshl_add_u64 v[6:7], v[2:3], 0, s[4:5]
	s_or_b32 s4, s36, 26
	s_ashr_i32 s5, s4, 31
	s_lshl_b64 s[4:5], s[4:5], 15
	v_lshl_add_u64 v[8:9], v[2:3], 0, s[4:5]
	s_or_b32 s4, s36, 27
	s_ashr_i32 s5, s4, 31
	s_lshl_b64 s[4:5], s[4:5], 15
	v_lshl_add_u64 v[10:11], v[2:3], 0, s[4:5]
	s_or_b32 s4, s36, 28
	s_ashr_i32 s5, s4, 31
	s_lshl_b64 s[4:5], s[4:5], 15
	global_load_dwordx2 v[68:69], v[4:5], off nt
	global_load_dwordx2 v[72:73], v[6:7], off nt
	global_load_dwordx2 v[70:71], v[8:9], off nt
	global_load_dwordx2 v[74:75], v[10:11], off nt
	v_lshl_add_u64 v[4:5], v[2:3], 0, s[4:5]
	s_or_b32 s4, s36, 29
	s_ashr_i32 s5, s4, 31
	s_lshl_b64 s[4:5], s[4:5], 15
	v_lshl_add_u64 v[6:7], v[2:3], 0, s[4:5]
	s_or_b32 s4, s36, 30
	s_ashr_i32 s5, s4, 31
	s_lshl_b64 s[4:5], s[4:5], 15
	v_lshl_add_u64 v[8:9], v[2:3], 0, s[4:5]
	s_or_b32 s4, s36, 31
	s_ashr_i32 s5, s4, 31
	s_lshl_b64 s[4:5], s[4:5], 15
	v_lshl_add_u64 v[10:11], v[2:3], 0, s[4:5]
	s_or_b32 s4, s36, 32
	s_ashr_i32 s5, s4, 31
	s_lshl_b64 s[4:5], s[4:5], 15
	global_load_dwordx2 v[76:77], v[4:5], off nt
	global_load_dwordx2 v[80:81], v[6:7], off nt
	global_load_dwordx2 v[78:79], v[8:9], off nt
	global_load_dwordx2 v[82:83], v[10:11], off nt
	v_lshl_add_u64 v[4:5], v[2:3], 0, s[4:5]
	s_or_b32 s4, s36, 33
	s_ashr_i32 s5, s4, 31
	s_lshl_b64 s[4:5], s[4:5], 15
	v_lshl_add_u64 v[6:7], v[2:3], 0, s[4:5]
	s_or_b32 s4, s36, 34
	s_ashr_i32 s5, s4, 31
	s_lshl_b64 s[4:5], s[4:5], 15
	v_lshl_add_u64 v[8:9], v[2:3], 0, s[4:5]
	s_or_b32 s4, s36, 35
	s_ashr_i32 s5, s4, 31
	s_lshl_b64 s[4:5], s[4:5], 15
	v_lshl_add_u64 v[10:11], v[2:3], 0, s[4:5]
	s_or_b32 s4, s36, 36
	s_ashr_i32 s5, s4, 31
	s_lshl_b64 s[4:5], s[4:5], 15
	global_load_dwordx2 v[84:85], v[4:5], off nt
	global_load_dwordx2 v[88:89], v[6:7], off nt
	global_load_dwordx2 v[86:87], v[8:9], off nt
	global_load_dwordx2 v[90:91], v[10:11], off nt
	v_lshl_add_u64 v[4:5], v[2:3], 0, s[4:5]
	s_or_b32 s4, s36, 37
	s_ashr_i32 s5, s4, 31
	s_lshl_b64 s[4:5], s[4:5], 15
	v_lshl_add_u64 v[6:7], v[2:3], 0, s[4:5]
	s_or_b32 s4, s36, 38
	s_ashr_i32 s5, s4, 31
	s_lshl_b64 s[4:5], s[4:5], 15
	v_lshl_add_u64 v[8:9], v[2:3], 0, s[4:5]
	s_or_b32 s4, s36, 39
	s_ashr_i32 s5, s4, 31
	s_lshl_b64 s[4:5], s[4:5], 15
	v_lshl_add_u64 v[10:11], v[2:3], 0, s[4:5]
	s_or_b32 s4, s36, 40
	s_ashr_i32 s5, s4, 31
	s_lshl_b64 s[4:5], s[4:5], 15
	global_load_dwordx2 v[92:93], v[4:5], off nt
	global_load_dwordx2 v[96:97], v[6:7], off nt
	global_load_dwordx2 v[94:95], v[8:9], off nt
	global_load_dwordx2 v[98:99], v[10:11], off nt
	v_lshl_add_u64 v[4:5], v[2:3], 0, s[4:5]
	s_or_b32 s4, s36, 41
	s_ashr_i32 s5, s4, 31
	s_lshl_b64 s[4:5], s[4:5], 15
	v_lshl_add_u64 v[6:7], v[2:3], 0, s[4:5]
	s_or_b32 s4, s36, 42
	s_ashr_i32 s5, s4, 31
	s_lshl_b64 s[4:5], s[4:5], 15
	v_lshl_add_u64 v[8:9], v[2:3], 0, s[4:5]
	s_or_b32 s4, s36, 43
	s_ashr_i32 s5, s4, 31
	s_lshl_b64 s[4:5], s[4:5], 15
	v_lshl_add_u64 v[10:11], v[2:3], 0, s[4:5]
	s_or_b32 s4, s36, 44
	s_ashr_i32 s5, s4, 31
	s_lshl_b64 s[4:5], s[4:5], 15
	global_load_dwordx2 v[100:101], v[4:5], off nt
	global_load_dwordx2 v[104:105], v[6:7], off nt
	global_load_dwordx2 v[102:103], v[8:9], off nt
	global_load_dwordx2 v[106:107], v[10:11], off nt
	v_lshl_add_u64 v[4:5], v[2:3], 0, s[4:5]
	s_or_b32 s4, s36, 45
	s_ashr_i32 s5, s4, 31
	s_lshl_b64 s[4:5], s[4:5], 15
	v_lshl_add_u64 v[6:7], v[2:3], 0, s[4:5]
	s_or_b32 s4, s36, 46
	s_ashr_i32 s5, s4, 31
	s_lshl_b64 s[4:5], s[4:5], 15
	v_lshl_add_u64 v[8:9], v[2:3], 0, s[4:5]
	s_or_b32 s4, s36, 47
	s_ashr_i32 s5, s4, 31
	s_lshl_b64 s[4:5], s[4:5], 15
	v_lshl_add_u64 v[10:11], v[2:3], 0, s[4:5]
	s_or_b32 s4, s36, 48
	s_ashr_i32 s5, s4, 31
	s_lshl_b64 s[4:5], s[4:5], 15
	global_load_dwordx2 v[108:109], v[4:5], off nt
	global_load_dwordx2 v[112:113], v[6:7], off nt
	global_load_dwordx2 v[110:111], v[8:9], off nt
	global_load_dwordx2 v[114:115], v[10:11], off nt
	v_lshl_add_u64 v[4:5], v[2:3], 0, s[4:5]
	s_or_b32 s4, s36, 49
	s_ashr_i32 s5, s4, 31
	s_lshl_b64 s[4:5], s[4:5], 15
	v_lshl_add_u64 v[6:7], v[2:3], 0, s[4:5]
	s_or_b32 s4, s36, 50
	s_ashr_i32 s5, s4, 31
	s_lshl_b64 s[4:5], s[4:5], 15
	v_lshl_add_u64 v[8:9], v[2:3], 0, s[4:5]
	s_or_b32 s4, s36, 51
	s_ashr_i32 s5, s4, 31
	s_lshl_b64 s[4:5], s[4:5], 15
	v_lshl_add_u64 v[10:11], v[2:3], 0, s[4:5]
	s_or_b32 s4, s36, 52
	s_ashr_i32 s5, s4, 31
	s_lshl_b64 s[4:5], s[4:5], 15
	global_load_dwordx2 v[116:117], v[4:5], off nt
	global_load_dwordx2 v[120:121], v[6:7], off nt
	global_load_dwordx2 v[118:119], v[8:9], off nt
	global_load_dwordx2 v[122:123], v[10:11], off nt
	v_lshl_add_u64 v[4:5], v[2:3], 0, s[4:5]
	s_or_b32 s4, s36, 53
	s_ashr_i32 s5, s4, 31
	s_lshl_b64 s[4:5], s[4:5], 15
	v_lshl_add_u64 v[6:7], v[2:3], 0, s[4:5]
	s_or_b32 s4, s36, 54
	s_ashr_i32 s5, s4, 31
	s_lshl_b64 s[4:5], s[4:5], 15
	v_lshl_add_u64 v[8:9], v[2:3], 0, s[4:5]
	s_or_b32 s4, s36, 55
	s_ashr_i32 s5, s4, 31
	s_lshl_b64 s[4:5], s[4:5], 15
	v_lshl_add_u64 v[10:11], v[2:3], 0, s[4:5]
	s_or_b32 s4, s36, 56
	s_ashr_i32 s5, s4, 31
	s_lshl_b64 s[4:5], s[4:5], 15
	global_load_dwordx2 v[124:125], v[4:5], off nt
	global_load_dwordx2 v[128:129], v[6:7], off nt
	global_load_dwordx2 v[126:127], v[8:9], off nt
	global_load_dwordx2 v[130:131], v[10:11], off nt
	v_lshl_add_u64 v[4:5], v[2:3], 0, s[4:5]
	s_or_b32 s4, s36, 57
	s_ashr_i32 s5, s4, 31
	s_lshl_b64 s[4:5], s[4:5], 15
	v_lshl_add_u64 v[6:7], v[2:3], 0, s[4:5]
	s_or_b32 s4, s36, 58
	s_ashr_i32 s5, s4, 31
	s_lshl_b64 s[4:5], s[4:5], 15
	v_lshl_add_u64 v[8:9], v[2:3], 0, s[4:5]
	s_or_b32 s4, s36, 59
	s_ashr_i32 s5, s4, 31
	s_lshl_b64 s[4:5], s[4:5], 15
	v_lshl_add_u64 v[10:11], v[2:3], 0, s[4:5]
	s_or_b32 s4, s36, 60
	s_ashr_i32 s5, s4, 31
	s_lshl_b64 s[4:5], s[4:5], 15
	global_load_dwordx2 v[132:133], v[4:5], off nt
	global_load_dwordx2 v[136:137], v[6:7], off nt
	global_load_dwordx2 v[134:135], v[8:9], off nt
	global_load_dwordx2 v[138:139], v[10:11], off nt
	v_lshl_add_u64 v[4:5], v[2:3], 0, s[4:5]
	s_or_b32 s4, s36, 61
	s_ashr_i32 s5, s4, 31
	s_lshl_b64 s[4:5], s[4:5], 15
	v_lshl_add_u64 v[6:7], v[2:3], 0, s[4:5]
	s_or_b32 s4, s36, 62
	s_ashr_i32 s5, s4, 31
	s_lshl_b64 s[4:5], s[4:5], 15
	v_lshl_add_u64 v[8:9], v[2:3], 0, s[4:5]
	s_or_b32 s4, s36, 63
	s_ashr_i32 s5, s4, 31
	s_lshl_b64 s[4:5], s[4:5], 15
	v_lshl_add_u64 v[2:3], v[2:3], 0, s[4:5]
	global_load_dwordx2 v[140:141], v[4:5], off nt
	global_load_dwordx2 v[144:145], v[6:7], off nt
	global_load_dwordx2 v[142:143], v[8:9], off nt
	global_load_dwordx2 v[146:147], v[2:3], off nt
	s_andn2_b64 vcc, exec, s[18:19]
	s_cbranch_vccnz .LBB0_19
	s_lshl_b64 s[4:5], s[36:37], 2
	s_add_u32 s6, s9, s4
	s_addc_u32 s7, s10, s5
	global_load_dwordx4 v[2:5], v149, s[6:7] offset:48
	global_load_dwordx4 v[6:9], v149, s[6:7] offset:32
	global_load_dwordx4 v[10:13], v149, s[6:7] offset:16
	global_load_dwordx4 v[154:157], v149, s[6:7]
	s_waitcnt vmcnt(3)
	v_pk_mul_f32 v[44:45], v[44:45], v[2:3] op_sel_hi:[1,0]
	s_waitcnt vmcnt(2)
	v_pk_mul_f32 v[34:35], v[34:35], v[6:7] op_sel_hi:[1,0]
	s_waitcnt vmcnt(1)
	v_pk_mul_f32 v[26:27], v[26:27], v[10:11] op_sel_hi:[1,0]
	s_waitcnt vmcnt(0)
	v_pk_mul_f32 v[18:19], v[18:19], v[154:155] op_sel_hi:[1,0]
	v_pk_mul_f32 v[22:23], v[22:23], v[154:155] op_sel:[0,1]
	v_mov_b32_e32 v154, v157
	v_pk_mul_f32 v[30:31], v[30:31], v[10:11] op_sel:[0,1]
	v_mov_b32_e32 v10, v13
	v_pk_mul_f32 v[38:39], v[38:39], v[6:7] op_sel:[0,1]
	v_mov_b32_e32 v6, v9
	v_pk_mul_f32 v[48:49], v[48:49], v[2:3] op_sel:[0,1]
	v_mov_b32_e32 v2, v5
	v_pk_mul_f32 v[20:21], v[20:21], v[156:157] op_sel_hi:[1,0]
	v_pk_mul_f32 v[24:25], v[24:25], v[154:155] op_sel_hi:[1,0]
	v_pk_mul_f32 v[28:29], v[28:29], v[12:13] op_sel_hi:[1,0]
	v_pk_mul_f32 v[32:33], v[32:33], v[10:11] op_sel_hi:[1,0]
	v_pk_mul_f32 v[36:37], v[36:37], v[8:9] op_sel_hi:[1,0]
	v_pk_mul_f32 v[40:41], v[40:41], v[6:7] op_sel_hi:[1,0]
	v_pk_mul_f32 v[46:47], v[46:47], v[4:5] op_sel_hi:[1,0]
	v_pk_mul_f32 v[50:51], v[50:51], v[2:3] op_sel_hi:[1,0]
	global_load_dwordx4 v[2:5], v149, s[6:7] offset:112
	global_load_dwordx4 v[6:9], v149, s[6:7] offset:96
	global_load_dwordx4 v[10:13], v149, s[6:7] offset:80
	global_load_dwordx4 v[154:157], v149, s[6:7] offset:64
	s_waitcnt vmcnt(3)
	v_pk_mul_f32 v[76:77], v[76:77], v[2:3] op_sel_hi:[1,0]
	s_waitcnt vmcnt(2)
	v_pk_mul_f32 v[68:69], v[68:69], v[6:7] op_sel_hi:[1,0]
	s_waitcnt vmcnt(1)
	v_pk_mul_f32 v[60:61], v[60:61], v[10:11] op_sel_hi:[1,0]
	s_waitcnt vmcnt(0)
	v_pk_mul_f32 v[52:53], v[52:53], v[154:155] op_sel_hi:[1,0]
	v_pk_mul_f32 v[56:57], v[56:57], v[154:155] op_sel:[0,1]
	v_mov_b32_e32 v154, v157
	v_pk_mul_f32 v[64:65], v[64:65], v[10:11] op_sel:[0,1]
	v_mov_b32_e32 v10, v13
	v_pk_mul_f32 v[72:73], v[72:73], v[6:7] op_sel:[0,1]
	v_mov_b32_e32 v6, v9
	v_pk_mul_f32 v[80:81], v[80:81], v[2:3] op_sel:[0,1]
	v_mov_b32_e32 v2, v5
	v_pk_mul_f32 v[54:55], v[54:55], v[156:157] op_sel_hi:[1,0]
	v_pk_mul_f32 v[58:59], v[58:59], v[154:155] op_sel_hi:[1,0]
	v_pk_mul_f32 v[62:63], v[62:63], v[12:13] op_sel_hi:[1,0]
	v_pk_mul_f32 v[66:67], v[66:67], v[10:11] op_sel_hi:[1,0]
	v_pk_mul_f32 v[70:71], v[70:71], v[8:9] op_sel_hi:[1,0]
	v_pk_mul_f32 v[74:75], v[74:75], v[6:7] op_sel_hi:[1,0]
	v_pk_mul_f32 v[78:79], v[78:79], v[4:5] op_sel_hi:[1,0]
	v_pk_mul_f32 v[82:83], v[82:83], v[2:3] op_sel_hi:[1,0]
	global_load_dwordx4 v[2:5], v149, s[6:7] offset:176
	global_load_dwordx4 v[6:9], v149, s[6:7] offset:160
	global_load_dwordx4 v[10:13], v149, s[6:7] offset:144
	global_load_dwordx4 v[154:157], v149, s[6:7] offset:128
	s_waitcnt vmcnt(3)
	v_pk_mul_f32 v[108:109], v[108:109], v[2:3] op_sel_hi:[1,0]
	s_waitcnt vmcnt(2)
	v_pk_mul_f32 v[100:101], v[100:101], v[6:7] op_sel_hi:[1,0]
	s_waitcnt vmcnt(1)
	v_pk_mul_f32 v[92:93], v[92:93], v[10:11] op_sel_hi:[1,0]
	s_waitcnt vmcnt(0)
	v_pk_mul_f32 v[84:85], v[84:85], v[154:155] op_sel_hi:[1,0]
	v_pk_mul_f32 v[88:89], v[88:89], v[154:155] op_sel:[0,1]
	v_mov_b32_e32 v154, v157
	v_pk_mul_f32 v[96:97], v[96:97], v[10:11] op_sel:[0,1]
	v_mov_b32_e32 v10, v13
	v_pk_mul_f32 v[104:105], v[104:105], v[6:7] op_sel:[0,1]
	v_mov_b32_e32 v6, v9
	v_pk_mul_f32 v[112:113], v[112:113], v[2:3] op_sel:[0,1]
	v_mov_b32_e32 v2, v5
	v_pk_mul_f32 v[86:87], v[86:87], v[156:157] op_sel_hi:[1,0]
	v_pk_mul_f32 v[90:91], v[90:91], v[154:155] op_sel_hi:[1,0]
	v_pk_mul_f32 v[94:95], v[94:95], v[12:13] op_sel_hi:[1,0]
	v_pk_mul_f32 v[98:99], v[98:99], v[10:11] op_sel_hi:[1,0]
	v_pk_mul_f32 v[102:103], v[102:103], v[8:9] op_sel_hi:[1,0]
	v_pk_mul_f32 v[106:107], v[106:107], v[6:7] op_sel_hi:[1,0]
	v_pk_mul_f32 v[110:111], v[110:111], v[4:5] op_sel_hi:[1,0]
	v_pk_mul_f32 v[114:115], v[114:115], v[2:3] op_sel_hi:[1,0]
	global_load_dwordx4 v[2:5], v149, s[6:7] offset:240
	global_load_dwordx4 v[6:9], v149, s[6:7] offset:224
	global_load_dwordx4 v[10:13], v149, s[6:7] offset:208
	global_load_dwordx4 v[154:157], v149, s[6:7] offset:192
	s_waitcnt vmcnt(3)
	v_pk_mul_f32 v[140:141], v[140:141], v[2:3] op_sel_hi:[1,0]
	s_waitcnt vmcnt(2)
	v_pk_mul_f32 v[132:133], v[132:133], v[6:7] op_sel_hi:[1,0]
	s_waitcnt vmcnt(1)
	v_pk_mul_f32 v[124:125], v[124:125], v[10:11] op_sel_hi:[1,0]
	s_waitcnt vmcnt(0)
	v_pk_mul_f32 v[116:117], v[116:117], v[154:155] op_sel_hi:[1,0]
	v_pk_mul_f32 v[120:121], v[120:121], v[154:155] op_sel:[0,1]
	v_mov_b32_e32 v154, v157
	v_pk_mul_f32 v[128:129], v[128:129], v[10:11] op_sel:[0,1]
	v_mov_b32_e32 v10, v13
	v_pk_mul_f32 v[136:137], v[136:137], v[6:7] op_sel:[0,1]
	v_mov_b32_e32 v6, v9
	v_pk_mul_f32 v[144:145], v[144:145], v[2:3] op_sel:[0,1]
	v_mov_b32_e32 v2, v5
	v_pk_mul_f32 v[118:119], v[118:119], v[156:157] op_sel_hi:[1,0]
	v_pk_mul_f32 v[122:123], v[122:123], v[154:155] op_sel_hi:[1,0]
	v_pk_mul_f32 v[126:127], v[126:127], v[12:13] op_sel_hi:[1,0]
	v_pk_mul_f32 v[130:131], v[130:131], v[10:11] op_sel_hi:[1,0]
	v_pk_mul_f32 v[134:135], v[134:135], v[8:9] op_sel_hi:[1,0]
	v_pk_mul_f32 v[138:139], v[138:139], v[6:7] op_sel_hi:[1,0]
	v_pk_mul_f32 v[142:143], v[142:143], v[4:5] op_sel_hi:[1,0]
	v_pk_mul_f32 v[146:147], v[146:147], v[2:3] op_sel_hi:[1,0]
	s_branch .LBB0_19

.LBB0_25:
	s_ashr_i32 s5, s3, 31
	s_lshr_b32 s5, s5, 29
	s_add_i32 s5, s3, s5
	s_ashr_i32 s5, s5, 3
	s_lshl_b32 s6, s5, 10
	s_lshl_b32 s36, s5, 6
	v_subrev_u32_e32 v2, s6, v56
	s_or_b32 s90, s36, 1
	s_or_b32 s92, s36, 2
	s_or_b32 s94, s36, 3
	s_or_b32 s6, s36, 4
	s_or_b32 s8, s36, 5
	s_or_b32 s10, s36, 6
	s_or_b32 s12, s36, 7
	s_or_b32 s14, s36, 8
	s_or_b32 s16, s36, 9
	s_or_b32 s18, s36, 10
	s_or_b32 s20, s36, 11
	s_or_b32 s22, s36, 12
	s_or_b32 s48, s36, 13
	s_or_b32 s54, s36, 14
	s_or_b32 s58, s36, 15
	s_or_b32 vcc_lo, s36, 16
	s_or_b32 s30, s36, 17
	s_or_b32 s62, s36, 18
	s_or_b32 s60, s36, 19
	s_or_b32 s56, s36, 20
	s_or_b32 s52, s36, 21
	s_or_b32 s50, s36, 22
	s_or_b32 s76, s36, 23
	s_ashr_i32 s37, s36, 31
	s_or_b32 s74, s36, 24
	v_ashrrev_i32_e32 v3, 31, v2
	s_ashr_i32 s91, s90, 31
	s_ashr_i32 s93, s92, 31
	s_ashr_i32 s95, s94, 31
	s_ashr_i32 s7, s6, 31
	s_ashr_i32 s9, s8, 31
	s_ashr_i32 s11, s10, 31
	s_ashr_i32 s13, s12, 31
	s_ashr_i32 s15, s14, 31
	s_ashr_i32 s17, s16, 31
	s_ashr_i32 s19, s18, 31
	s_ashr_i32 s21, s20, 31
	s_ashr_i32 s23, s22, 31
	s_ashr_i32 s49, s48, 31
	s_ashr_i32 s55, s54, 31
	s_ashr_i32 s59, s58, 31
	s_ashr_i32 vcc_hi, vcc_lo, 31
	s_ashr_i32 s31, s30, 31
	s_ashr_i32 s63, s62, 31
	s_ashr_i32 s61, s60, 31
	s_ashr_i32 s57, s56, 31
	s_ashr_i32 s53, s52, 31
	s_ashr_i32 s51, s50, 31
	s_ashr_i32 s77, s76, 31
	s_lshl_b64 s[88:89], s[36:37], 12
	v_lshl_add_u64 v[6:7], v[2:3], 2, s[34:35]
	s_lshl_b64 s[90:91], s[90:91], 12
	s_lshl_b64 s[92:93], s[92:93], 12
	s_lshl_b64 s[94:95], s[94:95], 12
	s_lshl_b64 s[6:7], s[6:7], 12
	s_lshl_b64 s[8:9], s[8:9], 12
	s_lshl_b64 s[10:11], s[10:11], 12
	s_lshl_b64 s[12:13], s[12:13], 12
	s_lshl_b64 s[14:15], s[14:15], 12
	s_lshl_b64 s[16:17], s[16:17], 12
	s_lshl_b64 s[18:19], s[18:19], 12
	s_lshl_b64 s[20:21], s[20:21], 12
	s_lshl_b64 s[22:23], s[22:23], 12
	s_lshl_b64 s[48:49], s[48:49], 12
	s_lshl_b64 s[54:55], s[54:55], 12
	s_lshl_b64 s[58:59], s[58:59], 12
	s_lshl_b64 vcc, vcc, 12
	s_lshl_b64 s[30:31], s[30:31], 12
	s_lshl_b64 s[62:63], s[62:63], 12
	s_lshl_b64 s[60:61], s[60:61], 12
	s_lshl_b64 s[56:57], s[56:57], 12
	s_lshl_b64 s[52:53], s[52:53], 12
	s_lshl_b64 s[50:51], s[50:51], 12
	s_lshl_b64 s[76:77], s[76:77], 12
	s_ashr_i32 s75, s74, 31
	s_or_b32 s38, s36, 25
	s_or_b32 s40, s36, 26
	s_or_b32 s42, s36, 27
	s_or_b32 s44, s36, 28
	s_or_b32 s64, s36, 29
	s_or_b32 s66, s36, 30
	s_or_b32 s68, s36, 31
	s_or_b32 s70, s36, 32
	s_or_b32 s72, s36, 33
	s_or_b32 s78, s36, 34
	s_or_b32 s80, s36, 35
	s_or_b32 s82, s36, 36
	s_or_b32 s84, s36, 37
	s_or_b32 s86, s36, 38
	v_lshl_add_u64 v[4:5], v[6:7], 0, s[88:89]
	s_or_b32 s88, s36, 39
	v_lshl_add_u64 v[8:9], v[6:7], 0, s[90:91]
	s_or_b32 s90, s36, 40
	v_lshl_add_u64 v[10:11], v[6:7], 0, s[92:93]
	s_or_b32 s92, s36, 41
	v_lshl_add_u64 v[12:13], v[6:7], 0, s[94:95]
	s_or_b32 s94, s36, 42
	v_lshl_add_u64 v[18:19], v[6:7], 0, s[6:7]
	s_or_b32 s6, s36, 43
	v_lshl_add_u64 v[20:21], v[6:7], 0, s[8:9]
	s_or_b32 s8, s36, 44
	v_lshl_add_u64 v[22:23], v[6:7], 0, s[10:11]
	s_or_b32 s10, s36, 45
	v_lshl_add_u64 v[24:25], v[6:7], 0, s[12:13]
	s_or_b32 s12, s36, 46
	v_lshl_add_u64 v[26:27], v[6:7], 0, s[14:15]
	s_or_b32 s14, s36, 47
	v_lshl_add_u64 v[28:29], v[6:7], 0, s[16:17]
	s_or_b32 s16, s36, 48
	v_lshl_add_u64 v[30:31], v[6:7], 0, s[18:19]
	s_or_b32 s18, s36, 49
	v_lshl_add_u64 v[32:33], v[6:7], 0, s[20:21]
	s_or_b32 s20, s36, 50
	v_lshl_add_u64 v[34:35], v[6:7], 0, s[22:23]
	s_or_b32 s22, s36, 51
	v_lshl_add_u64 v[36:37], v[6:7], 0, s[48:49]
	s_or_b32 s48, s36, 52
	v_lshl_add_u64 v[38:39], v[6:7], 0, s[54:55]
	s_or_b32 s54, s36, 53
	v_lshl_add_u64 v[40:41], v[6:7], 0, s[58:59]
	s_or_b32 s58, s36, 54
	v_lshl_add_u64 v[42:43], v[6:7], 0, vcc
	s_or_b32 vcc_lo, s36, 55
	v_lshl_add_u64 v[44:45], v[6:7], 0, s[30:31]
	s_or_b32 s30, s36, 56
	v_lshl_add_u64 v[46:47], v[6:7], 0, s[62:63]
	s_or_b32 s62, s36, 57
	v_lshl_add_u64 v[48:49], v[6:7], 0, s[60:61]
	s_or_b32 s60, s36, 58
	v_lshl_add_u64 v[50:51], v[6:7], 0, s[56:57]
	s_or_b32 s56, s36, 59
	v_lshl_add_u64 v[52:53], v[6:7], 0, s[52:53]
	s_or_b32 s52, s36, 60
	v_lshl_add_u64 v[54:55], v[6:7], 0, s[50:51]
	s_or_b32 s50, s36, 61
	v_lshl_add_u64 v[58:59], v[6:7], 0, s[76:77]
	s_or_b32 s76, s36, 62
	s_lshl_b64 s[74:75], s[74:75], 12
	v_lshl_add_u64 v[60:61], v[6:7], 0, s[74:75]
	s_or_b32 s74, s36, 63
	s_ashr_i32 s39, s38, 31
	s_ashr_i32 s41, s40, 31
	s_ashr_i32 s43, s42, 31
	s_ashr_i32 s45, s44, 31
	s_ashr_i32 s65, s64, 31
	s_ashr_i32 s67, s66, 31
	s_ashr_i32 s69, s68, 31
	s_ashr_i32 s71, s70, 31
	s_ashr_i32 s73, s72, 31
	s_ashr_i32 s79, s78, 31
	s_ashr_i32 s81, s80, 31
	s_ashr_i32 s83, s82, 31
	s_ashr_i32 s85, s84, 31
	s_ashr_i32 s87, s86, 31
	s_ashr_i32 s89, s88, 31
	s_ashr_i32 s91, s90, 31
	s_ashr_i32 s93, s92, 31
	s_ashr_i32 s95, s94, 31
	s_ashr_i32 s7, s6, 31
	s_ashr_i32 s9, s8, 31
	s_ashr_i32 s11, s10, 31
	s_ashr_i32 s13, s12, 31
	s_ashr_i32 s15, s14, 31
	s_ashr_i32 s17, s16, 31
	s_ashr_i32 s19, s18, 31
	s_ashr_i32 s21, s20, 31
	s_ashr_i32 s23, s22, 31
	s_ashr_i32 s49, s48, 31
	s_ashr_i32 s55, s54, 31
	s_ashr_i32 s59, s58, 31
	s_ashr_i32 vcc_hi, vcc_lo, 31
	s_ashr_i32 s31, s30, 31
	s_ashr_i32 s63, s62, 31
	s_ashr_i32 s61, s60, 31
	s_ashr_i32 s57, s56, 31
	s_ashr_i32 s53, s52, 31
	s_ashr_i32 s51, s50, 31
	s_ashr_i32 s77, s76, 31
	s_ashr_i32 s75, s74, 31
	s_lshl_b64 s[38:39], s[38:39], 12
	s_lshl_b64 s[40:41], s[40:41], 12
	s_lshl_b64 s[42:43], s[42:43], 12
	s_lshl_b64 s[44:45], s[44:45], 12
	s_lshl_b64 s[64:65], s[64:65], 12
	s_lshl_b64 s[66:67], s[66:67], 12
	s_lshl_b64 s[68:69], s[68:69], 12
	s_lshl_b64 s[70:71], s[70:71], 12
	s_lshl_b64 s[72:73], s[72:73], 12
	s_lshl_b64 s[78:79], s[78:79], 12
	s_lshl_b64 s[80:81], s[80:81], 12
	s_lshl_b64 s[82:83], s[82:83], 12
	s_lshl_b64 s[84:85], s[84:85], 12
	s_lshl_b64 s[86:87], s[86:87], 12
	s_lshl_b64 s[88:89], s[88:89], 12
	s_lshl_b64 s[90:91], s[90:91], 12
	s_lshl_b64 s[92:93], s[92:93], 12
	s_lshl_b64 s[94:95], s[94:95], 12
	s_lshl_b64 s[6:7], s[6:7], 12
	s_lshl_b64 s[8:9], s[8:9], 12
	s_lshl_b64 s[10:11], s[10:11], 12
	s_lshl_b64 s[12:13], s[12:13], 12
	s_lshl_b64 s[14:15], s[14:15], 12
	s_lshl_b64 s[16:17], s[16:17], 12
	s_lshl_b64 s[18:19], s[18:19], 12
	s_lshl_b64 s[20:21], s[20:21], 12
	s_lshl_b64 s[22:23], s[22:23], 12
	s_lshl_b64 s[48:49], s[48:49], 12
	s_lshl_b64 s[54:55], s[54:55], 12
	s_lshl_b64 s[58:59], s[58:59], 12
	s_lshl_b64 vcc, vcc, 12
	s_lshl_b64 s[30:31], s[30:31], 12
	s_lshl_b64 s[62:63], s[62:63], 12
	s_lshl_b64 s[60:61], s[60:61], 12
	s_lshl_b64 s[56:57], s[56:57], 12
	s_lshl_b64 s[52:53], s[52:53], 12
	s_lshl_b64 s[50:51], s[50:51], 12
	s_lshl_b64 s[76:77], s[76:77], 12
	s_lshl_b64 s[74:75], s[74:75], 12
	v_lshl_add_u64 v[64:65], v[6:7], 0, s[38:39]
	v_lshl_add_u64 v[66:67], v[6:7], 0, s[40:41]
	v_lshl_add_u64 v[68:69], v[6:7], 0, s[42:43]
	v_lshl_add_u64 v[70:71], v[6:7], 0, s[44:45]
	v_lshl_add_u64 v[72:73], v[6:7], 0, s[64:65]
	v_lshl_add_u64 v[74:75], v[6:7], 0, s[66:67]
	v_lshl_add_u64 v[76:77], v[6:7], 0, s[68:69]
	v_lshl_add_u64 v[78:79], v[6:7], 0, s[70:71]
	v_lshl_add_u64 v[80:81], v[6:7], 0, s[72:73]
	v_lshl_add_u64 v[82:83], v[6:7], 0, s[78:79]
	v_lshl_add_u64 v[84:85], v[6:7], 0, s[80:81]
	v_lshl_add_u64 v[86:87], v[6:7], 0, s[82:83]
	v_lshl_add_u64 v[88:89], v[6:7], 0, s[84:85]
	v_lshl_add_u64 v[90:91], v[6:7], 0, s[86:87]
	v_lshl_add_u64 v[92:93], v[6:7], 0, s[88:89]
	v_lshl_add_u64 v[94:95], v[6:7], 0, s[90:91]
	v_lshl_add_u64 v[96:97], v[6:7], 0, s[92:93]
	v_lshl_add_u64 v[98:99], v[6:7], 0, s[94:95]
	v_lshl_add_u64 v[100:101], v[6:7], 0, s[6:7]
	v_lshl_add_u64 v[102:103], v[6:7], 0, s[8:9]
	v_lshl_add_u64 v[104:105], v[6:7], 0, s[10:11]
	v_lshl_add_u64 v[106:107], v[6:7], 0, s[12:13]
	v_lshl_add_u64 v[108:109], v[6:7], 0, s[14:15]
	v_lshl_add_u64 v[110:111], v[6:7], 0, s[16:17]
	v_lshl_add_u64 v[112:113], v[6:7], 0, s[18:19]
	v_lshl_add_u64 v[114:115], v[6:7], 0, s[20:21]
	v_lshl_add_u64 v[116:117], v[6:7], 0, s[22:23]
	v_lshl_add_u64 v[118:119], v[6:7], 0, s[48:49]
	v_lshl_add_u64 v[120:121], v[6:7], 0, s[54:55]
	v_lshl_add_u64 v[122:123], v[6:7], 0, s[58:59]
	v_lshl_add_u64 v[124:125], v[6:7], 0, vcc
	v_lshl_add_u64 v[126:127], v[6:7], 0, s[30:31]
	v_lshl_add_u64 v[128:129], v[6:7], 0, s[62:63]
	v_lshl_add_u64 v[130:131], v[6:7], 0, s[60:61]
	v_lshl_add_u64 v[132:133], v[6:7], 0, s[56:57]
	v_lshl_add_u64 v[134:135], v[6:7], 0, s[52:53]
	v_lshl_add_u64 v[136:137], v[6:7], 0, s[50:51]
	v_lshl_add_u64 v[138:139], v[6:7], 0, s[76:77]
	v_lshl_add_u64 v[6:7], v[6:7], 0, s[74:75]
	global_load_dwordx2 v[140:141], v[4:5], off nt
	global_load_dwordx2 v[142:143], v[8:9], off nt
	global_load_dwordx2 v[144:145], v[10:11], off nt
	global_load_dwordx2 v[146:147], v[12:13], off nt
	global_load_dwordx2 v[152:153], v[18:19], off nt
	global_load_dwordx2 v[154:155], v[20:21], off nt
	global_load_dwordx2 v[156:157], v[22:23], off nt
	global_load_dwordx2 v[158:159], v[24:25], off nt
	global_load_dwordx2 v[160:161], v[26:27], off nt
	global_load_dwordx2 v[162:163], v[28:29], off nt
	global_load_dwordx2 v[164:165], v[30:31], off nt
	global_load_dwordx2 v[166:167], v[32:33], off nt
	global_load_dwordx2 v[168:169], v[34:35], off nt
	global_load_dwordx2 v[170:171], v[36:37], off nt
	global_load_dwordx2 v[172:173], v[38:39], off nt
	global_load_dwordx2 v[174:175], v[40:41], off nt
	global_load_dwordx2 v[176:177], v[42:43], off nt
	global_load_dwordx2 v[178:179], v[44:45], off nt
	s_nop 0
	global_load_dwordx2 v[46:47], v[46:47], off nt
	s_nop 0
	global_load_dwordx2 v[48:49], v[48:49], off nt
	s_nop 0
	global_load_dwordx2 v[50:51], v[50:51], off nt
	s_nop 0
	global_load_dwordx2 v[52:53], v[52:53], off nt
	s_nop 0
	global_load_dwordx2 v[54:55], v[54:55], off nt
	s_nop 0
	global_load_dwordx2 v[58:59], v[58:59], off nt
	s_nop 0
	global_load_dwordx2 v[60:61], v[60:61], off nt
	s_nop 0
	global_load_dwordx2 v[64:65], v[64:65], off nt
	s_nop 0
	global_load_dwordx2 v[66:67], v[66:67], off nt
	s_nop 0
	global_load_dwordx2 v[68:69], v[68:69], off nt
	s_nop 0
	global_load_dwordx2 v[70:71], v[70:71], off nt
	s_nop 0
	global_load_dwordx2 v[72:73], v[72:73], off nt
	s_nop 0
	global_load_dwordx2 v[74:75], v[74:75], off nt
	s_nop 0
	global_load_dwordx2 v[76:77], v[76:77], off nt
	s_nop 0
	global_load_dwordx2 v[78:79], v[78:79], off nt
	s_nop 0
	global_load_dwordx2 v[80:81], v[80:81], off nt
	s_nop 0
	global_load_dwordx2 v[82:83], v[82:83], off nt
	s_nop 0
	global_load_dwordx2 v[84:85], v[84:85], off nt
	s_nop 0
	global_load_dwordx2 v[86:87], v[86:87], off nt
	s_nop 0
	global_load_dwordx2 v[88:89], v[88:89], off nt
	s_nop 0
	global_load_dwordx2 v[90:91], v[90:91], off nt
	s_nop 0
	global_load_dwordx2 v[92:93], v[92:93], off nt
	s_nop 0
	global_load_dwordx2 v[94:95], v[94:95], off nt
	s_nop 0
	global_load_dwordx2 v[96:97], v[96:97], off nt
	s_nop 0
	global_load_dwordx2 v[98:99], v[98:99], off nt
	s_nop 0
	global_load_dwordx2 v[100:101], v[100:101], off nt
	s_nop 0
	global_load_dwordx2 v[102:103], v[102:103], off nt
	s_nop 0
	global_load_dwordx2 v[104:105], v[104:105], off nt
	s_nop 0
	global_load_dwordx2 v[106:107], v[106:107], off nt
	s_nop 0
	global_load_dwordx2 v[108:109], v[108:109], off nt
	s_nop 0
	global_load_dwordx2 v[110:111], v[110:111], off nt
	s_nop 0
	global_load_dwordx2 v[112:113], v[112:113], off nt
	s_nop 0
	global_load_dwordx2 v[114:115], v[114:115], off nt
	s_nop 0
	global_load_dwordx2 v[116:117], v[116:117], off nt
	s_nop 0
	global_load_dwordx2 v[118:119], v[118:119], off nt
	s_nop 0
	global_load_dwordx2 v[120:121], v[120:121], off nt
	s_nop 0
	global_load_dwordx2 v[122:123], v[122:123], off nt
	s_nop 0
	global_load_dwordx2 v[124:125], v[124:125], off nt
	s_nop 0
	global_load_dwordx2 v[126:127], v[126:127], off nt
	s_nop 0
	global_load_dwordx2 v[128:129], v[128:129], off nt
	s_nop 0
	global_load_dwordx2 v[130:131], v[130:131], off nt
	s_nop 0
	global_load_dwordx2 v[132:133], v[132:133], off nt
	s_nop 0
	global_load_dwordx2 v[134:135], v[134:135], off nt
	s_nop 0
	global_load_dwordx2 v[136:137], v[136:137], off nt
	s_nop 0
	global_load_dwordx2 v[138:139], v[138:139], off nt
	s_nop 0
	global_load_dwordx2 v[180:181], v[6:7], off nt
	s_lshl_b64 s[36:37], s[36:37], 1
	v_add_u32_e32 v62, 1, v2
	v_readlane_b32 s40, v250, 58
	s_add_u32 s6, s28, s36
	v_lshlrev_b64 v[2:3], 13, v[2:3]
	v_ashrrev_i32_e32 v63, 31, v62
	s_addc_u32 s7, s29, s37
	s_add_i32 s3, s3, s40
	v_add_u32_e32 v56, s4, v56
	v_lshlrev_b64 v[62:63], 13, v[62:63]
	v_lshl_add_u64 v[182:183], s[6:7], 0, v[2:3]
	s_cmpk_lt_i32 s3, 0x200
	v_readlane_b32 s41, v250, 59
	v_lshl_add_u64 v[184:185], s[6:7], 0, v[62:63]
	s_waitcnt vmcnt(62)
	v_cvt_pk_bf16_f32 v2, v140, v142
	v_cvt_pk_bf16_f32 v34, v141, v143
	s_waitcnt vmcnt(60)
	v_cvt_pk_bf16_f32 v3, v144, v146
	v_cvt_pk_bf16_f32 v35, v145, v147
	s_waitcnt vmcnt(58)
	v_cvt_pk_bf16_f32 v4, v152, v154
	v_cvt_pk_bf16_f32 v36, v153, v155
	s_waitcnt vmcnt(56)
	v_cvt_pk_bf16_f32 v5, v156, v158
	v_cvt_pk_bf16_f32 v37, v157, v159
	s_waitcnt vmcnt(54)
	v_cvt_pk_bf16_f32 v6, v160, v162
	v_cvt_pk_bf16_f32 v42, v161, v163
	s_waitcnt vmcnt(52)
	v_cvt_pk_bf16_f32 v7, v164, v166
	v_cvt_pk_bf16_f32 v43, v165, v167
	s_waitcnt vmcnt(50)
	v_cvt_pk_bf16_f32 v8, v168, v170
	v_cvt_pk_bf16_f32 v44, v169, v171
	s_waitcnt vmcnt(48)
	v_cvt_pk_bf16_f32 v9, v172, v174
	v_cvt_pk_bf16_f32 v45, v173, v175
	s_waitcnt vmcnt(46)
	v_cvt_pk_bf16_f32 v10, v176, v178
	s_waitcnt vmcnt(44)
	v_cvt_pk_bf16_f32 v11, v46, v48
	v_cvt_pk_bf16_f32 v46, v177, v179
	s_waitcnt vmcnt(42)
	v_cvt_pk_bf16_f32 v12, v50, v52
	v_cvt_pk_bf16_f32 v47, v47, v49
	s_waitcnt vmcnt(40)
	v_cvt_pk_bf16_f32 v13, v54, v58
	v_cvt_pk_bf16_f32 v48, v51, v53
	s_waitcnt vmcnt(38)
	v_cvt_pk_bf16_f32 v18, v60, v64
	v_cvt_pk_bf16_f32 v49, v55, v59
	s_waitcnt vmcnt(36)
	v_cvt_pk_bf16_f32 v19, v66, v68
	v_cvt_pk_bf16_f32 v50, v61, v65
	s_waitcnt vmcnt(34)
	v_cvt_pk_bf16_f32 v20, v70, v72
	v_cvt_pk_bf16_f32 v51, v67, v69
	s_waitcnt vmcnt(32)
	v_cvt_pk_bf16_f32 v21, v74, v76
	v_cvt_pk_bf16_f32 v52, v71, v73
	s_waitcnt vmcnt(30)
	v_cvt_pk_bf16_f32 v22, v78, v80
	v_cvt_pk_bf16_f32 v53, v75, v77
	s_waitcnt vmcnt(28)
	v_cvt_pk_bf16_f32 v23, v82, v84
	v_cvt_pk_bf16_f32 v58, v79, v81
	s_waitcnt vmcnt(26)
	v_cvt_pk_bf16_f32 v24, v86, v88
	v_cvt_pk_bf16_f32 v59, v83, v85
	s_waitcnt vmcnt(24)
	v_cvt_pk_bf16_f32 v25, v90, v92
	v_cvt_pk_bf16_f32 v60, v87, v89
	s_waitcnt vmcnt(22)
	v_cvt_pk_bf16_f32 v26, v94, v96
	v_cvt_pk_bf16_f32 v61, v91, v93
	s_waitcnt vmcnt(20)
	v_cvt_pk_bf16_f32 v27, v98, v100
	v_cvt_pk_bf16_f32 v62, v95, v97
	s_waitcnt vmcnt(18)
	v_cvt_pk_bf16_f32 v28, v102, v104
	v_cvt_pk_bf16_f32 v63, v99, v101
	s_waitcnt vmcnt(16)
	v_cvt_pk_bf16_f32 v29, v106, v108
	v_cvt_pk_bf16_f32 v64, v103, v105
	s_waitcnt vmcnt(14)
	v_cvt_pk_bf16_f32 v30, v110, v112
	v_cvt_pk_bf16_f32 v65, v107, v109
	s_waitcnt vmcnt(12)
	v_cvt_pk_bf16_f32 v31, v114, v116
	v_cvt_pk_bf16_f32 v66, v111, v113
	s_waitcnt vmcnt(10)
	v_cvt_pk_bf16_f32 v32, v118, v120
	v_cvt_pk_bf16_f32 v67, v115, v117
	s_waitcnt vmcnt(8)
	v_cvt_pk_bf16_f32 v33, v122, v124
	v_cvt_pk_bf16_f32 v68, v119, v121
	s_waitcnt vmcnt(6)
	v_cvt_pk_bf16_f32 v38, v126, v128
	v_cvt_pk_bf16_f32 v69, v123, v125
	s_waitcnt vmcnt(4)
	v_cvt_pk_bf16_f32 v39, v130, v132
	v_cvt_pk_bf16_f32 v70, v127, v129
	s_waitcnt vmcnt(2)
	v_cvt_pk_bf16_f32 v40, v134, v136
	v_cvt_pk_bf16_f32 v71, v131, v133
	s_waitcnt vmcnt(0)
	v_cvt_pk_bf16_f32 v41, v138, v180
	v_cvt_pk_bf16_f32 v72, v135, v137
	v_cvt_pk_bf16_f32 v73, v139, v181
	global_store_dwordx4 v[182:183], v[2:5], off
	global_store_dwordx4 v[182:183], v[6:9], off offset:16
	global_store_dwordx4 v[182:183], v[10:13], off offset:32
	global_store_dwordx4 v[182:183], v[18:21], off offset:48
	global_store_dwordx4 v[182:183], v[22:25], off offset:64
	global_store_dwordx4 v[182:183], v[26:29], off offset:80
	global_store_dwordx4 v[182:183], v[30:33], off offset:96
	global_store_dwordx4 v[182:183], v[38:41], off offset:112
	global_store_dwordx4 v[184:185], v[34:37], off
	global_store_dwordx4 v[184:185], v[42:45], off offset:16
	global_store_dwordx4 v[184:185], v[46:49], off offset:32
	global_store_dwordx4 v[184:185], v[50:53], off offset:48
	global_store_dwordx4 v[184:185], v[58:61], off offset:64
	global_store_dwordx4 v[184:185], v[62:65], off offset:80
	global_store_dwordx4 v[184:185], v[66:69], off offset:96
	global_store_dwordx4 v[184:185], v[70:73], off offset:112
	s_cbranch_scc1 .LBB0_25
	v_readlane_b32 s38, v251, 12
	v_readlane_b32 s70, v250, 56
	v_readlane_b32 s48, v250, 60
	v_readlane_b32 s76, v250, 3
	v_readlane_b32 s39, v251, 13
	v_readlane_b32 s16, v251, 18
	v_readlane_b32 s18, v251, 20
	v_readlane_b32 s20, v251, 32
	v_readlane_b32 s22, v251, 34
	v_readlane_b32 s14, v251, 36
	v_readlane_b32 s72, v250, 54
	v_readlane_b32 s71, v250, 57
	v_readlane_b32 s50, v250, 62
	v_readlane_b32 s51, v250, 63
	v_readlane_b32 s52, v251, 0
	v_readlane_b32 s53, v251, 1
	v_readlane_b32 s54, v251, 2
	v_readlane_b32 s55, v251, 3
	v_readlane_b32 s56, v251, 4
	v_readlane_b32 s57, v251, 5
	v_readlane_b32 s58, v251, 6
	v_readlane_b32 s59, v251, 7
	v_readlane_b32 s60, v251, 8
	v_readlane_b32 s61, v251, 9
	v_readlane_b32 s62, v251, 10
	v_readlane_b32 s63, v251, 11
	v_readlane_b32 s77, v250, 4
	v_readlane_b32 s78, v250, 5
	v_readlane_b32 s79, v250, 6
	v_readlane_b32 s80, v250, 7
	v_readlane_b32 s81, v250, 8
	v_readlane_b32 s82, v250, 9
	v_readlane_b32 s83, v250, 10
	v_readlane_b32 s84, v250, 11
	v_readlane_b32 s85, v250, 12
	v_readlane_b32 s86, v250, 13
	v_readlane_b32 s87, v250, 14
	v_readlane_b32 s88, v250, 15
	v_readlane_b32 s89, v250, 16
	v_readlane_b32 s90, v250, 17
	v_readlane_b32 s91, v250, 18
	v_readlane_b32 s39, v251, 14
	v_readlane_b32 s41, v251, 16
	v_readlane_b32 s17, v251, 19
	v_readlane_b32 s19, v251, 21
	v_readlane_b32 s21, v251, 33
	v_readlane_b32 s23, v251, 35
	v_readlane_b32 s15, v251, 37
	v_readlane_b32 s73, v250, 55
	v_readlane_b32 s49, v250, 61

.LBB0_30:
	s_ashr_i32 s6, s3, 31
	s_lshr_b32 s6, s6, 29
	s_add_i32 s6, s3, s6
	s_ashr_i32 s6, s6, 3
	s_lshl_b32 s7, s6, 10
	v_subrev_u32_e32 v2, s7, v136
	s_lshl_b32 s28, s6, 6
	v_ashrrev_i32_e32 v3, 31, v2
	s_ashr_i32 s29, s28, 31
	v_lshl_add_u64 v[128:129], v[2:3], 2, s[30:31]
	s_lshl_b64 s[6:7], s[28:29], 12
	v_lshl_add_u64 v[4:5], v[128:129], 0, s[6:7]
	s_or_b32 s6, s28, 1
	s_ashr_i32 s7, s6, 31
	s_lshl_b64 s[6:7], s[6:7], 12
	v_lshl_add_u64 v[6:7], v[128:129], 0, s[6:7]
	s_or_b32 s6, s28, 2
	s_ashr_i32 s7, s6, 31
	s_lshl_b64 s[6:7], s[6:7], 12
	v_lshl_add_u64 v[10:11], v[128:129], 0, s[6:7]
	s_or_b32 s6, s28, 3
	s_ashr_i32 s7, s6, 31
	s_lshl_b64 s[6:7], s[6:7], 12
	v_lshl_add_u64 v[12:13], v[128:129], 0, s[6:7]
	s_or_b32 s6, s28, 4
	s_ashr_i32 s7, s6, 31
	s_lshl_b64 s[6:7], s[6:7], 12
	global_load_dwordx2 v[4:5], v[4:5], off nt
	s_nop 0
	global_load_dwordx2 v[8:9], v[6:7], off nt
	s_nop 0
	global_load_dwordx2 v[6:7], v[10:11], off nt
	s_nop 0
	global_load_dwordx2 v[10:11], v[12:13], off nt
	v_lshl_add_u64 v[12:13], v[128:129], 0, s[6:7]
	s_or_b32 s6, s28, 5
	s_ashr_i32 s7, s6, 31
	s_lshl_b64 s[6:7], s[6:7], 12
	v_lshl_add_u64 v[18:19], v[128:129], 0, s[6:7]
	s_or_b32 s6, s28, 6
	s_ashr_i32 s7, s6, 31
	s_lshl_b64 s[6:7], s[6:7], 12
	v_lshl_add_u64 v[22:23], v[128:129], 0, s[6:7]
	s_or_b32 s6, s28, 7
	s_ashr_i32 s7, s6, 31
	s_lshl_b64 s[6:7], s[6:7], 12
	v_lshl_add_u64 v[24:25], v[128:129], 0, s[6:7]
	s_or_b32 s6, s28, 8
	s_ashr_i32 s7, s6, 31
	s_lshl_b64 s[6:7], s[6:7], 12
	global_load_dwordx2 v[12:13], v[12:13], off nt
	s_nop 0
	global_load_dwordx2 v[20:21], v[18:19], off nt
	s_nop 0
	global_load_dwordx2 v[18:19], v[22:23], off nt
	s_nop 0
	global_load_dwordx2 v[22:23], v[24:25], off nt
	v_lshl_add_u64 v[24:25], v[128:129], 0, s[6:7]
	s_or_b32 s6, s28, 9
	s_ashr_i32 s7, s6, 31
	s_lshl_b64 s[6:7], s[6:7], 12
	v_lshl_add_u64 v[26:27], v[128:129], 0, s[6:7]
	s_or_b32 s6, s28, 10
	s_ashr_i32 s7, s6, 31
	s_lshl_b64 s[6:7], s[6:7], 12
	v_lshl_add_u64 v[30:31], v[128:129], 0, s[6:7]
	s_or_b32 s6, s28, 11
	s_ashr_i32 s7, s6, 31
	s_lshl_b64 s[6:7], s[6:7], 12
	v_lshl_add_u64 v[32:33], v[128:129], 0, s[6:7]
	s_or_b32 s6, s28, 12
	s_ashr_i32 s7, s6, 31
	s_lshl_b64 s[6:7], s[6:7], 12
	global_load_dwordx2 v[24:25], v[24:25], off nt
	s_nop 0
	global_load_dwordx2 v[28:29], v[26:27], off nt
	s_nop 0
	global_load_dwordx2 v[26:27], v[30:31], off nt
	s_nop 0
	global_load_dwordx2 v[30:31], v[32:33], off nt
	v_lshl_add_u64 v[32:33], v[128:129], 0, s[6:7]
	s_or_b32 s6, s28, 13
	s_ashr_i32 s7, s6, 31
	s_lshl_b64 s[6:7], s[6:7], 12
	v_lshl_add_u64 v[34:35], v[128:129], 0, s[6:7]
	s_or_b32 s6, s28, 14
	s_ashr_i32 s7, s6, 31
	s_lshl_b64 s[6:7], s[6:7], 12
	v_lshl_add_u64 v[38:39], v[128:129], 0, s[6:7]
	s_or_b32 s6, s28, 15
	s_ashr_i32 s7, s6, 31
	s_lshl_b64 s[6:7], s[6:7], 12
	v_lshl_add_u64 v[40:41], v[128:129], 0, s[6:7]
	s_or_b32 s6, s28, 16
	s_ashr_i32 s7, s6, 31
	s_lshl_b64 s[6:7], s[6:7], 12
	global_load_dwordx2 v[32:33], v[32:33], off nt
	s_nop 0
	global_load_dwordx2 v[36:37], v[34:35], off nt
	s_nop 0
	global_load_dwordx2 v[34:35], v[38:39], off nt
	s_nop 0
	global_load_dwordx2 v[38:39], v[40:41], off nt
	v_lshl_add_u64 v[40:41], v[128:129], 0, s[6:7]
	s_or_b32 s6, s28, 17
	s_ashr_i32 s7, s6, 31
	s_lshl_b64 s[6:7], s[6:7], 12
	v_lshl_add_u64 v[42:43], v[128:129], 0, s[6:7]
	s_or_b32 s6, s28, 18
	s_ashr_i32 s7, s6, 31
	s_lshl_b64 s[6:7], s[6:7], 12
	v_lshl_add_u64 v[46:47], v[128:129], 0, s[6:7]
	s_or_b32 s6, s28, 19
	s_ashr_i32 s7, s6, 31
	s_lshl_b64 s[6:7], s[6:7], 12
	v_lshl_add_u64 v[48:49], v[128:129], 0, s[6:7]
	s_or_b32 s6, s28, 20
	s_ashr_i32 s7, s6, 31
	s_lshl_b64 s[6:7], s[6:7], 12
	global_load_dwordx2 v[40:41], v[40:41], off nt
	s_nop 0
	global_load_dwordx2 v[44:45], v[42:43], off nt
	s_nop 0
	global_load_dwordx2 v[42:43], v[46:47], off nt
	s_nop 0
	global_load_dwordx2 v[46:47], v[48:49], off nt
	v_lshl_add_u64 v[48:49], v[128:129], 0, s[6:7]
	s_or_b32 s6, s28, 21
	s_ashr_i32 s7, s6, 31
	s_lshl_b64 s[6:7], s[6:7], 12
	v_lshl_add_u64 v[50:51], v[128:129], 0, s[6:7]
	s_or_b32 s6, s28, 22
	s_ashr_i32 s7, s6, 31
	s_lshl_b64 s[6:7], s[6:7], 12
	v_lshl_add_u64 v[54:55], v[128:129], 0, s[6:7]
	s_or_b32 s6, s28, 23
	s_ashr_i32 s7, s6, 31
	s_lshl_b64 s[6:7], s[6:7], 12
	v_lshl_add_u64 v[56:57], v[128:129], 0, s[6:7]
	s_or_b32 s6, s28, 24
	s_ashr_i32 s7, s6, 31
	s_lshl_b64 s[6:7], s[6:7], 12
	global_load_dwordx2 v[48:49], v[48:49], off nt
	s_nop 0
	global_load_dwordx2 v[52:53], v[50:51], off nt
	s_nop 0
	global_load_dwordx2 v[50:51], v[54:55], off nt
	s_nop 0
	global_load_dwordx2 v[54:55], v[56:57], off nt
	v_lshl_add_u64 v[56:57], v[128:129], 0, s[6:7]
	s_or_b32 s6, s28, 25
	s_ashr_i32 s7, s6, 31
	s_lshl_b64 s[6:7], s[6:7], 12
	v_lshl_add_u64 v[58:59], v[128:129], 0, s[6:7]
	s_or_b32 s6, s28, 26
	s_ashr_i32 s7, s6, 31
	s_lshl_b64 s[6:7], s[6:7], 12
	v_lshl_add_u64 v[62:63], v[128:129], 0, s[6:7]
	s_or_b32 s6, s28, 27
	s_ashr_i32 s7, s6, 31
	s_lshl_b64 s[6:7], s[6:7], 12
	v_lshl_add_u64 v[64:65], v[128:129], 0, s[6:7]
	s_or_b32 s6, s28, 28
	s_ashr_i32 s7, s6, 31
	s_lshl_b64 s[6:7], s[6:7], 12
	global_load_dwordx2 v[56:57], v[56:57], off nt
	s_nop 0
	global_load_dwordx2 v[60:61], v[58:59], off nt
	s_nop 0
	global_load_dwordx2 v[58:59], v[62:63], off nt
	s_nop 0
	global_load_dwordx2 v[62:63], v[64:65], off nt
	v_lshl_add_u64 v[64:65], v[128:129], 0, s[6:7]
	s_or_b32 s6, s28, 29
	s_ashr_i32 s7, s6, 31
	s_lshl_b64 s[6:7], s[6:7], 12
	v_lshl_add_u64 v[66:67], v[128:129], 0, s[6:7]
	s_or_b32 s6, s28, 30
	s_ashr_i32 s7, s6, 31
	s_lshl_b64 s[6:7], s[6:7], 12
	v_lshl_add_u64 v[70:71], v[128:129], 0, s[6:7]
	s_or_b32 s6, s28, 31
	s_ashr_i32 s7, s6, 31
	s_lshl_b64 s[6:7], s[6:7], 12
	v_lshl_add_u64 v[72:73], v[128:129], 0, s[6:7]
	s_or_b32 s6, s28, 32
	s_ashr_i32 s7, s6, 31
	s_lshl_b64 s[6:7], s[6:7], 12
	global_load_dwordx2 v[64:65], v[64:65], off nt
	s_nop 0
	global_load_dwordx2 v[68:69], v[66:67], off nt
	s_nop 0
	global_load_dwordx2 v[66:67], v[70:71], off nt
	s_nop 0
	global_load_dwordx2 v[70:71], v[72:73], off nt
	v_lshl_add_u64 v[72:73], v[128:129], 0, s[6:7]
	s_or_b32 s6, s28, 33
	s_ashr_i32 s7, s6, 31
	s_lshl_b64 s[6:7], s[6:7], 12
	v_lshl_add_u64 v[74:75], v[128:129], 0, s[6:7]
	s_or_b32 s6, s28, 34
	s_ashr_i32 s7, s6, 31
	s_lshl_b64 s[6:7], s[6:7], 12
	v_lshl_add_u64 v[78:79], v[128:129], 0, s[6:7]
	s_or_b32 s6, s28, 35
	s_ashr_i32 s7, s6, 31
	s_lshl_b64 s[6:7], s[6:7], 12
	v_lshl_add_u64 v[80:81], v[128:129], 0, s[6:7]
	s_or_b32 s6, s28, 36
	s_ashr_i32 s7, s6, 31
	s_lshl_b64 s[6:7], s[6:7], 12
	global_load_dwordx2 v[72:73], v[72:73], off nt
	s_nop 0
	global_load_dwordx2 v[76:77], v[74:75], off nt
	s_nop 0
	global_load_dwordx2 v[74:75], v[78:79], off nt
	s_nop 0
	global_load_dwordx2 v[78:79], v[80:81], off nt
	v_lshl_add_u64 v[80:81], v[128:129], 0, s[6:7]
	s_or_b32 s6, s28, 37
	s_ashr_i32 s7, s6, 31
	s_lshl_b64 s[6:7], s[6:7], 12
	v_lshl_add_u64 v[82:83], v[128:129], 0, s[6:7]
	s_or_b32 s6, s28, 38
	s_ashr_i32 s7, s6, 31
	s_lshl_b64 s[6:7], s[6:7], 12
	v_lshl_add_u64 v[86:87], v[128:129], 0, s[6:7]
	s_or_b32 s6, s28, 39
	s_ashr_i32 s7, s6, 31
	s_lshl_b64 s[6:7], s[6:7], 12
	v_lshl_add_u64 v[88:89], v[128:129], 0, s[6:7]
	s_or_b32 s6, s28, 40
	s_ashr_i32 s7, s6, 31
	s_lshl_b64 s[6:7], s[6:7], 12
	global_load_dwordx2 v[80:81], v[80:81], off nt
	s_nop 0
	global_load_dwordx2 v[84:85], v[82:83], off nt
	s_nop 0
	global_load_dwordx2 v[82:83], v[86:87], off nt
	s_nop 0
	global_load_dwordx2 v[86:87], v[88:89], off nt
	v_lshl_add_u64 v[88:89], v[128:129], 0, s[6:7]
	s_or_b32 s6, s28, 41
	s_ashr_i32 s7, s6, 31
	s_lshl_b64 s[6:7], s[6:7], 12
	v_lshl_add_u64 v[90:91], v[128:129], 0, s[6:7]
	s_or_b32 s6, s28, 42
	s_ashr_i32 s7, s6, 31
	s_lshl_b64 s[6:7], s[6:7], 12
	v_lshl_add_u64 v[94:95], v[128:129], 0, s[6:7]
	s_or_b32 s6, s28, 43
	s_ashr_i32 s7, s6, 31
	s_lshl_b64 s[6:7], s[6:7], 12
	v_lshl_add_u64 v[96:97], v[128:129], 0, s[6:7]
	s_or_b32 s6, s28, 44
	s_ashr_i32 s7, s6, 31
	s_lshl_b64 s[6:7], s[6:7], 12
	global_load_dwordx2 v[88:89], v[88:89], off nt
	s_nop 0
	global_load_dwordx2 v[92:93], v[90:91], off nt
	s_nop 0
	global_load_dwordx2 v[90:91], v[94:95], off nt
	s_nop 0
	global_load_dwordx2 v[94:95], v[96:97], off nt
	v_lshl_add_u64 v[96:97], v[128:129], 0, s[6:7]
	s_or_b32 s6, s28, 45
	s_ashr_i32 s7, s6, 31
	s_lshl_b64 s[6:7], s[6:7], 12
	v_lshl_add_u64 v[98:99], v[128:129], 0, s[6:7]
	s_or_b32 s6, s28, 46
	s_ashr_i32 s7, s6, 31
	s_lshl_b64 s[6:7], s[6:7], 12
	v_lshl_add_u64 v[102:103], v[128:129], 0, s[6:7]
	s_or_b32 s6, s28, 47
	s_ashr_i32 s7, s6, 31
	s_lshl_b64 s[6:7], s[6:7], 12
	v_lshl_add_u64 v[104:105], v[128:129], 0, s[6:7]
	s_or_b32 s6, s28, 48
	s_ashr_i32 s7, s6, 31
	s_lshl_b64 s[6:7], s[6:7], 12
	global_load_dwordx2 v[96:97], v[96:97], off nt
	s_nop 0
	global_load_dwordx2 v[100:101], v[98:99], off nt
	s_nop 0
	global_load_dwordx2 v[98:99], v[102:103], off nt
	s_nop 0
	global_load_dwordx2 v[102:103], v[104:105], off nt
	v_lshl_add_u64 v[104:105], v[128:129], 0, s[6:7]
	s_or_b32 s6, s28, 49
	s_ashr_i32 s7, s6, 31
	s_lshl_b64 s[6:7], s[6:7], 12
	v_lshl_add_u64 v[106:107], v[128:129], 0, s[6:7]
	s_or_b32 s6, s28, 50
	s_ashr_i32 s7, s6, 31
	s_lshl_b64 s[6:7], s[6:7], 12
	v_lshl_add_u64 v[110:111], v[128:129], 0, s[6:7]
	s_or_b32 s6, s28, 51
	s_ashr_i32 s7, s6, 31
	s_lshl_b64 s[6:7], s[6:7], 12
	v_lshl_add_u64 v[112:113], v[128:129], 0, s[6:7]
	s_or_b32 s6, s28, 52
	s_ashr_i32 s7, s6, 31
	s_lshl_b64 s[6:7], s[6:7], 12
	global_load_dwordx2 v[104:105], v[104:105], off nt
	s_nop 0
	global_load_dwordx2 v[108:109], v[106:107], off nt
	s_nop 0
	global_load_dwordx2 v[106:107], v[110:111], off nt
	s_nop 0
	global_load_dwordx2 v[110:111], v[112:113], off nt
	v_lshl_add_u64 v[112:113], v[128:129], 0, s[6:7]
	s_or_b32 s6, s28, 53
	s_ashr_i32 s7, s6, 31
	s_lshl_b64 s[6:7], s[6:7], 12
	v_lshl_add_u64 v[114:115], v[128:129], 0, s[6:7]
	s_or_b32 s6, s28, 54
	s_ashr_i32 s7, s6, 31
	s_lshl_b64 s[6:7], s[6:7], 12
	v_lshl_add_u64 v[118:119], v[128:129], 0, s[6:7]
	s_or_b32 s6, s28, 55
	s_ashr_i32 s7, s6, 31
	s_lshl_b64 s[6:7], s[6:7], 12
	v_lshl_add_u64 v[120:121], v[128:129], 0, s[6:7]
	s_or_b32 s6, s28, 56
	s_ashr_i32 s7, s6, 31
	s_lshl_b64 s[6:7], s[6:7], 12
	global_load_dwordx2 v[112:113], v[112:113], off nt
	s_nop 0
	global_load_dwordx2 v[116:117], v[114:115], off nt
	s_nop 0
	global_load_dwordx2 v[114:115], v[118:119], off nt
	s_nop 0
	global_load_dwordx2 v[118:119], v[120:121], off nt
	v_lshl_add_u64 v[120:121], v[128:129], 0, s[6:7]
	s_or_b32 s6, s28, 57
	s_ashr_i32 s7, s6, 31
	s_lshl_b64 s[6:7], s[6:7], 12
	v_lshl_add_u64 v[122:123], v[128:129], 0, s[6:7]
	s_or_b32 s6, s28, 58
	s_ashr_i32 s7, s6, 31
	s_lshl_b64 s[6:7], s[6:7], 12
	v_lshl_add_u64 v[126:127], v[128:129], 0, s[6:7]
	s_or_b32 s6, s28, 59
	s_ashr_i32 s7, s6, 31
	s_lshl_b64 s[6:7], s[6:7], 12
	v_lshl_add_u64 v[130:131], v[128:129], 0, s[6:7]
	s_or_b32 s6, s28, 60
	s_ashr_i32 s7, s6, 31
	s_lshl_b64 s[6:7], s[6:7], 12
	global_load_dwordx2 v[120:121], v[120:121], off nt
	s_nop 0
	global_load_dwordx2 v[124:125], v[122:123], off nt
	s_nop 0
	global_load_dwordx2 v[122:123], v[126:127], off nt
	s_nop 0
	global_load_dwordx2 v[126:127], v[130:131], off nt
	v_lshl_add_u64 v[130:131], v[128:129], 0, s[6:7]
	s_or_b32 s6, s28, 61
	s_ashr_i32 s7, s6, 31
	s_lshl_b64 s[6:7], s[6:7], 12
	v_lshl_add_u64 v[132:133], v[128:129], 0, s[6:7]
	s_or_b32 s6, s28, 62
	s_ashr_i32 s7, s6, 31
	s_lshl_b64 s[6:7], s[6:7], 12
	v_lshl_add_u64 v[134:135], v[128:129], 0, s[6:7]
	s_or_b32 s6, s28, 63
	s_ashr_i32 s7, s6, 31
	s_lshl_b64 s[6:7], s[6:7], 12
	v_lshl_add_u64 v[138:139], v[128:129], 0, s[6:7]
	global_load_dwordx2 v[128:129], v[130:131], off nt
	s_nop 0
	global_load_dwordx2 v[132:133], v[132:133], off nt
	s_nop 0
	global_load_dwordx2 v[130:131], v[134:135], off nt
	s_nop 0
	global_load_dwordx2 v[134:135], v[138:139], off nt
	s_andn2_b64 vcc, exec, s[24:25]
	s_cbranch_vccnz .LBB0_29
	s_lshl_b64 s[6:7], s[28:29], 2
	s_add_u32 s6, s4, s6
	s_addc_u32 s7, s5, s7
	global_load_dwordx4 v[138:141], v149, s[6:7]
	global_load_dwordx4 v[142:145], v149, s[6:7] offset:16
	global_load_dwordx4 v[152:155], v149, s[6:7] offset:32
	global_load_dwordx4 v[156:159], v149, s[6:7] offset:48
	global_load_dwordx4 v[160:163], v149, s[6:7] offset:64
	global_load_dwordx4 v[164:167], v149, s[6:7] offset:80
	global_load_dwordx4 v[168:171], v149, s[6:7] offset:96
	global_load_dwordx4 v[172:175], v149, s[6:7] offset:112
	global_load_dwordx4 v[176:179], v149, s[6:7] offset:128
	global_load_dwordx4 v[180:183], v149, s[6:7] offset:144
	global_load_dwordx4 v[184:187], v149, s[6:7] offset:160
	global_load_dwordx4 v[188:191], v149, s[6:7] offset:176
	global_load_dwordx4 v[192:195], v149, s[6:7] offset:192
	global_load_dwordx4 v[196:199], v149, s[6:7] offset:208
	global_load_dwordx4 v[200:203], v149, s[6:7] offset:224
	global_load_dwordx4 v[204:207], v149, s[6:7] offset:240
	s_waitcnt vmcnt(15)
	v_pk_mul_f32 v[4:5], v[4:5], v[138:139] op_sel_hi:[1,0]
	v_pk_mul_f32 v[8:9], v[8:9], v[138:139] op_sel:[0,1]
	v_mov_b32_e32 v138, v141
	v_pk_mul_f32 v[10:11], v[10:11], v[138:139] op_sel_hi:[1,0]
	v_pk_mul_f32 v[6:7], v[6:7], v[140:141] op_sel_hi:[1,0]
	s_waitcnt vmcnt(14)
	v_pk_mul_f32 v[12:13], v[12:13], v[142:143] op_sel_hi:[1,0]
	v_pk_mul_f32 v[20:21], v[20:21], v[142:143] op_sel:[0,1]
	v_pk_mul_f32 v[18:19], v[18:19], v[144:145] op_sel_hi:[1,0]
	v_mov_b32_e32 v140, v145
	s_waitcnt vmcnt(13)
	v_pk_mul_f32 v[24:25], v[24:25], v[152:153] op_sel_hi:[1,0]
	v_pk_mul_f32 v[28:29], v[28:29], v[152:153] op_sel:[0,1]
	v_pk_mul_f32 v[26:27], v[26:27], v[154:155] op_sel_hi:[1,0]
	v_mov_b32_e32 v142, v155
	s_waitcnt vmcnt(2)
	v_mov_b32_e32 v138, v199
	v_pk_mul_f32 v[118:119], v[118:119], v[138:139] op_sel_hi:[1,0]
	s_waitcnt vmcnt(1)
	v_mov_b32_e32 v138, v203
	v_pk_mul_f32 v[32:33], v[32:33], v[156:157] op_sel_hi:[1,0]
	v_pk_mul_f32 v[36:37], v[36:37], v[156:157] op_sel:[0,1]
	v_pk_mul_f32 v[34:35], v[34:35], v[158:159] op_sel_hi:[1,0]
	v_mov_b32_e32 v144, v159
	v_pk_mul_f32 v[40:41], v[40:41], v[160:161] op_sel_hi:[1,0]
	v_pk_mul_f32 v[44:45], v[44:45], v[160:161] op_sel:[0,1]
	v_pk_mul_f32 v[42:43], v[42:43], v[162:163] op_sel_hi:[1,0]
	v_mov_b32_e32 v146, v163
	v_pk_mul_f32 v[48:49], v[48:49], v[164:165] op_sel_hi:[1,0]
	v_pk_mul_f32 v[52:53], v[52:53], v[164:165] op_sel:[0,1]
	v_pk_mul_f32 v[50:51], v[50:51], v[166:167] op_sel_hi:[1,0]
	v_mov_b32_e32 v152, v167
	v_mov_b32_e32 v154, v171
	v_mov_b32_e32 v156, v175
	v_mov_b32_e32 v158, v179
	v_mov_b32_e32 v160, v183
	v_mov_b32_e32 v162, v187
	v_mov_b32_e32 v164, v191
	v_mov_b32_e32 v166, v195
	v_pk_mul_f32 v[126:127], v[126:127], v[138:139] op_sel_hi:[1,0]
	s_waitcnt vmcnt(0)
	v_mov_b32_e32 v138, v207
	v_pk_mul_f32 v[56:57], v[56:57], v[168:169] op_sel_hi:[1,0]
	v_pk_mul_f32 v[60:61], v[60:61], v[168:169] op_sel:[0,1]
	v_pk_mul_f32 v[58:59], v[58:59], v[170:171] op_sel_hi:[1,0]
	v_pk_mul_f32 v[64:65], v[64:65], v[172:173] op_sel_hi:[1,0]
	v_pk_mul_f32 v[68:69], v[68:69], v[172:173] op_sel:[0,1]
	v_pk_mul_f32 v[66:67], v[66:67], v[174:175] op_sel_hi:[1,0]
	v_pk_mul_f32 v[72:73], v[72:73], v[176:177] op_sel_hi:[1,0]
	v_pk_mul_f32 v[76:77], v[76:77], v[176:177] op_sel:[0,1]
	v_pk_mul_f32 v[74:75], v[74:75], v[178:179] op_sel_hi:[1,0]
	v_pk_mul_f32 v[80:81], v[80:81], v[180:181] op_sel_hi:[1,0]
	v_pk_mul_f32 v[84:85], v[84:85], v[180:181] op_sel:[0,1]
	v_pk_mul_f32 v[82:83], v[82:83], v[182:183] op_sel_hi:[1,0]
	v_pk_mul_f32 v[88:89], v[88:89], v[184:185] op_sel_hi:[1,0]
	v_pk_mul_f32 v[92:93], v[92:93], v[184:185] op_sel:[0,1]
	v_pk_mul_f32 v[90:91], v[90:91], v[186:187] op_sel_hi:[1,0]
	v_pk_mul_f32 v[96:97], v[96:97], v[188:189] op_sel_hi:[1,0]
	v_pk_mul_f32 v[100:101], v[100:101], v[188:189] op_sel:[0,1]
	v_pk_mul_f32 v[98:99], v[98:99], v[190:191] op_sel_hi:[1,0]
	v_pk_mul_f32 v[104:105], v[104:105], v[192:193] op_sel_hi:[1,0]
	v_pk_mul_f32 v[108:109], v[108:109], v[192:193] op_sel:[0,1]
	v_pk_mul_f32 v[106:107], v[106:107], v[194:195] op_sel_hi:[1,0]
	v_pk_mul_f32 v[112:113], v[112:113], v[196:197] op_sel_hi:[1,0]
	v_pk_mul_f32 v[22:23], v[22:23], v[140:141] op_sel_hi:[1,0]
	v_pk_mul_f32 v[30:31], v[30:31], v[142:143] op_sel_hi:[1,0]
	v_pk_mul_f32 v[38:39], v[38:39], v[144:145] op_sel_hi:[1,0]
	v_pk_mul_f32 v[46:47], v[46:47], v[146:147] op_sel_hi:[1,0]
	v_pk_mul_f32 v[54:55], v[54:55], v[152:153] op_sel_hi:[1,0]
	v_pk_mul_f32 v[62:63], v[62:63], v[154:155] op_sel_hi:[1,0]
	v_pk_mul_f32 v[70:71], v[70:71], v[156:157] op_sel_hi:[1,0]
	v_pk_mul_f32 v[78:79], v[78:79], v[158:159] op_sel_hi:[1,0]
	v_pk_mul_f32 v[86:87], v[86:87], v[160:161] op_sel_hi:[1,0]
	v_pk_mul_f32 v[94:95], v[94:95], v[162:163] op_sel_hi:[1,0]
	v_pk_mul_f32 v[102:103], v[102:103], v[164:165] op_sel_hi:[1,0]
	v_pk_mul_f32 v[110:111], v[110:111], v[166:167] op_sel_hi:[1,0]
	v_pk_mul_f32 v[116:117], v[116:117], v[196:197] op_sel:[0,1]
	v_pk_mul_f32 v[114:115], v[114:115], v[198:199] op_sel_hi:[1,0]
	v_pk_mul_f32 v[120:121], v[120:121], v[200:201] op_sel_hi:[1,0]
	v_pk_mul_f32 v[124:125], v[124:125], v[200:201] op_sel:[0,1]
	v_pk_mul_f32 v[122:123], v[122:123], v[202:203] op_sel_hi:[1,0]
	v_pk_mul_f32 v[128:129], v[128:129], v[204:205] op_sel_hi:[1,0]
	v_pk_mul_f32 v[132:133], v[132:133], v[204:205] op_sel:[0,1]
	v_pk_mul_f32 v[130:131], v[130:131], v[206:207] op_sel_hi:[1,0]
	v_pk_mul_f32 v[134:135], v[134:135], v[138:139] op_sel_hi:[1,0]
	s_branch .LBB0_29

.LBB0_34:
	s_ashr_i32 s5, s3, 31
	s_lshr_b32 s5, s5, 29
	s_add_i32 s5, s3, s5
	s_ashr_i32 s5, s5, 3
	s_lshl_b32 s6, s5, 10
	s_lshl_b32 s30, s5, 6
	v_subrev_u32_e32 v2, s6, v56
	s_or_b32 s86, s30, 1
	s_or_b32 s88, s30, 2
	s_or_b32 s90, s30, 3
	s_or_b32 s6, s30, 4
	s_or_b32 s8, s30, 5
	s_or_b32 s10, s30, 6
	s_or_b32 s12, s30, 7
	s_or_b32 s14, s30, 8
	s_or_b32 s16, s30, 9
	s_or_b32 s18, s30, 10
	s_or_b32 s20, s30, 11
	s_or_b32 s22, s30, 12
	s_or_b32 s48, s30, 13
	s_or_b32 s54, s30, 14
	s_or_b32 s58, s30, 15
	s_or_b32 s92, s30, 16
	s_or_b32 s94, s30, 17
	s_or_b32 s62, s30, 18
	s_or_b32 s60, s30, 19
	s_or_b32 s56, s30, 20
	s_or_b32 s52, s30, 21
	s_or_b32 s50, s30, 22
	s_or_b32 s72, s30, 23
	s_ashr_i32 s31, s30, 31
	s_or_b32 s70, s30, 24
	v_ashrrev_i32_e32 v3, 31, v2
	s_ashr_i32 s87, s86, 31
	s_ashr_i32 s89, s88, 31
	s_ashr_i32 s91, s90, 31
	s_ashr_i32 s7, s6, 31
	s_ashr_i32 s9, s8, 31
	s_ashr_i32 s11, s10, 31
	s_ashr_i32 s13, s12, 31
	s_ashr_i32 s15, s14, 31
	s_ashr_i32 s17, s16, 31
	s_ashr_i32 s19, s18, 31
	s_ashr_i32 s21, s20, 31
	s_ashr_i32 s23, s22, 31
	s_ashr_i32 s49, s48, 31
	s_ashr_i32 s55, s54, 31
	s_ashr_i32 s59, s58, 31
	s_ashr_i32 s93, s92, 31
	s_ashr_i32 s95, s94, 31
	s_ashr_i32 s63, s62, 31
	s_ashr_i32 s61, s60, 31
	s_ashr_i32 s57, s56, 31
	s_ashr_i32 s53, s52, 31
	s_ashr_i32 s51, s50, 31
	s_ashr_i32 s73, s72, 31
	s_lshl_b64 s[84:85], s[30:31], 12
	v_lshl_add_u64 v[6:7], v[2:3], 2, s[28:29]
	s_lshl_b64 s[86:87], s[86:87], 12
	s_lshl_b64 s[88:89], s[88:89], 12
	s_lshl_b64 s[90:91], s[90:91], 12
	s_lshl_b64 s[6:7], s[6:7], 12
	s_lshl_b64 s[8:9], s[8:9], 12
	s_lshl_b64 s[10:11], s[10:11], 12
	s_lshl_b64 s[12:13], s[12:13], 12
	s_lshl_b64 s[14:15], s[14:15], 12
	s_lshl_b64 s[16:17], s[16:17], 12
	s_lshl_b64 s[18:19], s[18:19], 12
	s_lshl_b64 s[20:21], s[20:21], 12
	s_lshl_b64 s[22:23], s[22:23], 12
	s_lshl_b64 s[48:49], s[48:49], 12
	s_lshl_b64 s[54:55], s[54:55], 12
	s_lshl_b64 s[58:59], s[58:59], 12
	s_lshl_b64 s[92:93], s[92:93], 12
	s_lshl_b64 s[94:95], s[94:95], 12
	s_lshl_b64 s[62:63], s[62:63], 12
	s_lshl_b64 s[60:61], s[60:61], 12
	s_lshl_b64 s[56:57], s[56:57], 12
	s_lshl_b64 s[52:53], s[52:53], 12
	s_lshl_b64 s[50:51], s[50:51], 12
	s_lshl_b64 s[72:73], s[72:73], 12
	s_ashr_i32 s71, s70, 31
	s_or_b32 s34, s30, 25
	s_or_b32 s36, s30, 26
	s_or_b32 s38, s30, 27
	s_or_b32 s40, s30, 28
	s_or_b32 s42, s30, 29
	s_or_b32 s44, s30, 30
	s_or_b32 s64, s30, 31
	s_or_b32 s66, s30, 32
	s_or_b32 s68, s30, 33
	s_or_b32 s74, s30, 34
	s_or_b32 s76, s30, 35
	s_or_b32 s78, s30, 36
	s_or_b32 s80, s30, 37
	s_or_b32 s82, s30, 38
	v_lshl_add_u64 v[4:5], v[6:7], 0, s[84:85]
	s_or_b32 s84, s30, 39
	v_lshl_add_u64 v[8:9], v[6:7], 0, s[86:87]
	s_or_b32 s86, s30, 40
	v_lshl_add_u64 v[10:11], v[6:7], 0, s[88:89]
	s_or_b32 s88, s30, 41
	v_lshl_add_u64 v[12:13], v[6:7], 0, s[90:91]
	s_or_b32 s90, s30, 42
	v_lshl_add_u64 v[18:19], v[6:7], 0, s[6:7]
	s_or_b32 s6, s30, 43
	v_lshl_add_u64 v[20:21], v[6:7], 0, s[8:9]
	s_or_b32 s8, s30, 44
	v_lshl_add_u64 v[22:23], v[6:7], 0, s[10:11]
	s_or_b32 s10, s30, 45
	v_lshl_add_u64 v[24:25], v[6:7], 0, s[12:13]
	s_or_b32 s12, s30, 46
	v_lshl_add_u64 v[26:27], v[6:7], 0, s[14:15]
	s_or_b32 s14, s30, 47
	v_lshl_add_u64 v[28:29], v[6:7], 0, s[16:17]
	s_or_b32 s16, s30, 48
	v_lshl_add_u64 v[30:31], v[6:7], 0, s[18:19]
	s_or_b32 s18, s30, 49
	v_lshl_add_u64 v[32:33], v[6:7], 0, s[20:21]
	s_or_b32 s20, s30, 50
	v_lshl_add_u64 v[34:35], v[6:7], 0, s[22:23]
	s_or_b32 s22, s30, 51
	v_lshl_add_u64 v[36:37], v[6:7], 0, s[48:49]
	s_or_b32 s48, s30, 52
	v_lshl_add_u64 v[38:39], v[6:7], 0, s[54:55]
	s_or_b32 s54, s30, 53
	v_lshl_add_u64 v[40:41], v[6:7], 0, s[58:59]
	s_or_b32 s58, s30, 54
	v_lshl_add_u64 v[42:43], v[6:7], 0, s[92:93]
	s_or_b32 s92, s30, 55
	v_lshl_add_u64 v[44:45], v[6:7], 0, s[94:95]
	s_or_b32 s94, s30, 56
	v_lshl_add_u64 v[46:47], v[6:7], 0, s[62:63]
	s_or_b32 s62, s30, 57
	v_lshl_add_u64 v[48:49], v[6:7], 0, s[60:61]
	s_or_b32 s60, s30, 58
	v_lshl_add_u64 v[50:51], v[6:7], 0, s[56:57]
	s_or_b32 s56, s30, 59
	v_lshl_add_u64 v[52:53], v[6:7], 0, s[52:53]
	s_or_b32 s52, s30, 60
	v_lshl_add_u64 v[54:55], v[6:7], 0, s[50:51]
	s_or_b32 s50, s30, 61
	v_lshl_add_u64 v[58:59], v[6:7], 0, s[72:73]
	s_or_b32 s72, s30, 62
	s_lshl_b64 s[70:71], s[70:71], 12
	v_lshl_add_u64 v[60:61], v[6:7], 0, s[70:71]
	s_or_b32 s70, s30, 63
	s_ashr_i32 s35, s34, 31
	s_ashr_i32 s37, s36, 31
	s_ashr_i32 s39, s38, 31
	s_ashr_i32 s41, s40, 31
	s_ashr_i32 s43, s42, 31
	s_ashr_i32 s45, s44, 31
	s_ashr_i32 s65, s64, 31
	s_ashr_i32 s67, s66, 31
	s_ashr_i32 s69, s68, 31
	s_ashr_i32 s75, s74, 31
	s_ashr_i32 s77, s76, 31
	s_ashr_i32 s79, s78, 31
	s_ashr_i32 s81, s80, 31
	s_ashr_i32 s83, s82, 31
	s_ashr_i32 s85, s84, 31
	s_ashr_i32 s87, s86, 31
	s_ashr_i32 s89, s88, 31
	s_ashr_i32 s91, s90, 31
	s_ashr_i32 s7, s6, 31
	s_ashr_i32 s9, s8, 31
	s_ashr_i32 s11, s10, 31
	s_ashr_i32 s13, s12, 31
	s_ashr_i32 s15, s14, 31
	s_ashr_i32 s17, s16, 31
	s_ashr_i32 s19, s18, 31
	s_ashr_i32 s21, s20, 31
	s_ashr_i32 s23, s22, 31
	s_ashr_i32 s49, s48, 31
	s_ashr_i32 s55, s54, 31
	s_ashr_i32 s59, s58, 31
	s_ashr_i32 s93, s92, 31
	s_ashr_i32 s95, s94, 31
	s_ashr_i32 s63, s62, 31
	s_ashr_i32 s61, s60, 31
	s_ashr_i32 s57, s56, 31
	s_ashr_i32 s53, s52, 31
	s_ashr_i32 s51, s50, 31
	s_ashr_i32 s73, s72, 31
	s_ashr_i32 s71, s70, 31
	s_lshl_b64 s[34:35], s[34:35], 12
	s_lshl_b64 s[36:37], s[36:37], 12
	s_lshl_b64 s[38:39], s[38:39], 12
	s_lshl_b64 s[40:41], s[40:41], 12
	s_lshl_b64 s[42:43], s[42:43], 12
	s_lshl_b64 s[44:45], s[44:45], 12
	s_lshl_b64 s[64:65], s[64:65], 12
	s_lshl_b64 s[66:67], s[66:67], 12
	s_lshl_b64 s[68:69], s[68:69], 12
	s_lshl_b64 s[74:75], s[74:75], 12
	s_lshl_b64 s[76:77], s[76:77], 12
	s_lshl_b64 s[78:79], s[78:79], 12
	s_lshl_b64 s[80:81], s[80:81], 12
	s_lshl_b64 s[82:83], s[82:83], 12
	s_lshl_b64 s[84:85], s[84:85], 12
	s_lshl_b64 s[86:87], s[86:87], 12
	s_lshl_b64 s[88:89], s[88:89], 12
	s_lshl_b64 s[90:91], s[90:91], 12
	s_lshl_b64 s[6:7], s[6:7], 12
	s_lshl_b64 s[8:9], s[8:9], 12
	s_lshl_b64 s[10:11], s[10:11], 12
	s_lshl_b64 s[12:13], s[12:13], 12
	s_lshl_b64 s[14:15], s[14:15], 12
	s_lshl_b64 s[16:17], s[16:17], 12
	s_lshl_b64 s[18:19], s[18:19], 12
	s_lshl_b64 s[20:21], s[20:21], 12
	s_lshl_b64 s[22:23], s[22:23], 12
	s_lshl_b64 s[48:49], s[48:49], 12
	s_lshl_b64 s[54:55], s[54:55], 12
	s_lshl_b64 s[58:59], s[58:59], 12
	s_lshl_b64 s[92:93], s[92:93], 12
	s_lshl_b64 s[94:95], s[94:95], 12
	s_lshl_b64 s[62:63], s[62:63], 12
	s_lshl_b64 s[60:61], s[60:61], 12
	s_lshl_b64 s[56:57], s[56:57], 12
	s_lshl_b64 s[52:53], s[52:53], 12
	s_lshl_b64 s[50:51], s[50:51], 12
	s_lshl_b64 s[72:73], s[72:73], 12
	s_lshl_b64 s[70:71], s[70:71], 12
	v_lshl_add_u64 v[64:65], v[6:7], 0, s[34:35]
	v_lshl_add_u64 v[66:67], v[6:7], 0, s[36:37]
	v_lshl_add_u64 v[68:69], v[6:7], 0, s[38:39]
	v_lshl_add_u64 v[70:71], v[6:7], 0, s[40:41]
	v_lshl_add_u64 v[72:73], v[6:7], 0, s[42:43]
	v_lshl_add_u64 v[74:75], v[6:7], 0, s[44:45]
	v_lshl_add_u64 v[76:77], v[6:7], 0, s[64:65]
	v_lshl_add_u64 v[78:79], v[6:7], 0, s[66:67]
	v_lshl_add_u64 v[80:81], v[6:7], 0, s[68:69]
	v_lshl_add_u64 v[82:83], v[6:7], 0, s[74:75]
	v_lshl_add_u64 v[84:85], v[6:7], 0, s[76:77]
	v_lshl_add_u64 v[86:87], v[6:7], 0, s[78:79]
	v_lshl_add_u64 v[88:89], v[6:7], 0, s[80:81]
	v_lshl_add_u64 v[90:91], v[6:7], 0, s[82:83]
	v_lshl_add_u64 v[92:93], v[6:7], 0, s[84:85]
	v_lshl_add_u64 v[94:95], v[6:7], 0, s[86:87]
	v_lshl_add_u64 v[96:97], v[6:7], 0, s[88:89]
	v_lshl_add_u64 v[98:99], v[6:7], 0, s[90:91]
	v_lshl_add_u64 v[100:101], v[6:7], 0, s[6:7]
	v_lshl_add_u64 v[102:103], v[6:7], 0, s[8:9]
	v_lshl_add_u64 v[104:105], v[6:7], 0, s[10:11]
	v_lshl_add_u64 v[106:107], v[6:7], 0, s[12:13]
	v_lshl_add_u64 v[108:109], v[6:7], 0, s[14:15]
	v_lshl_add_u64 v[110:111], v[6:7], 0, s[16:17]
	v_lshl_add_u64 v[112:113], v[6:7], 0, s[18:19]
	v_lshl_add_u64 v[114:115], v[6:7], 0, s[20:21]
	v_lshl_add_u64 v[116:117], v[6:7], 0, s[22:23]
	v_lshl_add_u64 v[118:119], v[6:7], 0, s[48:49]
	v_lshl_add_u64 v[120:121], v[6:7], 0, s[54:55]
	v_lshl_add_u64 v[122:123], v[6:7], 0, s[58:59]
	v_lshl_add_u64 v[124:125], v[6:7], 0, s[92:93]
	v_lshl_add_u64 v[126:127], v[6:7], 0, s[94:95]
	v_lshl_add_u64 v[128:129], v[6:7], 0, s[62:63]
	v_lshl_add_u64 v[130:131], v[6:7], 0, s[60:61]
	v_lshl_add_u64 v[132:133], v[6:7], 0, s[56:57]
	v_lshl_add_u64 v[134:135], v[6:7], 0, s[52:53]
	v_lshl_add_u64 v[136:137], v[6:7], 0, s[50:51]
	v_lshl_add_u64 v[138:139], v[6:7], 0, s[72:73]
	v_lshl_add_u64 v[6:7], v[6:7], 0, s[70:71]
	global_load_dwordx2 v[140:141], v[4:5], off nt
	global_load_dwordx2 v[142:143], v[8:9], off nt
	global_load_dwordx2 v[144:145], v[10:11], off nt
	global_load_dwordx2 v[146:147], v[12:13], off nt
	global_load_dwordx2 v[152:153], v[18:19], off nt
	global_load_dwordx2 v[154:155], v[20:21], off nt
	global_load_dwordx2 v[156:157], v[22:23], off nt
	global_load_dwordx2 v[158:159], v[24:25], off nt
	global_load_dwordx2 v[160:161], v[26:27], off nt
	global_load_dwordx2 v[162:163], v[28:29], off nt
	global_load_dwordx2 v[164:165], v[30:31], off nt
	global_load_dwordx2 v[166:167], v[32:33], off nt
	global_load_dwordx2 v[168:169], v[34:35], off nt
	global_load_dwordx2 v[170:171], v[36:37], off nt
	global_load_dwordx2 v[172:173], v[38:39], off nt
	global_load_dwordx2 v[174:175], v[40:41], off nt
	global_load_dwordx2 v[176:177], v[42:43], off nt
	global_load_dwordx2 v[178:179], v[44:45], off nt
	s_nop 0
	global_load_dwordx2 v[46:47], v[46:47], off nt
	s_nop 0
	global_load_dwordx2 v[48:49], v[48:49], off nt
	s_nop 0
	global_load_dwordx2 v[50:51], v[50:51], off nt
	s_nop 0
	global_load_dwordx2 v[52:53], v[52:53], off nt
	s_nop 0
	global_load_dwordx2 v[54:55], v[54:55], off nt
	s_nop 0
	global_load_dwordx2 v[58:59], v[58:59], off nt
	s_nop 0
	global_load_dwordx2 v[60:61], v[60:61], off nt
	s_nop 0
	global_load_dwordx2 v[64:65], v[64:65], off nt
	s_nop 0
	global_load_dwordx2 v[66:67], v[66:67], off nt
	s_nop 0
	global_load_dwordx2 v[68:69], v[68:69], off nt
	s_nop 0
	global_load_dwordx2 v[70:71], v[70:71], off nt
	s_nop 0
	global_load_dwordx2 v[72:73], v[72:73], off nt
	s_nop 0
	global_load_dwordx2 v[74:75], v[74:75], off nt
	s_nop 0
	global_load_dwordx2 v[76:77], v[76:77], off nt
	s_nop 0
	global_load_dwordx2 v[78:79], v[78:79], off nt
	s_nop 0
	global_load_dwordx2 v[80:81], v[80:81], off nt
	s_nop 0
	global_load_dwordx2 v[82:83], v[82:83], off nt
	s_nop 0
	global_load_dwordx2 v[84:85], v[84:85], off nt
	s_nop 0
	global_load_dwordx2 v[86:87], v[86:87], off nt
	s_nop 0
	global_load_dwordx2 v[88:89], v[88:89], off nt
	s_nop 0
	global_load_dwordx2 v[90:91], v[90:91], off nt
	s_nop 0
	global_load_dwordx2 v[92:93], v[92:93], off nt
	s_nop 0
	global_load_dwordx2 v[94:95], v[94:95], off nt
	s_nop 0
	global_load_dwordx2 v[96:97], v[96:97], off nt
	s_nop 0
	global_load_dwordx2 v[98:99], v[98:99], off nt
	s_nop 0
	global_load_dwordx2 v[100:101], v[100:101], off nt
	s_nop 0
	global_load_dwordx2 v[102:103], v[102:103], off nt
	s_nop 0
	global_load_dwordx2 v[104:105], v[104:105], off nt
	s_nop 0
	global_load_dwordx2 v[106:107], v[106:107], off nt
	s_nop 0
	global_load_dwordx2 v[108:109], v[108:109], off nt
	s_nop 0
	global_load_dwordx2 v[110:111], v[110:111], off nt
	s_nop 0
	global_load_dwordx2 v[112:113], v[112:113], off nt
	s_nop 0
	global_load_dwordx2 v[114:115], v[114:115], off nt
	s_nop 0
	global_load_dwordx2 v[116:117], v[116:117], off nt
	s_nop 0
	global_load_dwordx2 v[118:119], v[118:119], off nt
	s_nop 0
	global_load_dwordx2 v[120:121], v[120:121], off nt
	s_nop 0
	global_load_dwordx2 v[122:123], v[122:123], off nt
	s_nop 0
	global_load_dwordx2 v[124:125], v[124:125], off nt
	s_nop 0
	global_load_dwordx2 v[126:127], v[126:127], off nt
	s_nop 0
	global_load_dwordx2 v[128:129], v[128:129], off nt
	s_nop 0
	global_load_dwordx2 v[130:131], v[130:131], off nt
	s_nop 0
	global_load_dwordx2 v[132:133], v[132:133], off nt
	s_nop 0
	global_load_dwordx2 v[134:135], v[134:135], off nt
	s_nop 0
	global_load_dwordx2 v[136:137], v[136:137], off nt
	s_nop 0
	global_load_dwordx2 v[138:139], v[138:139], off nt
	s_nop 0
	global_load_dwordx2 v[180:181], v[6:7], off nt
	s_lshl_b64 s[30:31], s[30:31], 1
	v_add_u32_e32 v62, 1, v2
	v_readlane_b32 s40, v250, 58
	s_add_u32 s6, s27, s30
	v_lshlrev_b64 v[2:3], 9, v[2:3]
	v_ashrrev_i32_e32 v63, 31, v62
	s_addc_u32 s7, s0, s31
	s_add_i32 s3, s3, s40
	v_add_u32_e32 v56, s4, v56
	v_lshlrev_b64 v[62:63], 9, v[62:63]
	v_lshl_add_u64 v[182:183], s[6:7], 0, v[2:3]
	s_cmp_lt_i32 s3, 32
	v_readlane_b32 s41, v250, 59
	v_lshl_add_u64 v[184:185], s[6:7], 0, v[62:63]
	s_waitcnt vmcnt(62)
	v_cvt_pk_bf16_f32 v2, v140, v142
	v_cvt_pk_bf16_f32 v34, v141, v143
	s_waitcnt vmcnt(60)
	v_cvt_pk_bf16_f32 v3, v144, v146
	v_cvt_pk_bf16_f32 v35, v145, v147
	s_waitcnt vmcnt(58)
	v_cvt_pk_bf16_f32 v4, v152, v154
	v_cvt_pk_bf16_f32 v36, v153, v155
	s_waitcnt vmcnt(56)
	v_cvt_pk_bf16_f32 v5, v156, v158
	v_cvt_pk_bf16_f32 v37, v157, v159
	s_waitcnt vmcnt(54)
	v_cvt_pk_bf16_f32 v6, v160, v162
	v_cvt_pk_bf16_f32 v42, v161, v163
	s_waitcnt vmcnt(52)
	v_cvt_pk_bf16_f32 v7, v164, v166
	v_cvt_pk_bf16_f32 v43, v165, v167
	s_waitcnt vmcnt(50)
	v_cvt_pk_bf16_f32 v8, v168, v170
	v_cvt_pk_bf16_f32 v44, v169, v171
	s_waitcnt vmcnt(48)
	v_cvt_pk_bf16_f32 v9, v172, v174
	v_cvt_pk_bf16_f32 v45, v173, v175
	s_waitcnt vmcnt(46)
	v_cvt_pk_bf16_f32 v10, v176, v178
	s_waitcnt vmcnt(44)
	v_cvt_pk_bf16_f32 v11, v46, v48
	v_cvt_pk_bf16_f32 v46, v177, v179
	s_waitcnt vmcnt(42)
	v_cvt_pk_bf16_f32 v12, v50, v52
	v_cvt_pk_bf16_f32 v47, v47, v49
	s_waitcnt vmcnt(40)
	v_cvt_pk_bf16_f32 v13, v54, v58
	v_cvt_pk_bf16_f32 v48, v51, v53
	s_waitcnt vmcnt(38)
	v_cvt_pk_bf16_f32 v18, v60, v64
	v_cvt_pk_bf16_f32 v49, v55, v59
	s_waitcnt vmcnt(36)
	v_cvt_pk_bf16_f32 v19, v66, v68
	v_cvt_pk_bf16_f32 v50, v61, v65
	s_waitcnt vmcnt(34)
	v_cvt_pk_bf16_f32 v20, v70, v72
	v_cvt_pk_bf16_f32 v51, v67, v69
	s_waitcnt vmcnt(32)
	v_cvt_pk_bf16_f32 v21, v74, v76
	v_cvt_pk_bf16_f32 v52, v71, v73
	s_waitcnt vmcnt(30)
	v_cvt_pk_bf16_f32 v22, v78, v80
	v_cvt_pk_bf16_f32 v53, v75, v77
	s_waitcnt vmcnt(28)
	v_cvt_pk_bf16_f32 v23, v82, v84
	v_cvt_pk_bf16_f32 v58, v79, v81
	s_waitcnt vmcnt(26)
	v_cvt_pk_bf16_f32 v24, v86, v88
	v_cvt_pk_bf16_f32 v59, v83, v85
	s_waitcnt vmcnt(24)
	v_cvt_pk_bf16_f32 v25, v90, v92
	v_cvt_pk_bf16_f32 v60, v87, v89
	s_waitcnt vmcnt(22)
	v_cvt_pk_bf16_f32 v26, v94, v96
	v_cvt_pk_bf16_f32 v61, v91, v93
	s_waitcnt vmcnt(20)
	v_cvt_pk_bf16_f32 v27, v98, v100
	v_cvt_pk_bf16_f32 v62, v95, v97
	s_waitcnt vmcnt(18)
	v_cvt_pk_bf16_f32 v28, v102, v104
	v_cvt_pk_bf16_f32 v63, v99, v101
	s_waitcnt vmcnt(16)
	v_cvt_pk_bf16_f32 v29, v106, v108
	v_cvt_pk_bf16_f32 v64, v103, v105
	s_waitcnt vmcnt(14)
	v_cvt_pk_bf16_f32 v30, v110, v112
	v_cvt_pk_bf16_f32 v65, v107, v109
	s_waitcnt vmcnt(12)
	v_cvt_pk_bf16_f32 v31, v114, v116
	v_cvt_pk_bf16_f32 v66, v111, v113
	s_waitcnt vmcnt(10)
	v_cvt_pk_bf16_f32 v32, v118, v120
	v_cvt_pk_bf16_f32 v67, v115, v117
	s_waitcnt vmcnt(8)
	v_cvt_pk_bf16_f32 v33, v122, v124
	v_cvt_pk_bf16_f32 v68, v119, v121
	s_waitcnt vmcnt(6)
	v_cvt_pk_bf16_f32 v38, v126, v128
	v_cvt_pk_bf16_f32 v69, v123, v125
	s_waitcnt vmcnt(4)
	v_cvt_pk_bf16_f32 v39, v130, v132
	v_cvt_pk_bf16_f32 v70, v127, v129
	s_waitcnt vmcnt(2)
	v_cvt_pk_bf16_f32 v40, v134, v136
	v_cvt_pk_bf16_f32 v71, v131, v133
	s_waitcnt vmcnt(0)
	v_cvt_pk_bf16_f32 v41, v138, v180
	v_cvt_pk_bf16_f32 v72, v135, v137
	v_cvt_pk_bf16_f32 v73, v139, v181
	global_store_dwordx4 v[182:183], v[2:5], off
	global_store_dwordx4 v[182:183], v[6:9], off offset:16
	global_store_dwordx4 v[182:183], v[10:13], off offset:32
	global_store_dwordx4 v[182:183], v[18:21], off offset:48
	global_store_dwordx4 v[182:183], v[22:25], off offset:64
	global_store_dwordx4 v[182:183], v[26:29], off offset:80
	global_store_dwordx4 v[182:183], v[30:33], off offset:96
	global_store_dwordx4 v[182:183], v[38:41], off offset:112
	global_store_dwordx4 v[184:185], v[34:37], off
	global_store_dwordx4 v[184:185], v[42:45], off offset:16
	global_store_dwordx4 v[184:185], v[46:49], off offset:32
	global_store_dwordx4 v[184:185], v[50:53], off offset:48
	global_store_dwordx4 v[184:185], v[58:61], off offset:64
	global_store_dwordx4 v[184:185], v[62:65], off offset:80
	global_store_dwordx4 v[184:185], v[66:69], off offset:96
	global_store_dwordx4 v[184:185], v[70:73], off offset:112
	s_cbranch_scc1 .LBB0_34
	v_readlane_b32 s38, v251, 12
	v_readlane_b32 s70, v250, 56
	v_readlane_b32 s48, v250, 60
	v_readlane_b32 s76, v250, 3
	v_readlane_b32 s39, v251, 13
	v_readlane_b32 s16, v251, 18
	v_readlane_b32 s18, v251, 20
	v_readlane_b32 s20, v251, 32
	v_readlane_b32 s72, v250, 54
	v_readlane_b32 s71, v250, 57
	v_readlane_b32 s56, v251, 4
	v_readlane_b32 s57, v251, 5
	v_readlane_b32 s58, v251, 6
	v_readlane_b32 s59, v251, 7
	v_readlane_b32 s60, v251, 8
	v_readlane_b32 s61, v251, 9
	v_readlane_b32 s62, v251, 10
	v_readlane_b32 s63, v251, 11
	v_readlane_b32 s77, v250, 4
	v_readlane_b32 s78, v250, 5
	v_readlane_b32 s79, v250, 6
	v_readlane_b32 s80, v250, 7
	v_readlane_b32 s81, v250, 8
	v_readlane_b32 s82, v250, 9
	v_readlane_b32 s83, v250, 10
	v_readlane_b32 s84, v250, 11
	v_readlane_b32 s85, v250, 12
	v_readlane_b32 s86, v250, 13
	v_readlane_b32 s87, v250, 14
	v_readlane_b32 s88, v250, 15
	v_readlane_b32 s89, v250, 16
	v_readlane_b32 s90, v250, 17
	v_readlane_b32 s91, v250, 18
	v_readlane_b32 s39, v251, 14
	v_readlane_b32 s41, v251, 16
	v_readlane_b32 s17, v251, 19
	v_readlane_b32 s19, v251, 21
	v_readlane_b32 s21, v251, 33
	v_readlane_b32 s73, v250, 55
	v_readlane_b32 s49, v250, 61
	v_readlane_b32 s50, v250, 62
	v_readlane_b32 s51, v250, 63
	v_readlane_b32 s52, v251, 0
	v_readlane_b32 s53, v251, 1
	v_readlane_b32 s54, v251, 2
	v_readlane_b32 s55, v251, 3
	s_branch .LBB0_6

.LBB0_41:
	s_ashr_i32 s0, s3, 31
	s_lshr_b32 s0, s0, 28
	s_add_i32 s0, s3, s0
	s_ashr_i32 s0, s0, 4
	s_lshl_b32 s7, s0, 11
	v_subrev_u32_e32 v30, s7, v139
	s_lshl_b32 s16, s0, 6
	v_ashrrev_i32_e32 v31, 31, v30
	s_ashr_i32 s17, s16, 31
	v_lshl_add_u64 v[128:129], v[30:31], 2, s[14:15]
	s_lshl_b64 s[0:1], s[16:17], 13
	v_lshl_add_u64 v[2:3], v[128:129], 0, s[0:1]
	s_or_b32 s0, s16, 1
	s_ashr_i32 s1, s0, 31
	s_lshl_b64 s[0:1], s[0:1], 13
	v_lshl_add_u64 v[4:5], v[128:129], 0, s[0:1]
	s_or_b32 s0, s16, 2
	s_ashr_i32 s1, s0, 31
	s_lshl_b64 s[0:1], s[0:1], 13
	v_lshl_add_u64 v[8:9], v[128:129], 0, s[0:1]
	s_or_b32 s0, s16, 3
	s_ashr_i32 s1, s0, 31
	s_lshl_b64 s[0:1], s[0:1], 13
	v_lshl_add_u64 v[10:11], v[128:129], 0, s[0:1]
	s_or_b32 s0, s16, 4
	s_ashr_i32 s1, s0, 31
	s_lshl_b64 s[0:1], s[0:1], 13
	global_load_dwordx2 v[2:3], v[2:3], off nt
	s_nop 0
	global_load_dwordx2 v[6:7], v[4:5], off nt
	s_nop 0
	global_load_dwordx2 v[4:5], v[8:9], off nt
	s_nop 0
	global_load_dwordx2 v[8:9], v[10:11], off nt
	v_lshl_add_u64 v[10:11], v[128:129], 0, s[0:1]
	s_or_b32 s0, s16, 5
	s_ashr_i32 s1, s0, 31
	s_lshl_b64 s[0:1], s[0:1], 13
	v_lshl_add_u64 v[12:13], v[128:129], 0, s[0:1]
	s_or_b32 s0, s16, 6
	s_ashr_i32 s1, s0, 31
	s_lshl_b64 s[0:1], s[0:1], 13
	v_lshl_add_u64 v[20:21], v[128:129], 0, s[0:1]
	s_or_b32 s0, s16, 7
	s_ashr_i32 s1, s0, 31
	s_lshl_b64 s[0:1], s[0:1], 13
	v_lshl_add_u64 v[22:23], v[128:129], 0, s[0:1]
	s_or_b32 s0, s16, 8
	s_ashr_i32 s1, s0, 31
	s_lshl_b64 s[0:1], s[0:1], 13
	global_load_dwordx2 v[10:11], v[10:11], off nt
	s_nop 0
	global_load_dwordx2 v[18:19], v[12:13], off nt
	s_nop 0
	global_load_dwordx2 v[12:13], v[20:21], off nt
	s_nop 0
	global_load_dwordx2 v[20:21], v[22:23], off nt
	v_lshl_add_u64 v[22:23], v[128:129], 0, s[0:1]
	s_or_b32 s0, s16, 9
	s_ashr_i32 s1, s0, 31
	s_lshl_b64 s[0:1], s[0:1], 13
	v_lshl_add_u64 v[24:25], v[128:129], 0, s[0:1]
	s_or_b32 s0, s16, 10
	s_ashr_i32 s1, s0, 31
	s_lshl_b64 s[0:1], s[0:1], 13
	v_lshl_add_u64 v[28:29], v[128:129], 0, s[0:1]
	s_or_b32 s0, s16, 11
	s_ashr_i32 s1, s0, 31
	s_lshl_b64 s[0:1], s[0:1], 13
	v_lshl_add_u64 v[32:33], v[128:129], 0, s[0:1]
	s_or_b32 s0, s16, 12
	s_ashr_i32 s1, s0, 31
	s_lshl_b64 s[0:1], s[0:1], 13
	global_load_dwordx2 v[22:23], v[22:23], off nt
	s_nop 0
	global_load_dwordx2 v[26:27], v[24:25], off nt
	s_nop 0
	global_load_dwordx2 v[24:25], v[28:29], off nt
	s_nop 0
	global_load_dwordx2 v[28:29], v[32:33], off nt
	v_lshl_add_u64 v[32:33], v[128:129], 0, s[0:1]
	s_or_b32 s0, s16, 13
	s_ashr_i32 s1, s0, 31
	s_lshl_b64 s[0:1], s[0:1], 13
	v_lshl_add_u64 v[34:35], v[128:129], 0, s[0:1]
	s_or_b32 s0, s16, 14
	s_ashr_i32 s1, s0, 31
	s_lshl_b64 s[0:1], s[0:1], 13
	v_lshl_add_u64 v[38:39], v[128:129], 0, s[0:1]
	s_or_b32 s0, s16, 15
	s_ashr_i32 s1, s0, 31
	s_lshl_b64 s[0:1], s[0:1], 13
	v_lshl_add_u64 v[40:41], v[128:129], 0, s[0:1]
	s_or_b32 s0, s16, 16
	s_ashr_i32 s1, s0, 31
	s_lshl_b64 s[0:1], s[0:1], 13
	global_load_dwordx2 v[32:33], v[32:33], off nt
	s_nop 0
	global_load_dwordx2 v[36:37], v[34:35], off nt
	s_nop 0
	global_load_dwordx2 v[34:35], v[38:39], off nt
	s_nop 0
	global_load_dwordx2 v[38:39], v[40:41], off nt
	v_lshl_add_u64 v[40:41], v[128:129], 0, s[0:1]
	s_or_b32 s0, s16, 17
	s_ashr_i32 s1, s0, 31
	s_lshl_b64 s[0:1], s[0:1], 13
	v_lshl_add_u64 v[42:43], v[128:129], 0, s[0:1]
	s_or_b32 s0, s16, 18
	s_ashr_i32 s1, s0, 31
	s_lshl_b64 s[0:1], s[0:1], 13
	v_lshl_add_u64 v[46:47], v[128:129], 0, s[0:1]
	s_or_b32 s0, s16, 19
	s_ashr_i32 s1, s0, 31
	s_lshl_b64 s[0:1], s[0:1], 13
	v_lshl_add_u64 v[48:49], v[128:129], 0, s[0:1]
	s_or_b32 s0, s16, 20
	s_ashr_i32 s1, s0, 31
	s_lshl_b64 s[0:1], s[0:1], 13
	global_load_dwordx2 v[40:41], v[40:41], off nt
	s_nop 0
	global_load_dwordx2 v[44:45], v[42:43], off nt
	s_nop 0
	global_load_dwordx2 v[42:43], v[46:47], off nt
	s_nop 0
	global_load_dwordx2 v[46:47], v[48:49], off nt
	v_lshl_add_u64 v[48:49], v[128:129], 0, s[0:1]
	s_or_b32 s0, s16, 21
	s_ashr_i32 s1, s0, 31
	s_lshl_b64 s[0:1], s[0:1], 13
	v_lshl_add_u64 v[50:51], v[128:129], 0, s[0:1]
	s_or_b32 s0, s16, 22
	s_ashr_i32 s1, s0, 31
	s_lshl_b64 s[0:1], s[0:1], 13
	v_lshl_add_u64 v[54:55], v[128:129], 0, s[0:1]
	s_or_b32 s0, s16, 23
	s_ashr_i32 s1, s0, 31
	s_lshl_b64 s[0:1], s[0:1], 13
	v_lshl_add_u64 v[56:57], v[128:129], 0, s[0:1]
	s_or_b32 s0, s16, 24
	s_ashr_i32 s1, s0, 31
	s_lshl_b64 s[0:1], s[0:1], 13
	global_load_dwordx2 v[48:49], v[48:49], off nt
	s_nop 0
	global_load_dwordx2 v[52:53], v[50:51], off nt
	s_nop 0
	global_load_dwordx2 v[50:51], v[54:55], off nt
	s_nop 0
	global_load_dwordx2 v[54:55], v[56:57], off nt
	v_lshl_add_u64 v[56:57], v[128:129], 0, s[0:1]
	s_or_b32 s0, s16, 25
	s_ashr_i32 s1, s0, 31
	s_lshl_b64 s[0:1], s[0:1], 13
	v_lshl_add_u64 v[58:59], v[128:129], 0, s[0:1]
	s_or_b32 s0, s16, 26
	s_ashr_i32 s1, s0, 31
	s_lshl_b64 s[0:1], s[0:1], 13
	v_lshl_add_u64 v[62:63], v[128:129], 0, s[0:1]
	s_or_b32 s0, s16, 27
	s_ashr_i32 s1, s0, 31
	s_lshl_b64 s[0:1], s[0:1], 13
	v_lshl_add_u64 v[64:65], v[128:129], 0, s[0:1]
	s_or_b32 s0, s16, 28
	s_ashr_i32 s1, s0, 31
	s_lshl_b64 s[0:1], s[0:1], 13
	global_load_dwordx2 v[56:57], v[56:57], off nt
	s_nop 0
	global_load_dwordx2 v[60:61], v[58:59], off nt
	s_nop 0
	global_load_dwordx2 v[58:59], v[62:63], off nt
	s_nop 0
	global_load_dwordx2 v[62:63], v[64:65], off nt
	v_lshl_add_u64 v[64:65], v[128:129], 0, s[0:1]
	s_or_b32 s0, s16, 29
	s_ashr_i32 s1, s0, 31
	s_lshl_b64 s[0:1], s[0:1], 13
	v_lshl_add_u64 v[66:67], v[128:129], 0, s[0:1]
	s_or_b32 s0, s16, 30
	s_ashr_i32 s1, s0, 31
	s_lshl_b64 s[0:1], s[0:1], 13
	v_lshl_add_u64 v[70:71], v[128:129], 0, s[0:1]
	s_or_b32 s0, s16, 31
	s_ashr_i32 s1, s0, 31
	s_lshl_b64 s[0:1], s[0:1], 13
	v_lshl_add_u64 v[72:73], v[128:129], 0, s[0:1]
	s_or_b32 s0, s16, 32
	s_ashr_i32 s1, s0, 31
	s_lshl_b64 s[0:1], s[0:1], 13
	global_load_dwordx2 v[64:65], v[64:65], off nt
	s_nop 0
	global_load_dwordx2 v[68:69], v[66:67], off nt
	s_nop 0
	global_load_dwordx2 v[66:67], v[70:71], off nt
	s_nop 0
	global_load_dwordx2 v[70:71], v[72:73], off nt
	v_lshl_add_u64 v[72:73], v[128:129], 0, s[0:1]
	s_or_b32 s0, s16, 33
	s_ashr_i32 s1, s0, 31
	s_lshl_b64 s[0:1], s[0:1], 13
	v_lshl_add_u64 v[74:75], v[128:129], 0, s[0:1]
	s_or_b32 s0, s16, 34
	s_ashr_i32 s1, s0, 31
	s_lshl_b64 s[0:1], s[0:1], 13
	v_lshl_add_u64 v[78:79], v[128:129], 0, s[0:1]
	s_or_b32 s0, s16, 35
	s_ashr_i32 s1, s0, 31
	s_lshl_b64 s[0:1], s[0:1], 13
	v_lshl_add_u64 v[80:81], v[128:129], 0, s[0:1]
	s_or_b32 s0, s16, 36
	s_ashr_i32 s1, s0, 31
	s_lshl_b64 s[0:1], s[0:1], 13
	global_load_dwordx2 v[72:73], v[72:73], off nt
	s_nop 0
	global_load_dwordx2 v[76:77], v[74:75], off nt
	s_nop 0
	global_load_dwordx2 v[74:75], v[78:79], off nt
	s_nop 0
	global_load_dwordx2 v[78:79], v[80:81], off nt
	v_lshl_add_u64 v[80:81], v[128:129], 0, s[0:1]
	s_or_b32 s0, s16, 37
	s_ashr_i32 s1, s0, 31
	s_lshl_b64 s[0:1], s[0:1], 13
	v_lshl_add_u64 v[82:83], v[128:129], 0, s[0:1]
	s_or_b32 s0, s16, 38
	s_ashr_i32 s1, s0, 31
	s_lshl_b64 s[0:1], s[0:1], 13
	v_lshl_add_u64 v[86:87], v[128:129], 0, s[0:1]
	s_or_b32 s0, s16, 39
	s_ashr_i32 s1, s0, 31
	s_lshl_b64 s[0:1], s[0:1], 13
	v_lshl_add_u64 v[88:89], v[128:129], 0, s[0:1]
	s_or_b32 s0, s16, 40
	s_ashr_i32 s1, s0, 31
	s_lshl_b64 s[0:1], s[0:1], 13
	global_load_dwordx2 v[80:81], v[80:81], off nt
	s_nop 0
	global_load_dwordx2 v[84:85], v[82:83], off nt
	s_nop 0
	global_load_dwordx2 v[82:83], v[86:87], off nt
	s_nop 0
	global_load_dwordx2 v[86:87], v[88:89], off nt
	v_lshl_add_u64 v[88:89], v[128:129], 0, s[0:1]
	s_or_b32 s0, s16, 41
	s_ashr_i32 s1, s0, 31
	s_lshl_b64 s[0:1], s[0:1], 13
	v_lshl_add_u64 v[90:91], v[128:129], 0, s[0:1]
	s_or_b32 s0, s16, 42
	s_ashr_i32 s1, s0, 31
	s_lshl_b64 s[0:1], s[0:1], 13
	v_lshl_add_u64 v[94:95], v[128:129], 0, s[0:1]
	s_or_b32 s0, s16, 43
	s_ashr_i32 s1, s0, 31
	s_lshl_b64 s[0:1], s[0:1], 13
	v_lshl_add_u64 v[96:97], v[128:129], 0, s[0:1]
	s_or_b32 s0, s16, 44
	s_ashr_i32 s1, s0, 31
	s_lshl_b64 s[0:1], s[0:1], 13
	global_load_dwordx2 v[88:89], v[88:89], off nt
	s_nop 0
	global_load_dwordx2 v[92:93], v[90:91], off nt
	s_nop 0
	global_load_dwordx2 v[90:91], v[94:95], off nt
	s_nop 0
	global_load_dwordx2 v[94:95], v[96:97], off nt
	v_lshl_add_u64 v[96:97], v[128:129], 0, s[0:1]
	s_or_b32 s0, s16, 45
	s_ashr_i32 s1, s0, 31
	s_lshl_b64 s[0:1], s[0:1], 13
	v_lshl_add_u64 v[98:99], v[128:129], 0, s[0:1]
	s_or_b32 s0, s16, 46
	s_ashr_i32 s1, s0, 31
	s_lshl_b64 s[0:1], s[0:1], 13
	v_lshl_add_u64 v[102:103], v[128:129], 0, s[0:1]
	s_or_b32 s0, s16, 47
	s_ashr_i32 s1, s0, 31
	s_lshl_b64 s[0:1], s[0:1], 13
	v_lshl_add_u64 v[104:105], v[128:129], 0, s[0:1]
	s_or_b32 s0, s16, 48
	s_ashr_i32 s1, s0, 31
	s_lshl_b64 s[0:1], s[0:1], 13
	global_load_dwordx2 v[96:97], v[96:97], off nt
	s_nop 0
	global_load_dwordx2 v[100:101], v[98:99], off nt
	s_nop 0
	global_load_dwordx2 v[98:99], v[102:103], off nt
	s_nop 0
	global_load_dwordx2 v[102:103], v[104:105], off nt
	v_lshl_add_u64 v[104:105], v[128:129], 0, s[0:1]
	s_or_b32 s0, s16, 49
	s_ashr_i32 s1, s0, 31
	s_lshl_b64 s[0:1], s[0:1], 13
	v_lshl_add_u64 v[106:107], v[128:129], 0, s[0:1]
	s_or_b32 s0, s16, 50
	s_ashr_i32 s1, s0, 31
	s_lshl_b64 s[0:1], s[0:1], 13
	v_lshl_add_u64 v[110:111], v[128:129], 0, s[0:1]
	s_or_b32 s0, s16, 51
	s_ashr_i32 s1, s0, 31
	s_lshl_b64 s[0:1], s[0:1], 13
	v_lshl_add_u64 v[112:113], v[128:129], 0, s[0:1]
	s_or_b32 s0, s16, 52
	s_ashr_i32 s1, s0, 31
	s_lshl_b64 s[0:1], s[0:1], 13
	global_load_dwordx2 v[104:105], v[104:105], off nt
	s_nop 0
	global_load_dwordx2 v[108:109], v[106:107], off nt
	s_nop 0
	global_load_dwordx2 v[106:107], v[110:111], off nt
	s_nop 0
	global_load_dwordx2 v[110:111], v[112:113], off nt
	v_lshl_add_u64 v[112:113], v[128:129], 0, s[0:1]
	s_or_b32 s0, s16, 53
	s_ashr_i32 s1, s0, 31
	s_lshl_b64 s[0:1], s[0:1], 13
	v_lshl_add_u64 v[114:115], v[128:129], 0, s[0:1]
	s_or_b32 s0, s16, 54
	s_ashr_i32 s1, s0, 31
	s_lshl_b64 s[0:1], s[0:1], 13
	v_lshl_add_u64 v[118:119], v[128:129], 0, s[0:1]
	s_or_b32 s0, s16, 55
	s_ashr_i32 s1, s0, 31
	s_lshl_b64 s[0:1], s[0:1], 13
	v_lshl_add_u64 v[120:121], v[128:129], 0, s[0:1]
	s_or_b32 s0, s16, 56
	s_ashr_i32 s1, s0, 31
	s_lshl_b64 s[0:1], s[0:1], 13
	global_load_dwordx2 v[112:113], v[112:113], off nt
	s_nop 0
	global_load_dwordx2 v[116:117], v[114:115], off nt
	s_nop 0
	global_load_dwordx2 v[114:115], v[118:119], off nt
	s_nop 0
	global_load_dwordx2 v[118:119], v[120:121], off nt
	v_lshl_add_u64 v[120:121], v[128:129], 0, s[0:1]
	s_or_b32 s0, s16, 57
	s_ashr_i32 s1, s0, 31
	s_lshl_b64 s[0:1], s[0:1], 13
	v_lshl_add_u64 v[122:123], v[128:129], 0, s[0:1]
	s_or_b32 s0, s16, 58
	s_ashr_i32 s1, s0, 31
	s_lshl_b64 s[0:1], s[0:1], 13
	v_lshl_add_u64 v[126:127], v[128:129], 0, s[0:1]
	s_or_b32 s0, s16, 59
	s_ashr_i32 s1, s0, 31
	s_lshl_b64 s[0:1], s[0:1], 13
	v_lshl_add_u64 v[130:131], v[128:129], 0, s[0:1]
	s_or_b32 s0, s16, 60
	s_ashr_i32 s1, s0, 31
	s_lshl_b64 s[0:1], s[0:1], 13
	global_load_dwordx2 v[120:121], v[120:121], off nt
	s_nop 0
	global_load_dwordx2 v[124:125], v[122:123], off nt
	s_nop 0
	global_load_dwordx2 v[122:123], v[126:127], off nt
	s_nop 0
	global_load_dwordx2 v[126:127], v[130:131], off nt
	v_lshl_add_u64 v[130:131], v[128:129], 0, s[0:1]
	s_or_b32 s0, s16, 61
	s_ashr_i32 s1, s0, 31
	s_lshl_b64 s[0:1], s[0:1], 13
	v_lshl_add_u64 v[132:133], v[128:129], 0, s[0:1]
	s_or_b32 s0, s16, 62
	s_ashr_i32 s1, s0, 31
	s_lshl_b64 s[0:1], s[0:1], 13
	v_lshl_add_u64 v[134:135], v[128:129], 0, s[0:1]
	s_or_b32 s0, s16, 63
	s_ashr_i32 s1, s0, 31
	s_lshl_b64 s[0:1], s[0:1], 13
	v_lshl_add_u64 v[140:141], v[128:129], 0, s[0:1]
	global_load_dwordx2 v[128:129], v[130:131], off nt
	s_nop 0
	global_load_dwordx2 v[132:133], v[132:133], off nt
	s_nop 0
	global_load_dwordx2 v[130:131], v[134:135], off nt
	s_nop 0
	global_load_dwordx2 v[134:135], v[140:141], off nt
	s_andn2_b64 vcc, exec, s[34:35]
	s_cbranch_vccnz .LBB0_40
	s_lshl_b64 s[0:1], s[16:17], 2
	s_add_u32 s0, s2, s0
	s_addc_u32 s1, s33, s1
	global_load_dwordx4 v[140:143], v136, s[0:1]
	global_load_dwordx4 v[144:147], v136, s[0:1] offset:16
	global_load_dwordx4 v[150:153], v136, s[0:1] offset:32
	global_load_dwordx4 v[154:157], v136, s[0:1] offset:48
	global_load_dwordx4 v[158:161], v136, s[0:1] offset:64
	global_load_dwordx4 v[162:165], v136, s[0:1] offset:80
	global_load_dwordx4 v[166:169], v136, s[0:1] offset:96
	global_load_dwordx4 v[170:173], v136, s[0:1] offset:112
	global_load_dwordx4 v[174:177], v136, s[0:1] offset:128
	global_load_dwordx4 v[178:181], v136, s[0:1] offset:144
	global_load_dwordx4 v[182:185], v136, s[0:1] offset:160
	global_load_dwordx4 v[186:189], v136, s[0:1] offset:176
	global_load_dwordx4 v[190:193], v136, s[0:1] offset:192
	global_load_dwordx4 v[194:197], v136, s[0:1] offset:208
	global_load_dwordx4 v[198:201], v136, s[0:1] offset:224
	global_load_dwordx4 v[202:205], v136, s[0:1] offset:240
	s_waitcnt vmcnt(15)
	v_pk_mul_f32 v[2:3], v[2:3], v[140:141] op_sel_hi:[1,0]
	v_pk_mul_f32 v[6:7], v[6:7], v[140:141] op_sel:[0,1]
	v_mov_b32_e32 v140, v143
	v_pk_mul_f32 v[8:9], v[8:9], v[140:141] op_sel_hi:[1,0]
	v_pk_mul_f32 v[4:5], v[4:5], v[142:143] op_sel_hi:[1,0]
	s_waitcnt vmcnt(14)
	v_pk_mul_f32 v[10:11], v[10:11], v[144:145] op_sel_hi:[1,0]
	v_pk_mul_f32 v[18:19], v[18:19], v[144:145] op_sel:[0,1]
	v_pk_mul_f32 v[12:13], v[12:13], v[146:147] op_sel_hi:[1,0]
	v_mov_b32_e32 v142, v147
	s_waitcnt vmcnt(13)
	v_pk_mul_f32 v[22:23], v[22:23], v[150:151] op_sel_hi:[1,0]
	v_pk_mul_f32 v[26:27], v[26:27], v[150:151] op_sel:[0,1]
	v_pk_mul_f32 v[24:25], v[24:25], v[152:153] op_sel_hi:[1,0]
	v_mov_b32_e32 v144, v153
	s_waitcnt vmcnt(2)
	v_mov_b32_e32 v140, v197
	v_pk_mul_f32 v[118:119], v[118:119], v[140:141] op_sel_hi:[1,0]
	s_waitcnt vmcnt(1)
	v_mov_b32_e32 v140, v201
	v_pk_mul_f32 v[32:33], v[32:33], v[154:155] op_sel_hi:[1,0]
	v_pk_mul_f32 v[36:37], v[36:37], v[154:155] op_sel:[0,1]
	v_pk_mul_f32 v[34:35], v[34:35], v[156:157] op_sel_hi:[1,0]
	v_mov_b32_e32 v146, v157
	v_pk_mul_f32 v[40:41], v[40:41], v[158:159] op_sel_hi:[1,0]
	v_pk_mul_f32 v[44:45], v[44:45], v[158:159] op_sel:[0,1]
	v_pk_mul_f32 v[42:43], v[42:43], v[160:161] op_sel_hi:[1,0]
	v_mov_b32_e32 v150, v161
	v_pk_mul_f32 v[48:49], v[48:49], v[162:163] op_sel_hi:[1,0]
	v_pk_mul_f32 v[52:53], v[52:53], v[162:163] op_sel:[0,1]
	v_pk_mul_f32 v[50:51], v[50:51], v[164:165] op_sel_hi:[1,0]
	v_mov_b32_e32 v152, v165
	v_pk_mul_f32 v[56:57], v[56:57], v[166:167] op_sel_hi:[1,0]
	v_pk_mul_f32 v[60:61], v[60:61], v[166:167] op_sel:[0,1]
	v_mov_b32_e32 v154, v169
	v_mov_b32_e32 v156, v173
	v_mov_b32_e32 v158, v177
	v_mov_b32_e32 v160, v181
	v_mov_b32_e32 v162, v185
	v_mov_b32_e32 v164, v189
	v_mov_b32_e32 v166, v193
	v_pk_mul_f32 v[126:127], v[126:127], v[140:141] op_sel_hi:[1,0]
	s_waitcnt vmcnt(0)
	v_mov_b32_e32 v140, v205
	v_pk_mul_f32 v[58:59], v[58:59], v[168:169] op_sel_hi:[1,0]
	v_pk_mul_f32 v[64:65], v[64:65], v[170:171] op_sel_hi:[1,0]
	v_pk_mul_f32 v[68:69], v[68:69], v[170:171] op_sel:[0,1]
	v_pk_mul_f32 v[66:67], v[66:67], v[172:173] op_sel_hi:[1,0]
	v_pk_mul_f32 v[72:73], v[72:73], v[174:175] op_sel_hi:[1,0]
	v_pk_mul_f32 v[76:77], v[76:77], v[174:175] op_sel:[0,1]
	v_pk_mul_f32 v[74:75], v[74:75], v[176:177] op_sel_hi:[1,0]
	v_pk_mul_f32 v[80:81], v[80:81], v[178:179] op_sel_hi:[1,0]
	v_pk_mul_f32 v[84:85], v[84:85], v[178:179] op_sel:[0,1]
	v_pk_mul_f32 v[82:83], v[82:83], v[180:181] op_sel_hi:[1,0]
	v_pk_mul_f32 v[88:89], v[88:89], v[182:183] op_sel_hi:[1,0]
	v_pk_mul_f32 v[92:93], v[92:93], v[182:183] op_sel:[0,1]
	v_pk_mul_f32 v[90:91], v[90:91], v[184:185] op_sel_hi:[1,0]
	v_pk_mul_f32 v[96:97], v[96:97], v[186:187] op_sel_hi:[1,0]
	v_pk_mul_f32 v[100:101], v[100:101], v[186:187] op_sel:[0,1]
	v_pk_mul_f32 v[98:99], v[98:99], v[188:189] op_sel_hi:[1,0]
	v_pk_mul_f32 v[104:105], v[104:105], v[190:191] op_sel_hi:[1,0]
	v_pk_mul_f32 v[108:109], v[108:109], v[190:191] op_sel:[0,1]
	v_pk_mul_f32 v[106:107], v[106:107], v[192:193] op_sel_hi:[1,0]
	v_pk_mul_f32 v[112:113], v[112:113], v[194:195] op_sel_hi:[1,0]
	v_pk_mul_f32 v[20:21], v[20:21], v[142:143] op_sel_hi:[1,0]
	v_pk_mul_f32 v[28:29], v[28:29], v[144:145] op_sel_hi:[1,0]
	v_pk_mul_f32 v[38:39], v[38:39], v[146:147] op_sel_hi:[1,0]
	v_pk_mul_f32 v[46:47], v[46:47], v[150:151] op_sel_hi:[1,0]
	v_pk_mul_f32 v[54:55], v[54:55], v[152:153] op_sel_hi:[1,0]
	v_pk_mul_f32 v[62:63], v[62:63], v[154:155] op_sel_hi:[1,0]
	v_pk_mul_f32 v[70:71], v[70:71], v[156:157] op_sel_hi:[1,0]
	v_pk_mul_f32 v[78:79], v[78:79], v[158:159] op_sel_hi:[1,0]
	v_pk_mul_f32 v[86:87], v[86:87], v[160:161] op_sel_hi:[1,0]
	v_pk_mul_f32 v[94:95], v[94:95], v[162:163] op_sel_hi:[1,0]
	v_pk_mul_f32 v[102:103], v[102:103], v[164:165] op_sel_hi:[1,0]
	v_pk_mul_f32 v[110:111], v[110:111], v[166:167] op_sel_hi:[1,0]
	v_pk_mul_f32 v[116:117], v[116:117], v[194:195] op_sel:[0,1]
	v_pk_mul_f32 v[114:115], v[114:115], v[196:197] op_sel_hi:[1,0]
	v_pk_mul_f32 v[120:121], v[120:121], v[198:199] op_sel_hi:[1,0]
	v_pk_mul_f32 v[124:125], v[124:125], v[198:199] op_sel:[0,1]
	v_pk_mul_f32 v[122:123], v[122:123], v[200:201] op_sel_hi:[1,0]
	v_pk_mul_f32 v[128:129], v[128:129], v[202:203] op_sel_hi:[1,0]
	v_pk_mul_f32 v[132:133], v[132:133], v[202:203] op_sel:[0,1]
	v_pk_mul_f32 v[130:131], v[130:131], v[204:205] op_sel_hi:[1,0]
	v_pk_mul_f32 v[134:135], v[134:135], v[140:141] op_sel_hi:[1,0]
	s_branch .LBB0_40

.LBB0_46:
	s_ashr_i32 s0, s3, 31
	s_lshr_b32 s0, s0, 29
	s_add_i32 s0, s3, s0
	s_ashr_i32 s0, s0, 3
	s_lshl_b32 s1, s0, 10
	s_lshl_b32 s22, s0, 6
	v_subrev_u32_e32 v2, s1, v56
	s_or_b32 s78, s22, 1
	s_or_b32 s80, s22, 2
	s_or_b32 s82, s22, 3
	s_or_b32 s84, s22, 4
	s_or_b32 s54, s22, 9
	s_or_b32 s6, s22, 10
	s_or_b32 s10, s22, 11
	s_or_b32 s52, s22, 12
	s_or_b32 s14, s22, 13
	s_or_b32 s4, s22, 14
	s_or_b32 s48, s22, 15
	s_or_b32 s50, s22, 16
	s_or_b32 s20, s22, 17
	s_or_b32 s0, s22, 18
	s_or_b32 s12, s22, 19
	s_or_b32 s16, s22, 20
	s_or_b32 s18, s22, 21
	s_or_b32 s8, s22, 22
	v_readlane_b32 s86, v251, 32
	s_ashr_i32 s23, s22, 31
	s_or_b32 s56, s22, 8
	s_or_b32 s70, s22, 23
	v_ashrrev_i32_e32 v3, 31, v2
	v_readlane_b32 s87, v251, 33
	s_ashr_i32 s79, s78, 31
	s_ashr_i32 s81, s80, 31
	s_ashr_i32 s83, s82, 31
	s_ashr_i32 s85, s84, 31
	s_ashr_i32 s55, s54, 31
	s_ashr_i32 s7, s6, 31
	s_ashr_i32 s11, s10, 31
	s_ashr_i32 s53, s52, 31
	s_ashr_i32 s15, s14, 31
	s_ashr_i32 s5, s4, 31
	s_ashr_i32 s49, s48, 31
	s_ashr_i32 s51, s50, 31
	s_ashr_i32 s21, s20, 31
	s_ashr_i32 s1, s0, 31
	s_ashr_i32 s13, s12, 31
	s_ashr_i32 s17, s16, 31
	s_ashr_i32 s19, s18, 31
	s_ashr_i32 s9, s8, 31
	s_or_b32 s62, s22, 5
	s_or_b32 s60, s22, 6
	s_or_b32 s58, s22, 7
	s_or_b32 s66, s22, 24
	s_lshl_b64 s[76:77], s[22:23], 12
	v_lshl_add_u64 v[6:7], v[2:3], 2, s[86:87]
	s_lshl_b64 s[78:79], s[78:79], 12
	s_lshl_b64 s[80:81], s[80:81], 12
	s_lshl_b64 s[82:83], s[82:83], 12
	s_lshl_b64 s[84:85], s[84:85], 12
	s_ashr_i32 s57, s56, 31
	s_lshl_b64 s[54:55], s[54:55], 12
	s_lshl_b64 s[6:7], s[6:7], 12
	s_lshl_b64 s[10:11], s[10:11], 12
	s_lshl_b64 s[52:53], s[52:53], 12
	s_lshl_b64 s[14:15], s[14:15], 12
	s_lshl_b64 s[4:5], s[4:5], 12
	s_lshl_b64 s[48:49], s[48:49], 12
	s_lshl_b64 s[50:51], s[50:51], 12
	s_lshl_b64 s[20:21], s[20:21], 12
	s_lshl_b64 s[0:1], s[0:1], 12
	s_lshl_b64 s[12:13], s[12:13], 12
	s_lshl_b64 s[16:17], s[16:17], 12
	s_lshl_b64 s[18:19], s[18:19], 12
	s_lshl_b64 s[8:9], s[8:9], 12
	s_ashr_i32 s71, s70, 31
	s_or_b32 s24, s22, 25
	s_or_b32 s26, s22, 26
	s_or_b32 s28, s22, 27
	s_or_b32 s30, s22, 28
	s_or_b32 s34, s22, 29
	s_or_b32 s36, s22, 30
	s_or_b32 s38, s22, 31
	s_or_b32 s40, s22, 32
	s_or_b32 s42, s22, 33
	s_or_b32 s44, s22, 34
	s_or_b32 s64, s22, 35
	s_or_b32 s68, s22, 36
	s_or_b32 s72, s22, 37
	s_or_b32 s74, s22, 38
	v_lshl_add_u64 v[4:5], v[6:7], 0, s[76:77]
	s_or_b32 s76, s22, 39
	v_lshl_add_u64 v[8:9], v[6:7], 0, s[78:79]
	s_or_b32 s78, s22, 40
	v_lshl_add_u64 v[10:11], v[6:7], 0, s[80:81]
	s_or_b32 s80, s22, 41
	v_lshl_add_u64 v[12:13], v[6:7], 0, s[82:83]
	s_or_b32 s82, s22, 42
	v_lshl_add_u64 v[18:19], v[6:7], 0, s[84:85]
	s_or_b32 s84, s22, 43
	s_ashr_i32 s63, s62, 31
	s_or_b32 s86, s22, 44
	s_ashr_i32 s61, s60, 31
	s_or_b32 s88, s22, 45
	s_ashr_i32 s59, s58, 31
	s_or_b32 s90, s22, 46
	s_lshl_b64 s[56:57], s[56:57], 12
	s_or_b32 s92, s22, 47
	v_lshl_add_u64 v[28:29], v[6:7], 0, s[54:55]
	s_or_b32 s94, s22, 48
	v_lshl_add_u64 v[30:31], v[6:7], 0, s[6:7]
	s_or_b32 s6, s22, 49
	v_lshl_add_u64 v[32:33], v[6:7], 0, s[10:11]
	s_or_b32 s10, s22, 50
	v_lshl_add_u64 v[34:35], v[6:7], 0, s[52:53]
	s_or_b32 vcc_lo, s22, 51
	v_lshl_add_u64 v[36:37], v[6:7], 0, s[14:15]
	s_or_b32 s14, s22, 52
	v_lshl_add_u64 v[38:39], v[6:7], 0, s[4:5]
	s_or_b32 s4, s22, 53
	v_lshl_add_u64 v[40:41], v[6:7], 0, s[48:49]
	s_or_b32 s48, s22, 54
	v_lshl_add_u64 v[42:43], v[6:7], 0, s[50:51]
	s_or_b32 s50, s22, 55
	v_lshl_add_u64 v[44:45], v[6:7], 0, s[20:21]
	s_or_b32 s20, s22, 56
	v_lshl_add_u64 v[46:47], v[6:7], 0, s[0:1]
	s_or_b32 s0, s22, 57
	v_lshl_add_u64 v[48:49], v[6:7], 0, s[12:13]
	s_or_b32 s12, s22, 58
	v_lshl_add_u64 v[50:51], v[6:7], 0, s[16:17]
	s_or_b32 s16, s22, 59
	v_lshl_add_u64 v[52:53], v[6:7], 0, s[18:19]
	s_or_b32 s18, s22, 60
	v_lshl_add_u64 v[54:55], v[6:7], 0, s[8:9]
	s_or_b32 s52, s22, 61
	s_lshl_b64 s[8:9], s[70:71], 12
	s_or_b32 s54, s22, 62
	s_ashr_i32 s67, s66, 31
	v_readlane_b32 s1, v251, 18
	s_lshl_b64 s[62:63], s[62:63], 12
	s_lshl_b64 s[60:61], s[60:61], 12
	s_lshl_b64 s[58:59], s[58:59], 12
	v_lshl_add_u64 v[26:27], v[6:7], 0, s[56:57]
	v_lshl_add_u64 v[58:59], v[6:7], 0, s[8:9]
	s_lshl_b64 s[8:9], s[66:67], 12
	s_or_b32 s56, s22, 63
	v_add_u32_e32 v56, s1, v56
	s_ashr_i32 s25, s24, 31
	s_ashr_i32 s27, s26, 31
	s_ashr_i32 s29, s28, 31
	s_ashr_i32 s31, s30, 31
	s_ashr_i32 s35, s34, 31
	s_ashr_i32 s37, s36, 31
	s_ashr_i32 s39, s38, 31
	s_ashr_i32 s41, s40, 31
	s_ashr_i32 s43, s42, 31
	s_ashr_i32 s45, s44, 31
	s_ashr_i32 s65, s64, 31
	s_ashr_i32 s69, s68, 31
	s_ashr_i32 s73, s72, 31
	s_ashr_i32 s75, s74, 31
	s_ashr_i32 s77, s76, 31
	s_ashr_i32 s79, s78, 31
	s_ashr_i32 s81, s80, 31
	s_ashr_i32 s83, s82, 31
	s_ashr_i32 s85, s84, 31
	s_ashr_i32 s87, s86, 31
	s_ashr_i32 s89, s88, 31
	s_ashr_i32 s91, s90, 31
	s_ashr_i32 s93, s92, 31
	s_ashr_i32 s95, s94, 31
	s_ashr_i32 s7, s6, 31
	s_ashr_i32 s11, s10, 31
	s_ashr_i32 vcc_hi, vcc_lo, 31
	s_ashr_i32 s15, s14, 31
	s_ashr_i32 s5, s4, 31
	s_ashr_i32 s49, s48, 31
	s_ashr_i32 s51, s50, 31
	s_ashr_i32 s21, s20, 31
	s_ashr_i32 s1, s0, 31
	s_ashr_i32 s13, s12, 31
	s_ashr_i32 s17, s16, 31
	s_ashr_i32 s19, s18, 31
	s_ashr_i32 s53, s52, 31
	s_ashr_i32 s55, s54, 31
	v_lshl_add_u64 v[20:21], v[6:7], 0, s[62:63]
	v_lshl_add_u64 v[22:23], v[6:7], 0, s[60:61]
	v_lshl_add_u64 v[24:25], v[6:7], 0, s[58:59]
	v_lshl_add_u64 v[60:61], v[6:7], 0, s[8:9]
	s_ashr_i32 s57, s56, 31
	s_lshl_b64 s[8:9], s[22:23], 1
	s_lshl_b64 s[22:23], s[24:25], 12
	s_lshl_b64 s[24:25], s[26:27], 12
	s_lshl_b64 s[26:27], s[28:29], 12
	s_lshl_b64 s[28:29], s[30:31], 12
	s_lshl_b64 s[30:31], s[34:35], 12
	s_lshl_b64 s[34:35], s[36:37], 12
	s_lshl_b64 s[36:37], s[38:39], 12
	s_lshl_b64 s[38:39], s[40:41], 12
	s_lshl_b64 s[40:41], s[42:43], 12
	s_lshl_b64 s[42:43], s[44:45], 12
	s_lshl_b64 s[44:45], s[64:65], 12
	s_lshl_b64 s[58:59], s[68:69], 12
	s_lshl_b64 s[60:61], s[72:73], 12
	s_lshl_b64 s[62:63], s[74:75], 12
	s_lshl_b64 s[64:65], s[76:77], 12
	s_lshl_b64 s[66:67], s[78:79], 12
	s_lshl_b64 s[68:69], s[80:81], 12
	s_lshl_b64 s[70:71], s[82:83], 12
	s_lshl_b64 s[72:73], s[84:85], 12
	s_lshl_b64 s[74:75], s[86:87], 12
	s_lshl_b64 s[76:77], s[88:89], 12
	s_lshl_b64 s[78:79], s[90:91], 12
	s_lshl_b64 s[80:81], s[92:93], 12
	s_lshl_b64 s[82:83], s[94:95], 12
	s_lshl_b64 s[6:7], s[6:7], 12
	s_lshl_b64 s[10:11], s[10:11], 12
	s_lshl_b64 s[84:85], vcc, 12
	s_lshl_b64 s[14:15], s[14:15], 12
	s_lshl_b64 s[4:5], s[4:5], 12
	s_lshl_b64 s[48:49], s[48:49], 12
	s_lshl_b64 s[50:51], s[50:51], 12
	s_lshl_b64 s[20:21], s[20:21], 12
	s_lshl_b64 s[0:1], s[0:1], 12
	s_lshl_b64 s[12:13], s[12:13], 12
	s_lshl_b64 s[16:17], s[16:17], 12
	s_lshl_b64 s[18:19], s[18:19], 12
	s_lshl_b64 s[52:53], s[52:53], 12
	s_lshl_b64 s[54:55], s[54:55], 12
	s_lshl_b64 s[56:57], s[56:57], 12
	v_lshl_add_u64 v[64:65], v[6:7], 0, s[22:23]
	v_lshl_add_u64 v[66:67], v[6:7], 0, s[24:25]
	v_lshl_add_u64 v[68:69], v[6:7], 0, s[26:27]
	v_lshl_add_u64 v[70:71], v[6:7], 0, s[28:29]
	v_lshl_add_u64 v[72:73], v[6:7], 0, s[30:31]
	v_lshl_add_u64 v[74:75], v[6:7], 0, s[34:35]
	v_lshl_add_u64 v[76:77], v[6:7], 0, s[36:37]
	v_lshl_add_u64 v[78:79], v[6:7], 0, s[38:39]
	v_lshl_add_u64 v[80:81], v[6:7], 0, s[40:41]
	v_lshl_add_u64 v[82:83], v[6:7], 0, s[42:43]
	v_lshl_add_u64 v[84:85], v[6:7], 0, s[44:45]
	v_lshl_add_u64 v[86:87], v[6:7], 0, s[58:59]
	v_lshl_add_u64 v[88:89], v[6:7], 0, s[60:61]
	v_lshl_add_u64 v[90:91], v[6:7], 0, s[62:63]
	v_lshl_add_u64 v[92:93], v[6:7], 0, s[64:65]
	v_lshl_add_u64 v[94:95], v[6:7], 0, s[66:67]
	v_lshl_add_u64 v[96:97], v[6:7], 0, s[68:69]
	v_lshl_add_u64 v[98:99], v[6:7], 0, s[70:71]
	v_lshl_add_u64 v[100:101], v[6:7], 0, s[72:73]
	v_lshl_add_u64 v[102:103], v[6:7], 0, s[74:75]
	v_lshl_add_u64 v[104:105], v[6:7], 0, s[76:77]
	v_lshl_add_u64 v[106:107], v[6:7], 0, s[78:79]
	v_lshl_add_u64 v[108:109], v[6:7], 0, s[80:81]
	v_lshl_add_u64 v[110:111], v[6:7], 0, s[82:83]
	v_lshl_add_u64 v[112:113], v[6:7], 0, s[6:7]
	v_lshl_add_u64 v[114:115], v[6:7], 0, s[10:11]
	v_lshl_add_u64 v[116:117], v[6:7], 0, s[84:85]
	v_lshl_add_u64 v[118:119], v[6:7], 0, s[14:15]
	v_lshl_add_u64 v[120:121], v[6:7], 0, s[4:5]
	v_lshl_add_u64 v[122:123], v[6:7], 0, s[48:49]
	v_lshl_add_u64 v[124:125], v[6:7], 0, s[50:51]
	v_lshl_add_u64 v[126:127], v[6:7], 0, s[20:21]
	v_lshl_add_u64 v[128:129], v[6:7], 0, s[0:1]
	v_lshl_add_u64 v[130:131], v[6:7], 0, s[12:13]
	v_lshl_add_u64 v[132:133], v[6:7], 0, s[16:17]
	v_lshl_add_u64 v[134:135], v[6:7], 0, s[18:19]
	v_lshl_add_u64 v[140:141], v[6:7], 0, s[52:53]
	v_lshl_add_u64 v[142:143], v[6:7], 0, s[54:55]
	v_lshl_add_u64 v[6:7], v[6:7], 0, s[56:57]
	global_load_dwordx2 v[144:145], v[4:5], off nt
	global_load_dwordx2 v[146:147], v[8:9], off nt
	global_load_dwordx2 v[150:151], v[10:11], off nt
	global_load_dwordx2 v[152:153], v[12:13], off nt
	global_load_dwordx2 v[154:155], v[18:19], off nt
	global_load_dwordx2 v[156:157], v[20:21], off nt
	global_load_dwordx2 v[158:159], v[22:23], off nt
	global_load_dwordx2 v[160:161], v[24:25], off nt
	global_load_dwordx2 v[162:163], v[26:27], off nt
	global_load_dwordx2 v[164:165], v[28:29], off nt
	global_load_dwordx2 v[166:167], v[30:31], off nt
	global_load_dwordx2 v[168:169], v[32:33], off nt
	global_load_dwordx2 v[170:171], v[34:35], off nt
	global_load_dwordx2 v[172:173], v[36:37], off nt
	global_load_dwordx2 v[174:175], v[38:39], off nt
	global_load_dwordx2 v[176:177], v[40:41], off nt
	global_load_dwordx2 v[178:179], v[42:43], off nt
	global_load_dwordx2 v[180:181], v[44:45], off nt
	s_nop 0
	global_load_dwordx2 v[46:47], v[46:47], off nt
	s_nop 0
	global_load_dwordx2 v[48:49], v[48:49], off nt
	s_nop 0
	global_load_dwordx2 v[50:51], v[50:51], off nt
	s_nop 0
	global_load_dwordx2 v[52:53], v[52:53], off nt
	s_nop 0
	global_load_dwordx2 v[54:55], v[54:55], off nt
	s_nop 0
	global_load_dwordx2 v[58:59], v[58:59], off nt
	s_nop 0
	global_load_dwordx2 v[60:61], v[60:61], off nt
	s_nop 0
	global_load_dwordx2 v[64:65], v[64:65], off nt
	s_nop 0
	global_load_dwordx2 v[66:67], v[66:67], off nt
	s_nop 0
	global_load_dwordx2 v[68:69], v[68:69], off nt
	s_nop 0
	global_load_dwordx2 v[70:71], v[70:71], off nt
	s_nop 0
	global_load_dwordx2 v[72:73], v[72:73], off nt
	s_nop 0
	global_load_dwordx2 v[74:75], v[74:75], off nt
	s_nop 0
	global_load_dwordx2 v[76:77], v[76:77], off nt
	s_nop 0
	global_load_dwordx2 v[78:79], v[78:79], off nt
	s_nop 0
	global_load_dwordx2 v[80:81], v[80:81], off nt
	s_nop 0
	global_load_dwordx2 v[82:83], v[82:83], off nt
	s_nop 0
	global_load_dwordx2 v[84:85], v[84:85], off nt
	s_nop 0
	global_load_dwordx2 v[86:87], v[86:87], off nt
	s_nop 0
	global_load_dwordx2 v[88:89], v[88:89], off nt
	s_nop 0
	global_load_dwordx2 v[90:91], v[90:91], off nt
	s_nop 0
	global_load_dwordx2 v[92:93], v[92:93], off nt
	s_nop 0
	global_load_dwordx2 v[94:95], v[94:95], off nt
	s_nop 0
	global_load_dwordx2 v[96:97], v[96:97], off nt
	s_nop 0
	global_load_dwordx2 v[98:99], v[98:99], off nt
	s_nop 0
	global_load_dwordx2 v[100:101], v[100:101], off nt
	s_nop 0
	global_load_dwordx2 v[102:103], v[102:103], off nt
	s_nop 0
	global_load_dwordx2 v[104:105], v[104:105], off nt
	s_nop 0
	global_load_dwordx2 v[106:107], v[106:107], off nt
	s_nop 0
	global_load_dwordx2 v[108:109], v[108:109], off nt
	s_nop 0
	global_load_dwordx2 v[110:111], v[110:111], off nt
	s_nop 0
	global_load_dwordx2 v[112:113], v[112:113], off nt
	s_nop 0
	global_load_dwordx2 v[114:115], v[114:115], off nt
	s_nop 0
	global_load_dwordx2 v[116:117], v[116:117], off nt
	s_nop 0
	global_load_dwordx2 v[118:119], v[118:119], off nt
	s_nop 0
	global_load_dwordx2 v[120:121], v[120:121], off nt
	s_nop 0
	global_load_dwordx2 v[122:123], v[122:123], off nt
	s_nop 0
	global_load_dwordx2 v[124:125], v[124:125], off nt
	s_nop 0
	global_load_dwordx2 v[126:127], v[126:127], off nt
	s_nop 0
	global_load_dwordx2 v[128:129], v[128:129], off nt
	s_nop 0
	global_load_dwordx2 v[130:131], v[130:131], off nt
	s_nop 0
	global_load_dwordx2 v[132:133], v[132:133], off nt
	s_nop 0
	global_load_dwordx2 v[134:135], v[134:135], off nt
	s_nop 0
	global_load_dwordx2 v[140:141], v[140:141], off nt
	s_nop 0
	global_load_dwordx2 v[142:143], v[142:143], off nt
	s_nop 0
	global_load_dwordx2 v[182:183], v[6:7], off nt
	v_readlane_b32 s0, v251, 34
	v_add_u32_e32 v62, 1, v2
	v_readlane_b32 s40, v250, 58
	s_add_u32 s0, s0, s8
	v_readlane_b32 s1, v251, 36
	v_lshlrev_b64 v[2:3], 11, v[2:3]
	v_ashrrev_i32_e32 v63, 31, v62
	s_addc_u32 s1, s1, s9
	s_add_i32 s3, s3, s40
	v_lshlrev_b64 v[62:63], 11, v[62:63]
	v_lshl_add_u64 v[184:185], s[0:1], 0, v[2:3]
	s_cmpk_lt_i32 s3, 0x80
	v_readlane_b32 s41, v250, 59
	v_lshl_add_u64 v[186:187], s[0:1], 0, v[62:63]
	s_waitcnt vmcnt(62)
	v_cvt_pk_bf16_f32 v2, v144, v146
	v_cvt_pk_bf16_f32 v34, v145, v147
	s_waitcnt vmcnt(60)
	v_cvt_pk_bf16_f32 v3, v150, v152
	v_cvt_pk_bf16_f32 v35, v151, v153
	s_waitcnt vmcnt(58)
	v_cvt_pk_bf16_f32 v4, v154, v156
	v_cvt_pk_bf16_f32 v36, v155, v157
	s_waitcnt vmcnt(56)
	v_cvt_pk_bf16_f32 v5, v158, v160
	v_cvt_pk_bf16_f32 v37, v159, v161
	s_waitcnt vmcnt(54)
	v_cvt_pk_bf16_f32 v6, v162, v164
	v_cvt_pk_bf16_f32 v42, v163, v165
	s_waitcnt vmcnt(52)
	v_cvt_pk_bf16_f32 v7, v166, v168
	v_cvt_pk_bf16_f32 v43, v167, v169
	s_waitcnt vmcnt(50)
	v_cvt_pk_bf16_f32 v8, v170, v172
	v_cvt_pk_bf16_f32 v44, v171, v173
	s_waitcnt vmcnt(48)
	v_cvt_pk_bf16_f32 v9, v174, v176
	v_cvt_pk_bf16_f32 v45, v175, v177
	s_waitcnt vmcnt(46)
	v_cvt_pk_bf16_f32 v10, v178, v180
	s_waitcnt vmcnt(44)
	v_cvt_pk_bf16_f32 v11, v46, v48
	v_cvt_pk_bf16_f32 v46, v179, v181
	s_waitcnt vmcnt(42)
	v_cvt_pk_bf16_f32 v12, v50, v52
	v_cvt_pk_bf16_f32 v47, v47, v49
	s_waitcnt vmcnt(40)
	v_cvt_pk_bf16_f32 v13, v54, v58
	v_cvt_pk_bf16_f32 v48, v51, v53
	s_waitcnt vmcnt(38)
	v_cvt_pk_bf16_f32 v18, v60, v64
	v_cvt_pk_bf16_f32 v49, v55, v59
	s_waitcnt vmcnt(36)
	v_cvt_pk_bf16_f32 v19, v66, v68
	v_cvt_pk_bf16_f32 v50, v61, v65
	s_waitcnt vmcnt(34)
	v_cvt_pk_bf16_f32 v20, v70, v72
	v_cvt_pk_bf16_f32 v51, v67, v69
	s_waitcnt vmcnt(32)
	v_cvt_pk_bf16_f32 v21, v74, v76
	v_cvt_pk_bf16_f32 v52, v71, v73
	s_waitcnt vmcnt(30)
	v_cvt_pk_bf16_f32 v22, v78, v80
	v_cvt_pk_bf16_f32 v53, v75, v77
	s_waitcnt vmcnt(28)
	v_cvt_pk_bf16_f32 v23, v82, v84
	v_cvt_pk_bf16_f32 v58, v79, v81
	s_waitcnt vmcnt(26)
	v_cvt_pk_bf16_f32 v24, v86, v88
	v_cvt_pk_bf16_f32 v59, v83, v85
	s_waitcnt vmcnt(24)
	v_cvt_pk_bf16_f32 v25, v90, v92
	v_cvt_pk_bf16_f32 v60, v87, v89
	s_waitcnt vmcnt(22)
	v_cvt_pk_bf16_f32 v26, v94, v96
	v_cvt_pk_bf16_f32 v61, v91, v93
	s_waitcnt vmcnt(20)
	v_cvt_pk_bf16_f32 v27, v98, v100
	v_cvt_pk_bf16_f32 v62, v95, v97
	s_waitcnt vmcnt(18)
	v_cvt_pk_bf16_f32 v28, v102, v104
	v_cvt_pk_bf16_f32 v63, v99, v101
	s_waitcnt vmcnt(16)
	v_cvt_pk_bf16_f32 v29, v106, v108
	v_cvt_pk_bf16_f32 v64, v103, v105
	s_waitcnt vmcnt(14)
	v_cvt_pk_bf16_f32 v30, v110, v112
	v_cvt_pk_bf16_f32 v65, v107, v109
	s_waitcnt vmcnt(12)
	v_cvt_pk_bf16_f32 v31, v114, v116
	v_cvt_pk_bf16_f32 v66, v111, v113
	s_waitcnt vmcnt(10)
	v_cvt_pk_bf16_f32 v32, v118, v120
	v_cvt_pk_bf16_f32 v67, v115, v117
	s_waitcnt vmcnt(8)
	v_cvt_pk_bf16_f32 v33, v122, v124
	v_cvt_pk_bf16_f32 v68, v119, v121
	s_waitcnt vmcnt(6)
	v_cvt_pk_bf16_f32 v38, v126, v128
	v_cvt_pk_bf16_f32 v69, v123, v125
	s_waitcnt vmcnt(4)
	v_cvt_pk_bf16_f32 v39, v130, v132
	v_cvt_pk_bf16_f32 v70, v127, v129
	s_waitcnt vmcnt(2)
	v_cvt_pk_bf16_f32 v40, v134, v140
	v_cvt_pk_bf16_f32 v71, v131, v133
	s_waitcnt vmcnt(0)
	v_cvt_pk_bf16_f32 v41, v142, v182
	v_cvt_pk_bf16_f32 v72, v135, v141
	v_cvt_pk_bf16_f32 v73, v143, v183
	global_store_dwordx4 v[184:185], v[2:5], off
	global_store_dwordx4 v[184:185], v[6:9], off offset:16
	global_store_dwordx4 v[184:185], v[10:13], off offset:32
	global_store_dwordx4 v[184:185], v[18:21], off offset:48
	global_store_dwordx4 v[184:185], v[22:25], off offset:64
	global_store_dwordx4 v[184:185], v[26:29], off offset:80
	global_store_dwordx4 v[184:185], v[30:33], off offset:96
	global_store_dwordx4 v[184:185], v[38:41], off offset:112
	global_store_dwordx4 v[186:187], v[34:37], off
	global_store_dwordx4 v[186:187], v[42:45], off offset:16
	global_store_dwordx4 v[186:187], v[46:49], off offset:32
	global_store_dwordx4 v[186:187], v[50:53], off offset:48
	global_store_dwordx4 v[186:187], v[58:61], off offset:64
	global_store_dwordx4 v[186:187], v[62:65], off offset:80
	global_store_dwordx4 v[186:187], v[66:69], off offset:96
	global_store_dwordx4 v[186:187], v[70:73], off offset:112
	s_cbranch_scc1 .LBB0_46
	v_readlane_b32 s38, v251, 12
	v_readlane_b32 s70, v250, 56
	v_readlane_b32 s48, v250, 60
	v_readlane_b32 s76, v250, 3
	v_readlane_b32 s39, v251, 13
	v_readlane_b32 s16, v250, 38
	v_readlane_b32 s10, v251, 20
	v_readlane_b32 s34, v251, 30
	v_readlane_b32 s36, v251, 43
	v_readlane_b32 s14, v251, 41
	v_readlane_b32 s72, v250, 54
	v_readlane_b32 s71, v250, 57
	v_readlane_b32 s56, v251, 4
	v_readlane_b32 s57, v251, 5
	v_readlane_b32 s58, v251, 6
	v_readlane_b32 s59, v251, 7
	v_readlane_b32 s60, v251, 8
	v_readlane_b32 s61, v251, 9
	v_readlane_b32 s62, v251, 10
	v_readlane_b32 s63, v251, 11
	v_readlane_b32 s80, v250, 7
	v_readlane_b32 s81, v250, 8
	v_readlane_b32 s84, v250, 11
	v_readlane_b32 s85, v250, 12
	v_readlane_b32 s86, v250, 13
	v_readlane_b32 s87, v250, 14
	v_readlane_b32 s88, v250, 15
	v_readlane_b32 s89, v250, 16
	v_readlane_b32 s17, v250, 39
	v_readlane_b32 s18, v250, 40
	v_readlane_b32 s19, v250, 41
	v_readlane_b32 s26, v250, 48
	v_readlane_b32 s27, v250, 49
	v_readlane_b32 s39, v251, 14
	v_readlane_b32 s41, v251, 16
	v_readlane_b32 s11, v251, 21
	v_readlane_b32 s35, v251, 31
	v_readlane_b32 s37, v251, 44
	v_readlane_b32 s15, v251, 42
	v_readlane_b32 s73, v250, 55
	v_readlane_b32 s49, v250, 61
	v_readlane_b32 s50, v250, 62
	v_readlane_b32 s51, v250, 63
	v_readlane_b32 s52, v251, 0
	v_readlane_b32 s53, v251, 1
	v_readlane_b32 s54, v251, 2
	v_readlane_b32 s55, v251, 3
	v_readlane_b32 s77, v250, 4
	v_readlane_b32 s78, v250, 5
	v_readlane_b32 s79, v250, 6
	v_readlane_b32 s82, v250, 9
	v_readlane_b32 s83, v250, 10
	v_readlane_b32 s90, v250, 17
	v_readlane_b32 s91, v250, 18
	v_readlane_b32 s20, v250, 42
	v_readlane_b32 s21, v250, 43
	v_readlane_b32 s22, v250, 44
	v_readlane_b32 s23, v250, 45
	v_readlane_b32 s24, v250, 46
	v_readlane_b32 s25, v250, 47
	v_readlane_b32 s28, v250, 50
	v_readlane_b32 s29, v250, 51
	v_readlane_b32 s30, v250, 52
	v_readlane_b32 s31, v250, 53

.LBB0_50:
	s_ashr_i32 s3, s1, 31
	s_lshr_b32 s3, s3, 29
	s_add_i32 s3, s1, s3
	s_ashr_i32 s3, s3, 3
	s_lshl_b32 s6, s3, 10
	v_subrev_u32_e32 v2, s6, v128
	s_lshl_b32 s22, s3, 6
	v_ashrrev_i32_e32 v3, 31, v2
	s_ashr_i32 s23, s22, 31
	v_lshl_add_u64 v[4:5], v[2:3], 2, s[20:21]
	s_lshl_b64 s[6:7], s[22:23], 12
	v_lshl_add_u64 v[6:7], v[4:5], 0, s[6:7]
	s_or_b32 s6, s22, 1
	s_ashr_i32 s7, s6, 31
	s_lshl_b64 s[6:7], s[6:7], 12
	v_lshl_add_u64 v[8:9], v[4:5], 0, s[6:7]
	s_or_b32 s6, s22, 2
	s_ashr_i32 s7, s6, 31
	s_lshl_b64 s[6:7], s[6:7], 12
	v_lshl_add_u64 v[10:11], v[4:5], 0, s[6:7]
	s_or_b32 s6, s22, 3
	s_ashr_i32 s7, s6, 31
	s_lshl_b64 s[6:7], s[6:7], 12
	v_lshl_add_u64 v[12:13], v[4:5], 0, s[6:7]
	s_or_b32 s6, s22, 4
	s_ashr_i32 s7, s6, 31
	s_lshl_b64 s[6:7], s[6:7], 12
	v_lshl_add_u64 v[18:19], v[4:5], 0, s[6:7]
	s_or_b32 s6, s22, 5
	s_ashr_i32 s7, s6, 31
	s_lshl_b64 s[6:7], s[6:7], 12
	v_lshl_add_u64 v[20:21], v[4:5], 0, s[6:7]
	s_or_b32 s6, s22, 6
	s_ashr_i32 s7, s6, 31
	s_lshl_b64 s[6:7], s[6:7], 12
	v_lshl_add_u64 v[22:23], v[4:5], 0, s[6:7]
	s_or_b32 s6, s22, 7
	s_ashr_i32 s7, s6, 31
	s_lshl_b64 s[6:7], s[6:7], 12
	v_lshl_add_u64 v[24:25], v[4:5], 0, s[6:7]
	s_or_b32 s6, s22, 8
	s_ashr_i32 s7, s6, 31
	s_lshl_b64 s[6:7], s[6:7], 12
	v_lshl_add_u64 v[26:27], v[4:5], 0, s[6:7]
	s_or_b32 s6, s22, 9
	s_ashr_i32 s7, s6, 31
	s_lshl_b64 s[6:7], s[6:7], 12
	v_lshl_add_u64 v[28:29], v[4:5], 0, s[6:7]
	s_or_b32 s6, s22, 10
	s_ashr_i32 s7, s6, 31
	s_lshl_b64 s[6:7], s[6:7], 12
	v_lshl_add_u64 v[30:31], v[4:5], 0, s[6:7]
	s_or_b32 s6, s22, 11
	s_ashr_i32 s7, s6, 31
	s_lshl_b64 s[6:7], s[6:7], 12
	v_lshl_add_u64 v[32:33], v[4:5], 0, s[6:7]
	s_or_b32 s6, s22, 12
	s_ashr_i32 s7, s6, 31
	s_lshl_b64 s[6:7], s[6:7], 12
	v_lshl_add_u64 v[34:35], v[4:5], 0, s[6:7]
	s_or_b32 s6, s22, 13
	s_ashr_i32 s7, s6, 31
	s_lshl_b64 s[6:7], s[6:7], 12
	v_lshl_add_u64 v[36:37], v[4:5], 0, s[6:7]
	s_or_b32 s6, s22, 14
	s_ashr_i32 s7, s6, 31
	s_lshl_b64 s[6:7], s[6:7], 12
	v_lshl_add_u64 v[38:39], v[4:5], 0, s[6:7]
	s_or_b32 s6, s22, 15
	s_ashr_i32 s7, s6, 31
	s_or_b32 s24, s22, 16
	s_lshl_b64 s[6:7], s[6:7], 12
	s_ashr_i32 s25, s24, 31
	v_lshl_add_u64 v[40:41], v[4:5], 0, s[6:7]
	s_lshl_b64 s[6:7], s[24:25], 12
	v_lshl_add_u64 v[42:43], v[4:5], 0, s[6:7]
	s_or_b32 s6, s22, 17
	s_ashr_i32 s7, s6, 31
	s_lshl_b64 s[6:7], s[6:7], 12
	v_lshl_add_u64 v[44:45], v[4:5], 0, s[6:7]
	s_or_b32 s6, s22, 18
	s_ashr_i32 s7, s6, 31
	s_lshl_b64 s[6:7], s[6:7], 12
	v_lshl_add_u64 v[46:47], v[4:5], 0, s[6:7]
	s_or_b32 s6, s22, 19
	s_ashr_i32 s7, s6, 31
	s_lshl_b64 s[6:7], s[6:7], 12
	v_lshl_add_u64 v[48:49], v[4:5], 0, s[6:7]
	s_or_b32 s6, s22, 20
	s_ashr_i32 s7, s6, 31
	s_lshl_b64 s[6:7], s[6:7], 12
	v_lshl_add_u64 v[50:51], v[4:5], 0, s[6:7]
	s_or_b32 s6, s22, 21
	s_ashr_i32 s7, s6, 31
	s_lshl_b64 s[6:7], s[6:7], 12
	v_lshl_add_u64 v[52:53], v[4:5], 0, s[6:7]
	s_or_b32 s6, s22, 22
	s_ashr_i32 s7, s6, 31
	s_lshl_b64 s[6:7], s[6:7], 12
	v_lshl_add_u64 v[54:55], v[4:5], 0, s[6:7]
	s_or_b32 s6, s22, 23
	s_ashr_i32 s7, s6, 31
	s_lshl_b64 s[6:7], s[6:7], 12
	v_lshl_add_u64 v[56:57], v[4:5], 0, s[6:7]
	s_or_b32 s6, s22, 24
	s_ashr_i32 s7, s6, 31
	s_lshl_b64 s[6:7], s[6:7], 12
	v_lshl_add_u64 v[58:59], v[4:5], 0, s[6:7]
	s_or_b32 s6, s22, 25
	s_ashr_i32 s7, s6, 31
	s_lshl_b64 s[6:7], s[6:7], 12
	v_lshl_add_u64 v[60:61], v[4:5], 0, s[6:7]
	s_or_b32 s6, s22, 26
	s_ashr_i32 s7, s6, 31
	s_lshl_b64 s[6:7], s[6:7], 12
	v_lshl_add_u64 v[62:63], v[4:5], 0, s[6:7]
	s_or_b32 s6, s22, 27
	s_ashr_i32 s7, s6, 31
	s_lshl_b64 s[6:7], s[6:7], 12
	v_lshl_add_u64 v[64:65], v[4:5], 0, s[6:7]
	s_or_b32 s6, s22, 28
	s_ashr_i32 s7, s6, 31
	s_lshl_b64 s[6:7], s[6:7], 12
	v_lshl_add_u64 v[66:67], v[4:5], 0, s[6:7]
	s_or_b32 s6, s22, 29
	s_ashr_i32 s7, s6, 31
	s_lshl_b64 s[6:7], s[6:7], 12
	v_lshl_add_u64 v[68:69], v[4:5], 0, s[6:7]
	s_or_b32 s6, s22, 30
	s_ashr_i32 s7, s6, 31
	s_lshl_b64 s[6:7], s[6:7], 12
	v_lshl_add_u64 v[70:71], v[4:5], 0, s[6:7]
	s_or_b32 s6, s22, 31
	s_ashr_i32 s7, s6, 31
	s_or_b32 s26, s22, 32
	s_lshl_b64 s[6:7], s[6:7], 12
	s_ashr_i32 s27, s26, 31
	v_lshl_add_u64 v[72:73], v[4:5], 0, s[6:7]
	s_lshl_b64 s[6:7], s[26:27], 12
	v_lshl_add_u64 v[74:75], v[4:5], 0, s[6:7]
	s_or_b32 s6, s22, 33
	s_ashr_i32 s7, s6, 31
	s_lshl_b64 s[6:7], s[6:7], 12
	v_lshl_add_u64 v[76:77], v[4:5], 0, s[6:7]
	s_or_b32 s6, s22, 34
	s_ashr_i32 s7, s6, 31
	s_lshl_b64 s[6:7], s[6:7], 12
	v_lshl_add_u64 v[78:79], v[4:5], 0, s[6:7]
	s_or_b32 s6, s22, 35
	s_ashr_i32 s7, s6, 31
	s_lshl_b64 s[6:7], s[6:7], 12
	v_lshl_add_u64 v[80:81], v[4:5], 0, s[6:7]
	s_or_b32 s6, s22, 36
	s_ashr_i32 s7, s6, 31
	s_lshl_b64 s[6:7], s[6:7], 12
	v_lshl_add_u64 v[82:83], v[4:5], 0, s[6:7]
	s_or_b32 s6, s22, 37
	s_ashr_i32 s7, s6, 31
	s_lshl_b64 s[6:7], s[6:7], 12
	v_lshl_add_u64 v[84:85], v[4:5], 0, s[6:7]
	s_or_b32 s6, s22, 38
	s_ashr_i32 s7, s6, 31
	s_lshl_b64 s[6:7], s[6:7], 12
	v_lshl_add_u64 v[86:87], v[4:5], 0, s[6:7]
	s_or_b32 s6, s22, 39
	s_ashr_i32 s7, s6, 31
	s_lshl_b64 s[6:7], s[6:7], 12
	v_lshl_add_u64 v[88:89], v[4:5], 0, s[6:7]
	s_or_b32 s6, s22, 40
	s_ashr_i32 s7, s6, 31
	s_lshl_b64 s[6:7], s[6:7], 12
	v_lshl_add_u64 v[90:91], v[4:5], 0, s[6:7]
	s_or_b32 s6, s22, 41
	s_ashr_i32 s7, s6, 31
	s_lshl_b64 s[6:7], s[6:7], 12
	v_lshl_add_u64 v[92:93], v[4:5], 0, s[6:7]
	s_or_b32 s6, s22, 42
	s_ashr_i32 s7, s6, 31
	s_lshl_b64 s[6:7], s[6:7], 12
	v_lshl_add_u64 v[94:95], v[4:5], 0, s[6:7]
	s_or_b32 s6, s22, 43
	s_ashr_i32 s7, s6, 31
	s_lshl_b64 s[6:7], s[6:7], 12
	v_lshl_add_u64 v[96:97], v[4:5], 0, s[6:7]
	s_or_b32 s6, s22, 44
	s_ashr_i32 s7, s6, 31
	s_lshl_b64 s[6:7], s[6:7], 12
	v_lshl_add_u64 v[98:99], v[4:5], 0, s[6:7]
	s_or_b32 s6, s22, 45
	s_ashr_i32 s7, s6, 31
	s_lshl_b64 s[6:7], s[6:7], 12
	v_lshl_add_u64 v[100:101], v[4:5], 0, s[6:7]
	s_or_b32 s6, s22, 46
	s_ashr_i32 s7, s6, 31
	s_lshl_b64 s[6:7], s[6:7], 12
	v_lshl_add_u64 v[102:103], v[4:5], 0, s[6:7]
	s_or_b32 s6, s22, 47
	s_ashr_i32 s7, s6, 31
	s_lshl_b64 s[6:7], s[6:7], 12
	v_lshl_add_u64 v[104:105], v[4:5], 0, s[6:7]
	s_or_b32 s6, s22, 48
	s_ashr_i32 s7, s6, 31
	s_lshl_b64 s[12:13], s[6:7], 12
	v_lshl_add_u64 v[106:107], v[4:5], 0, s[12:13]
	s_or_b32 s12, s22, 49
	s_ashr_i32 s13, s12, 31
	s_lshl_b64 s[12:13], s[12:13], 12
	v_lshl_add_u64 v[108:109], v[4:5], 0, s[12:13]
	s_or_b32 s12, s22, 50
	s_ashr_i32 s13, s12, 31
	s_lshl_b64 s[12:13], s[12:13], 12
	v_lshl_add_u64 v[110:111], v[4:5], 0, s[12:13]
	s_or_b32 s12, s22, 51
	s_ashr_i32 s13, s12, 31
	s_lshl_b64 s[12:13], s[12:13], 12
	v_lshl_add_u64 v[112:113], v[4:5], 0, s[12:13]
	s_or_b32 s12, s22, 52
	s_ashr_i32 s13, s12, 31
	s_lshl_b64 s[12:13], s[12:13], 12
	v_lshl_add_u64 v[114:115], v[4:5], 0, s[12:13]
	s_or_b32 s12, s22, 53
	s_ashr_i32 s13, s12, 31
	s_lshl_b64 s[12:13], s[12:13], 12
	v_lshl_add_u64 v[116:117], v[4:5], 0, s[12:13]
	s_or_b32 s12, s22, 54
	s_ashr_i32 s13, s12, 31
	s_lshl_b64 s[12:13], s[12:13], 12
	v_lshl_add_u64 v[118:119], v[4:5], 0, s[12:13]
	s_or_b32 s12, s22, 55
	s_ashr_i32 s13, s12, 31
	s_lshl_b64 s[12:13], s[12:13], 12
	v_lshl_add_u64 v[120:121], v[4:5], 0, s[12:13]
	s_or_b32 s12, s22, 56
	s_ashr_i32 s13, s12, 31
	s_lshl_b64 s[12:13], s[12:13], 12
	v_lshl_add_u64 v[122:123], v[4:5], 0, s[12:13]
	s_or_b32 s12, s22, 57
	s_ashr_i32 s13, s12, 31
	s_lshl_b64 s[12:13], s[12:13], 12
	v_lshl_add_u64 v[124:125], v[4:5], 0, s[12:13]
	s_or_b32 s12, s22, 58
	s_ashr_i32 s13, s12, 31
	s_lshl_b64 s[12:13], s[12:13], 12
	v_lshl_add_u64 v[126:127], v[4:5], 0, s[12:13]
	s_or_b32 s12, s22, 59
	s_ashr_i32 s13, s12, 31
	s_lshl_b64 s[12:13], s[12:13], 12
	v_lshl_add_u64 v[130:131], v[4:5], 0, s[12:13]
	s_or_b32 s12, s22, 60
	s_ashr_i32 s13, s12, 31
	s_lshl_b64 s[12:13], s[12:13], 12
	global_load_dwordx2 v[134:135], v[130:131], off nt
	v_lshl_add_u64 v[130:131], v[4:5], 0, s[12:13]
	s_or_b32 s12, s22, 61
	s_ashr_i32 s13, s12, 31
	s_lshl_b64 s[12:13], s[12:13], 12
	global_load_dwordx2 v[154:155], v[130:131], off nt
	v_lshl_add_u64 v[130:131], v[4:5], 0, s[12:13]
	s_or_b32 s12, s22, 62
	s_ashr_i32 s13, s12, 31
	s_lshl_b64 s[12:13], s[12:13], 12
	global_load_dwordx2 v[156:157], v[130:131], off nt
	v_lshl_add_u64 v[130:131], v[4:5], 0, s[12:13]
	s_or_b32 s12, s22, 63
	s_ashr_i32 s13, s12, 31
	s_lshl_b64 s[12:13], s[12:13], 12
	v_lshl_add_u64 v[4:5], v[4:5], 0, s[12:13]
	s_lshl_b64 s[12:13], s[22:23], 2
	s_add_u32 s12, s4, s12
	s_addc_u32 s13, s5, s13
	global_load_dwordx2 v[6:7], v[6:7], off nt
	v_add_u32_e32 v128, s10, v128
	global_load_dwordx2 v[8:9], v[8:9], off nt
	s_nop 0
	global_load_dwordx2 v[10:11], v[10:11], off nt
	s_nop 0
	global_load_dwordx2 v[160:161], v[4:5], off nt
	global_load_dwordx2 v[158:159], v[130:131], off nt
	s_nop 0
	global_load_dwordx2 v[12:13], v[12:13], off nt
	s_nop 0
	global_load_dwordx2 v[18:19], v[18:19], off nt
	s_nop 0
	global_load_dwordx2 v[20:21], v[20:21], off nt
	s_nop 0
	global_load_dwordx2 v[22:23], v[22:23], off nt
	s_nop 0
	global_load_dwordx2 v[24:25], v[24:25], off nt
	s_nop 0
	global_load_dwordx2 v[26:27], v[26:27], off nt
	s_nop 0
	global_load_dwordx2 v[28:29], v[28:29], off nt
	s_nop 0
	global_load_dwordx2 v[30:31], v[30:31], off nt
	s_nop 0
	global_load_dwordx2 v[32:33], v[32:33], off nt
	s_nop 0
	global_load_dwordx2 v[34:35], v[34:35], off nt
	s_nop 0
	global_load_dwordx2 v[36:37], v[36:37], off nt
	s_nop 0
	global_load_dwordx2 v[38:39], v[38:39], off nt
	s_nop 0
	global_load_dwordx2 v[40:41], v[40:41], off nt
	s_nop 0
	global_load_dwordx2 v[42:43], v[42:43], off nt
	s_nop 0
	global_load_dwordx2 v[44:45], v[44:45], off nt
	s_nop 0
	global_load_dwordx2 v[46:47], v[46:47], off nt
	s_nop 0
	global_load_dwordx2 v[48:49], v[48:49], off nt
	s_nop 0
	global_load_dwordx2 v[50:51], v[50:51], off nt
	s_nop 0
	global_load_dwordx2 v[52:53], v[52:53], off nt
	s_nop 0
	global_load_dwordx2 v[54:55], v[54:55], off nt
	s_nop 0
	global_load_dwordx2 v[56:57], v[56:57], off nt
	s_nop 0
	global_load_dwordx2 v[58:59], v[58:59], off nt
	s_nop 0
	global_load_dwordx2 v[60:61], v[60:61], off nt
	s_nop 0
	global_load_dwordx2 v[62:63], v[62:63], off nt
	s_nop 0
	global_load_dwordx2 v[64:65], v[64:65], off nt
	s_nop 0
	global_load_dwordx2 v[66:67], v[66:67], off nt
	s_nop 0
	global_load_dwordx2 v[68:69], v[68:69], off nt
	s_nop 0
	global_load_dwordx2 v[70:71], v[70:71], off nt
	s_nop 0
	global_load_dwordx2 v[72:73], v[72:73], off nt
	s_nop 0
	global_load_dwordx2 v[74:75], v[74:75], off nt
	s_nop 0
	global_load_dwordx2 v[76:77], v[76:77], off nt
	s_nop 0
	global_load_dwordx2 v[78:79], v[78:79], off nt
	s_nop 0
	global_load_dwordx2 v[80:81], v[80:81], off nt
	s_nop 0
	global_load_dwordx2 v[82:83], v[82:83], off nt
	s_nop 0
	global_load_dwordx2 v[84:85], v[84:85], off nt
	s_nop 0
	global_load_dwordx2 v[86:87], v[86:87], off nt
	s_nop 0
	global_load_dwordx2 v[88:89], v[88:89], off nt
	s_nop 0
	global_load_dwordx2 v[90:91], v[90:91], off nt
	s_nop 0
	global_load_dwordx2 v[92:93], v[92:93], off nt
	s_nop 0
	global_load_dwordx2 v[94:95], v[94:95], off nt
	s_nop 0
	global_load_dwordx2 v[96:97], v[96:97], off nt
	s_nop 0
	global_load_dwordx2 v[98:99], v[98:99], off nt
	s_nop 0
	global_load_dwordx2 v[100:101], v[100:101], off nt
	s_nop 0
	global_load_dwordx2 v[102:103], v[102:103], off nt
	s_nop 0
	global_load_dwordx2 v[104:105], v[104:105], off nt
	s_nop 0
	global_load_dwordx2 v[106:107], v[106:107], off nt
	s_nop 0
	global_load_dwordx2 v[108:109], v[108:109], off nt
	s_nop 0
	global_load_dwordx2 v[110:111], v[110:111], off nt
	s_nop 0
	global_load_dwordx2 v[112:113], v[112:113], off nt
	s_nop 0
	global_load_dwordx2 v[114:115], v[114:115], off nt
	s_nop 0
	global_load_dwordx2 v[116:117], v[116:117], off nt
	s_nop 0
	global_load_dwordx2 v[118:119], v[118:119], off nt
	s_nop 0
	global_load_dwordx2 v[120:121], v[120:121], off nt
	s_nop 0
	global_load_dwordx2 v[122:123], v[122:123], off nt
	s_nop 0
	global_load_dwordx2 v[124:125], v[124:125], off nt
	s_nop 0
	global_load_dwordx2 v[126:127], v[126:127], off nt
	s_nop 0
	global_load_dwordx4 v[130:133], v136, s[12:13] offset:48
	global_load_dwordx4 v[140:143], v136, s[12:13] offset:32
	global_load_dwordx4 v[144:147], v136, s[12:13] offset:16
	global_load_dwordx4 v[150:153], v136, s[12:13]
	s_lshl_b64 s[12:13], s[24:25], 2
	s_add_u32 s12, s4, s12
	s_addc_u32 s13, s5, s13
	s_waitcnt vmcnt(3)
	v_pk_mul_f32 v[34:35], v[34:35], v[130:131] op_sel_hi:[1,0]
	s_waitcnt vmcnt(2)
	v_pk_mul_f32 v[26:27], v[26:27], v[140:141] op_sel_hi:[1,0]
	s_waitcnt vmcnt(1)
	v_pk_mul_f32 v[166:167], v[22:23], v[146:147] op_sel_hi:[1,0]
	s_waitcnt vmcnt(0)
	v_mov_b32_e32 v4, v153
	v_pk_mul_f32 v[12:13], v[12:13], v[4:5] op_sel_hi:[1,0]
	v_mov_b32_e32 v4, v147
	v_pk_mul_f32 v[146:147], v[24:25], v[4:5] op_sel_hi:[1,0]
	v_mov_b32_e32 v4, v143
	v_pk_mul_f32 v[32:33], v[32:33], v[4:5] op_sel_hi:[1,0]
	v_mov_b32_e32 v4, v133
	v_pk_mul_f32 v[162:163], v[6:7], v[150:151] op_sel_hi:[1,0]
	v_pk_mul_f32 v[150:151], v[8:9], v[150:151] op_sel:[0,1]
	v_pk_mul_f32 v[164:165], v[10:11], v[152:153] op_sel_hi:[1,0]
	v_pk_mul_f32 v[152:153], v[18:19], v[144:145] op_sel_hi:[1,0]
	v_pk_mul_f32 v[144:145], v[20:21], v[144:145] op_sel:[0,1]
	v_pk_mul_f32 v[40:41], v[40:41], v[4:5] op_sel_hi:[1,0]
	global_load_dwordx4 v[4:7], v136, s[12:13] offset:48
	global_load_dwordx4 v[8:11], v136, s[12:13] offset:32
	global_load_dwordx4 v[18:21], v136, s[12:13] offset:16
	global_load_dwordx4 v[22:25], v136, s[12:13]
	s_lshl_b64 s[12:13], s[26:27], 2
	s_add_u32 s12, s4, s12
	s_addc_u32 s13, s5, s13
	s_lshl_b64 s[6:7], s[6:7], 2
	s_add_u32 s6, s4, s6
	s_addc_u32 s7, s5, s7
	v_pk_mul_f32 v[28:29], v[28:29], v[140:141] op_sel:[0,1]
	v_pk_mul_f32 v[30:31], v[30:31], v[142:143] op_sel_hi:[1,0]
	v_pk_mul_f32 v[36:37], v[36:37], v[130:131] op_sel:[0,1]
	v_pk_mul_f32 v[38:39], v[38:39], v[132:133] op_sel_hi:[1,0]
	s_waitcnt vmcnt(3)
	v_pk_mul_f32 v[66:67], v[66:67], v[4:5] op_sel_hi:[1,0]
	s_waitcnt vmcnt(2)
	v_pk_mul_f32 v[58:59], v[58:59], v[8:9] op_sel_hi:[1,0]
	s_waitcnt vmcnt(1)
	v_pk_mul_f32 v[50:51], v[50:51], v[18:19] op_sel_hi:[1,0]
	s_waitcnt vmcnt(0)
	v_pk_mul_f32 v[42:43], v[42:43], v[22:23] op_sel_hi:[1,0]
	v_pk_mul_f32 v[44:45], v[44:45], v[22:23] op_sel:[0,1]
	v_mov_b32_e32 v22, v25
	v_pk_mul_f32 v[52:53], v[52:53], v[18:19] op_sel:[0,1]
	v_mov_b32_e32 v18, v21
	v_pk_mul_f32 v[60:61], v[60:61], v[8:9] op_sel:[0,1]
	v_mov_b32_e32 v8, v11
	v_pk_mul_f32 v[68:69], v[68:69], v[4:5] op_sel:[0,1]
	v_mov_b32_e32 v4, v7
	v_pk_mul_f32 v[46:47], v[46:47], v[24:25] op_sel_hi:[1,0]
	v_pk_mul_f32 v[48:49], v[48:49], v[22:23] op_sel_hi:[1,0]
	v_pk_mul_f32 v[54:55], v[54:55], v[20:21] op_sel_hi:[1,0]
	v_pk_mul_f32 v[56:57], v[56:57], v[18:19] op_sel_hi:[1,0]
	v_pk_mul_f32 v[62:63], v[62:63], v[10:11] op_sel_hi:[1,0]
	v_pk_mul_f32 v[64:65], v[64:65], v[8:9] op_sel_hi:[1,0]
	v_pk_mul_f32 v[70:71], v[70:71], v[6:7] op_sel_hi:[1,0]
	v_pk_mul_f32 v[72:73], v[72:73], v[4:5] op_sel_hi:[1,0]
	global_load_dwordx4 v[4:7], v136, s[12:13] offset:48
	global_load_dwordx4 v[8:11], v136, s[12:13] offset:32
	global_load_dwordx4 v[18:21], v136, s[12:13] offset:16
	global_load_dwordx4 v[22:25], v136, s[12:13]
	s_waitcnt vmcnt(3)
	v_pk_mul_f32 v[98:99], v[98:99], v[4:5] op_sel_hi:[1,0]
	s_waitcnt vmcnt(2)
	v_pk_mul_f32 v[90:91], v[90:91], v[8:9] op_sel_hi:[1,0]
	s_waitcnt vmcnt(1)
	v_pk_mul_f32 v[82:83], v[82:83], v[18:19] op_sel_hi:[1,0]
	s_waitcnt vmcnt(0)
	v_pk_mul_f32 v[74:75], v[74:75], v[22:23] op_sel_hi:[1,0]
	v_pk_mul_f32 v[76:77], v[76:77], v[22:23] op_sel:[0,1]
	v_mov_b32_e32 v22, v25
	v_pk_mul_f32 v[84:85], v[84:85], v[18:19] op_sel:[0,1]
	v_mov_b32_e32 v18, v21
	v_pk_mul_f32 v[92:93], v[92:93], v[8:9] op_sel:[0,1]
	v_mov_b32_e32 v8, v11
	v_pk_mul_f32 v[100:101], v[100:101], v[4:5] op_sel:[0,1]
	v_mov_b32_e32 v4, v7
	v_pk_mul_f32 v[78:79], v[78:79], v[24:25] op_sel_hi:[1,0]
	v_pk_mul_f32 v[80:81], v[80:81], v[22:23] op_sel_hi:[1,0]
	v_pk_mul_f32 v[86:87], v[86:87], v[20:21] op_sel_hi:[1,0]
	v_pk_mul_f32 v[88:89], v[88:89], v[18:19] op_sel_hi:[1,0]
	v_pk_mul_f32 v[94:95], v[94:95], v[10:11] op_sel_hi:[1,0]
	v_pk_mul_f32 v[96:97], v[96:97], v[8:9] op_sel_hi:[1,0]
	v_pk_mul_f32 v[102:103], v[102:103], v[6:7] op_sel_hi:[1,0]
	v_pk_mul_f32 v[104:105], v[104:105], v[4:5] op_sel_hi:[1,0]
	global_load_dwordx4 v[4:7], v136, s[6:7] offset:48
	global_load_dwordx4 v[8:11], v136, s[6:7] offset:32
	global_load_dwordx4 v[18:21], v136, s[6:7] offset:16
	global_load_dwordx4 v[22:25], v136, s[6:7]
	s_lshl_b64 s[6:7], s[22:23], 1
	s_add_u32 s6, s8, s6
	s_addc_u32 s7, s9, s7
	s_add_i32 s1, s1, s40
	s_cmpk_lt_i32 s1, 0x80
	s_waitcnt vmcnt(0)
	v_pk_mul_f32 v[106:107], v[106:107], v[22:23] op_sel_hi:[1,0]
	v_pk_mul_f32 v[22:23], v[108:109], v[22:23] op_sel:[0,1]
	v_pk_mul_f32 v[108:109], v[110:111], v[24:25] op_sel_hi:[1,0]
	v_mov_b32_e32 v24, v25
	v_pk_mul_f32 v[24:25], v[112:113], v[24:25] op_sel_hi:[1,0]
	v_pk_mul_f32 v[112:113], v[118:119], v[20:21] op_sel_hi:[1,0]
	v_mov_b32_e32 v20, v21
	v_pk_mul_f32 v[20:21], v[120:121], v[20:21] op_sel_hi:[1,0]
	v_pk_mul_f32 v[118:119], v[154:155], v[4:5] op_sel_hi:[1,0]
	v_pk_mul_f32 v[120:121], v[156:157], v[4:5] op_sel:[0,1]
	v_mov_b32_e32 v4, v7
	v_pk_mul_f32 v[110:111], v[114:115], v[18:19] op_sel_hi:[1,0]
	v_pk_mul_f32 v[114:115], v[122:123], v[8:9] op_sel_hi:[1,0]
	v_pk_mul_f32 v[8:9], v[124:125], v[8:9] op_sel:[0,1]
	v_pk_mul_f32 v[124:125], v[160:161], v[4:5] op_sel_hi:[1,0]
	v_lshlrev_b64 v[4:5], 11, v[2:3]
	v_pk_mul_f32 v[18:19], v[116:117], v[18:19] op_sel:[0,1]
	v_pk_mul_f32 v[116:117], v[126:127], v[10:11] op_sel_hi:[1,0]
	v_pk_mul_f32 v[122:123], v[158:159], v[6:7] op_sel_hi:[1,0]
	v_lshl_add_u64 v[126:127], s[6:7], 0, v[4:5]
	v_cvt_pk_bf16_f32 v4, v162, v150
	v_cvt_pk_bf16_f32 v5, v164, v12
	v_cvt_pk_bf16_f32 v6, v152, v144
	v_cvt_pk_bf16_f32 v7, v166, v146
	global_store_dwordx4 v[126:127], v[4:7], off
	v_mov_b32_e32 v10, v11
	v_add_u32_e32 v2, 1, v2
	v_cvt_pk_bf16_f32 v4, v26, v28
	v_cvt_pk_bf16_f32 v5, v30, v32
	v_cvt_pk_bf16_f32 v6, v34, v36
	v_cvt_pk_bf16_f32 v7, v38, v40
	global_store_dwordx4 v[126:127], v[4:7], off offset:16
	v_pk_mul_f32 v[10:11], v[134:135], v[10:11] op_sel_hi:[1,0]
	v_ashrrev_i32_e32 v3, 31, v2
	v_cvt_pk_bf16_f32 v4, v42, v44
	v_cvt_pk_bf16_f32 v5, v46, v48
	v_cvt_pk_bf16_f32 v6, v50, v52
	v_cvt_pk_bf16_f32 v7, v54, v56
	global_store_dwordx4 v[126:127], v[4:7], off offset:32
	v_lshlrev_b64 v[2:3], 11, v[2:3]
	s_nop 0
	v_cvt_pk_bf16_f32 v4, v58, v60
	v_cvt_pk_bf16_f32 v5, v62, v64
	v_cvt_pk_bf16_f32 v6, v66, v68
	v_cvt_pk_bf16_f32 v7, v70, v72
	global_store_dwordx4 v[126:127], v[4:7], off offset:48
	s_nop 1
	v_cvt_pk_bf16_f32 v4, v74, v76
	v_cvt_pk_bf16_f32 v5, v78, v80
	v_cvt_pk_bf16_f32 v6, v82, v84
	v_cvt_pk_bf16_f32 v7, v86, v88
	global_store_dwordx4 v[126:127], v[4:7], off offset:64
	s_nop 1
	v_cvt_pk_bf16_f32 v4, v90, v92
	v_cvt_pk_bf16_f32 v5, v94, v96
	v_cvt_pk_bf16_f32 v6, v98, v100
	v_cvt_pk_bf16_f32 v7, v102, v104
	global_store_dwordx4 v[126:127], v[4:7], off offset:80
	s_nop 1
	v_cvt_pk_bf16_f32 v4, v106, v22
	v_cvt_pk_bf16_f32 v5, v108, v24
	v_cvt_pk_bf16_f32 v6, v110, v18
	v_cvt_pk_bf16_f32 v7, v112, v20
	global_store_dwordx4 v[126:127], v[4:7], off offset:96
	s_nop 1
	v_cvt_pk_bf16_f32 v4, v114, v8
	v_cvt_pk_bf16_f32 v5, v116, v10
	v_cvt_pk_bf16_f32 v6, v118, v120
	v_cvt_pk_bf16_f32 v7, v122, v124
	global_store_dwordx4 v[126:127], v[4:7], off offset:112
	s_nop 1
	v_lshl_add_u64 v[6:7], s[6:7], 0, v[2:3]
	v_cvt_pk_bf16_f32 v2, v163, v151
	v_cvt_pk_bf16_f32 v3, v165, v13
	v_cvt_pk_bf16_f32 v4, v153, v145
	v_cvt_pk_bf16_f32 v5, v167, v147
	global_store_dwordx4 v[6:7], v[2:5], off
	s_nop 1
	v_cvt_pk_bf16_f32 v2, v27, v29
	v_cvt_pk_bf16_f32 v3, v31, v33
	v_cvt_pk_bf16_f32 v4, v35, v37
	v_cvt_pk_bf16_f32 v5, v39, v41
	global_store_dwordx4 v[6:7], v[2:5], off offset:16
	s_nop 1
	v_cvt_pk_bf16_f32 v2, v43, v45
	v_cvt_pk_bf16_f32 v3, v47, v49
	v_cvt_pk_bf16_f32 v4, v51, v53
	v_cvt_pk_bf16_f32 v5, v55, v57
	global_store_dwordx4 v[6:7], v[2:5], off offset:32
	s_nop 1
	v_cvt_pk_bf16_f32 v2, v59, v61
	v_cvt_pk_bf16_f32 v3, v63, v65
	v_cvt_pk_bf16_f32 v4, v67, v69
	v_cvt_pk_bf16_f32 v5, v71, v73
	global_store_dwordx4 v[6:7], v[2:5], off offset:48
	s_nop 1
	v_cvt_pk_bf16_f32 v2, v75, v77
	v_cvt_pk_bf16_f32 v3, v79, v81
	v_cvt_pk_bf16_f32 v4, v83, v85
	v_cvt_pk_bf16_f32 v5, v87, v89
	global_store_dwordx4 v[6:7], v[2:5], off offset:64
	s_nop 1
	v_cvt_pk_bf16_f32 v2, v91, v93
	v_cvt_pk_bf16_f32 v3, v95, v97
	v_cvt_pk_bf16_f32 v4, v99, v101
	v_cvt_pk_bf16_f32 v5, v103, v105
	global_store_dwordx4 v[6:7], v[2:5], off offset:80
	s_nop 1
	v_cvt_pk_bf16_f32 v2, v107, v23
	v_cvt_pk_bf16_f32 v3, v109, v25
	v_cvt_pk_bf16_f32 v4, v111, v19
	v_cvt_pk_bf16_f32 v5, v113, v21
	global_store_dwordx4 v[6:7], v[2:5], off offset:96
	s_nop 1
	v_cvt_pk_bf16_f32 v2, v115, v9
	v_cvt_pk_bf16_f32 v3, v117, v11
	v_cvt_pk_bf16_f32 v4, v119, v121
	v_cvt_pk_bf16_f32 v5, v123, v125
	global_store_dwordx4 v[6:7], v[2:5], off offset:112
	s_cbranch_scc1 .LBB0_50
	v_readlane_b32 s16, v250, 38
	v_readlane_b32 s17, v250, 39
	v_readlane_b32 s18, v250, 40
	v_readlane_b32 s19, v250, 41
	v_readlane_b32 s26, v250, 48
	v_readlane_b32 s27, v250, 49
	v_readlane_b32 s20, v250, 42
	v_readlane_b32 s21, v250, 43
	v_readlane_b32 s22, v250, 44
	v_readlane_b32 s23, v250, 45
	v_readlane_b32 s24, v250, 46
	v_readlane_b32 s25, v250, 47
	v_readlane_b32 s28, v250, 50
	v_readlane_b32 s29, v250, 51
	v_readlane_b32 s30, v250, 52
	v_readlane_b32 s31, v250, 53

.LBB0_54:
	s_ashr_i32 s0, s3, 31
	s_lshr_b32 s0, s0, 29
	s_add_i32 s0, s3, s0
	s_ashr_i32 s0, s0, 3
	s_lshl_b32 s1, s0, 10
	s_lshl_b32 s14, s0, 6
	v_subrev_u32_e32 v2, s1, v56
	s_or_b32 s52, s14, 13
	v_readlane_b32 s84, v251, 32
	s_or_b32 s74, s14, 1
	s_or_b32 s76, s14, 2
	s_or_b32 s78, s14, 3
	s_or_b32 s80, s14, 4
	s_or_b32 s82, s14, 5
	s_or_b32 s56, s14, 9
	s_or_b32 s6, s14, 10
	s_or_b32 s10, s14, 11
	s_or_b32 s54, s14, 12
	s_or_b32 s4, s14, 14
	s_or_b32 s48, s14, 15
	s_or_b32 s50, s14, 16
	s_or_b32 s16, s14, 17
	s_or_b32 s0, s14, 18
	s_or_b32 s12, s14, 19
	s_or_b32 s94, s14, 20
	s_or_b32 s18, s14, 21
	s_or_b32 s8, s14, 22
	v_ashrrev_i32_e32 v3, 31, v2
	v_readlane_b32 s85, v251, 33
	s_ashr_i32 s53, s52, 31
	s_ashr_i32 s15, s14, 31
	s_or_b32 s66, s14, 23
	v_lshl_add_u64 v[6:7], v[2:3], 2, s[84:85]
	s_ashr_i32 s75, s74, 31
	s_ashr_i32 s77, s76, 31
	s_ashr_i32 s79, s78, 31
	s_ashr_i32 s81, s80, 31
	s_ashr_i32 s83, s82, 31
	s_ashr_i32 s57, s56, 31
	s_ashr_i32 s7, s6, 31
	s_ashr_i32 s11, s10, 31
	s_ashr_i32 s55, s54, 31
	s_lshl_b64 s[52:53], s[52:53], 12
	s_ashr_i32 s5, s4, 31
	s_ashr_i32 s49, s48, 31
	s_ashr_i32 s51, s50, 31
	s_ashr_i32 s17, s16, 31
	s_ashr_i32 s1, s0, 31
	s_ashr_i32 s13, s12, 31
	s_ashr_i32 s95, s94, 31
	s_ashr_i32 s19, s18, 31
	s_ashr_i32 s9, s8, 31
	s_or_b32 s62, s14, 6
	s_or_b32 s60, s14, 7
	s_or_b32 s58, s14, 8
	s_or_b32 s44, s14, 24
	s_lshl_b64 s[72:73], s[14:15], 12
	s_lshl_b64 s[74:75], s[74:75], 12
	s_lshl_b64 s[76:77], s[76:77], 12
	s_lshl_b64 s[78:79], s[78:79], 12
	s_lshl_b64 s[80:81], s[80:81], 12
	s_lshl_b64 s[82:83], s[82:83], 12
	s_lshl_b64 s[56:57], s[56:57], 12
	s_lshl_b64 s[6:7], s[6:7], 12
	s_lshl_b64 s[10:11], s[10:11], 12
	s_lshl_b64 s[54:55], s[54:55], 12
	v_lshl_add_u64 v[36:37], v[6:7], 0, s[52:53]
	s_lshl_b64 s[4:5], s[4:5], 12
	s_lshl_b64 s[48:49], s[48:49], 12
	s_lshl_b64 s[50:51], s[50:51], 12
	s_lshl_b64 s[16:17], s[16:17], 12
	s_lshl_b64 s[0:1], s[0:1], 12
	s_lshl_b64 s[12:13], s[12:13], 12
	s_lshl_b64 s[52:53], s[94:95], 12
	s_lshl_b64 s[18:19], s[18:19], 12
	s_lshl_b64 s[8:9], s[8:9], 12
	s_ashr_i32 s67, s66, 31
	s_or_b32 s20, s14, 25
	s_or_b32 s22, s14, 26
	s_or_b32 s24, s14, 27
	s_or_b32 s26, s14, 28
	s_or_b32 s28, s14, 29
	s_or_b32 s30, s14, 30
	s_or_b32 s34, s14, 31
	s_or_b32 s36, s14, 32
	s_or_b32 s38, s14, 33
	s_or_b32 s40, s14, 34
	s_or_b32 s42, s14, 35
	s_or_b32 s64, s14, 36
	s_or_b32 s68, s14, 37
	s_or_b32 s70, s14, 38
	v_lshl_add_u64 v[4:5], v[6:7], 0, s[72:73]
	s_or_b32 s72, s14, 39
	v_lshl_add_u64 v[8:9], v[6:7], 0, s[74:75]
	s_or_b32 s74, s14, 40
	v_lshl_add_u64 v[10:11], v[6:7], 0, s[76:77]
	s_or_b32 s76, s14, 41
	v_lshl_add_u64 v[12:13], v[6:7], 0, s[78:79]
	s_or_b32 s78, s14, 42
	v_lshl_add_u64 v[18:19], v[6:7], 0, s[80:81]
	s_or_b32 s80, s14, 43
	v_lshl_add_u64 v[20:21], v[6:7], 0, s[82:83]
	s_or_b32 s82, s14, 44
	s_ashr_i32 s63, s62, 31
	s_or_b32 s84, s14, 45
	s_ashr_i32 s61, s60, 31
	s_or_b32 s86, s14, 46
	s_ashr_i32 s59, s58, 31
	s_or_b32 s88, s14, 47
	v_lshl_add_u64 v[28:29], v[6:7], 0, s[56:57]
	s_or_b32 s90, s14, 48
	v_lshl_add_u64 v[30:31], v[6:7], 0, s[6:7]
	s_or_b32 s6, s14, 49
	v_lshl_add_u64 v[32:33], v[6:7], 0, s[10:11]
	s_or_b32 s10, s14, 50
	v_lshl_add_u64 v[34:35], v[6:7], 0, s[54:55]
	s_or_b32 s92, s14, 51
	s_or_b32 vcc_lo, s14, 52
	v_lshl_add_u64 v[38:39], v[6:7], 0, s[4:5]
	s_or_b32 s4, s14, 53
	v_lshl_add_u64 v[40:41], v[6:7], 0, s[48:49]
	s_or_b32 s48, s14, 54
	v_lshl_add_u64 v[42:43], v[6:7], 0, s[50:51]
	s_or_b32 s50, s14, 55
	v_lshl_add_u64 v[44:45], v[6:7], 0, s[16:17]
	s_or_b32 s16, s14, 56
	v_lshl_add_u64 v[46:47], v[6:7], 0, s[0:1]
	s_or_b32 s0, s14, 57
	v_lshl_add_u64 v[48:49], v[6:7], 0, s[12:13]
	s_or_b32 s12, s14, 58
	v_lshl_add_u64 v[50:51], v[6:7], 0, s[52:53]
	s_or_b32 s52, s14, 59
	v_lshl_add_u64 v[52:53], v[6:7], 0, s[18:19]
	s_or_b32 s18, s14, 60
	v_lshl_add_u64 v[54:55], v[6:7], 0, s[8:9]
	s_or_b32 s54, s14, 61
	s_lshl_b64 s[8:9], s[66:67], 12
	s_or_b32 s56, s14, 62
	s_ashr_i32 s45, s44, 31
	v_readlane_b32 s1, v251, 34
	s_lshl_b64 s[62:63], s[62:63], 12
	s_lshl_b64 s[60:61], s[60:61], 12
	s_lshl_b64 s[58:59], s[58:59], 12
	v_lshl_add_u64 v[58:59], v[6:7], 0, s[8:9]
	s_lshl_b64 s[8:9], s[44:45], 12
	s_or_b32 s44, s14, 63
	v_add_u32_e32 v56, s1, v56
	s_ashr_i32 s21, s20, 31
	s_ashr_i32 s23, s22, 31
	s_ashr_i32 s25, s24, 31
	s_ashr_i32 s27, s26, 31
	s_ashr_i32 s29, s28, 31
	s_ashr_i32 s31, s30, 31
	s_ashr_i32 s35, s34, 31
	s_ashr_i32 s37, s36, 31
	s_ashr_i32 s39, s38, 31
	s_ashr_i32 s41, s40, 31
	s_ashr_i32 s43, s42, 31
	s_ashr_i32 s65, s64, 31
	s_ashr_i32 s69, s68, 31
	s_ashr_i32 s71, s70, 31
	s_ashr_i32 s73, s72, 31
	s_ashr_i32 s75, s74, 31
	s_ashr_i32 s77, s76, 31
	s_ashr_i32 s79, s78, 31
	s_ashr_i32 s81, s80, 31
	s_ashr_i32 s83, s82, 31
	s_ashr_i32 s85, s84, 31
	s_ashr_i32 s87, s86, 31
	s_ashr_i32 s89, s88, 31
	s_ashr_i32 s91, s90, 31
	s_ashr_i32 s7, s6, 31
	s_ashr_i32 s11, s10, 31
	s_ashr_i32 s93, s92, 31
	s_ashr_i32 vcc_hi, vcc_lo, 31
	s_ashr_i32 s5, s4, 31
	s_ashr_i32 s49, s48, 31
	s_ashr_i32 s51, s50, 31
	s_ashr_i32 s17, s16, 31
	s_ashr_i32 s1, s0, 31
	s_ashr_i32 s13, s12, 31
	s_ashr_i32 s53, s52, 31
	s_ashr_i32 s19, s18, 31
	s_ashr_i32 s55, s54, 31
	s_ashr_i32 s57, s56, 31
	v_lshl_add_u64 v[22:23], v[6:7], 0, s[62:63]
	v_lshl_add_u64 v[24:25], v[6:7], 0, s[60:61]
	v_lshl_add_u64 v[26:27], v[6:7], 0, s[58:59]
	v_lshl_add_u64 v[60:61], v[6:7], 0, s[8:9]
	s_ashr_i32 s45, s44, 31
	s_lshl_b64 s[8:9], s[14:15], 1
	s_lshl_b64 s[14:15], s[20:21], 12
	s_lshl_b64 s[20:21], s[22:23], 12
	s_lshl_b64 s[22:23], s[24:25], 12
	s_lshl_b64 s[24:25], s[26:27], 12
	s_lshl_b64 s[26:27], s[28:29], 12
	s_lshl_b64 s[28:29], s[30:31], 12
	s_lshl_b64 s[30:31], s[34:35], 12
	s_lshl_b64 s[34:35], s[36:37], 12
	s_lshl_b64 s[36:37], s[38:39], 12
	s_lshl_b64 s[38:39], s[40:41], 12
	s_lshl_b64 s[40:41], s[42:43], 12
	s_lshl_b64 s[42:43], s[64:65], 12
	s_lshl_b64 s[58:59], s[68:69], 12
	s_lshl_b64 s[60:61], s[70:71], 12
	s_lshl_b64 s[62:63], s[72:73], 12
	s_lshl_b64 s[64:65], s[74:75], 12
	s_lshl_b64 s[66:67], s[76:77], 12
	s_lshl_b64 s[68:69], s[78:79], 12
	s_lshl_b64 s[70:71], s[80:81], 12
	s_lshl_b64 s[72:73], s[82:83], 12
	s_lshl_b64 s[74:75], s[84:85], 12
	s_lshl_b64 s[76:77], s[86:87], 12
	s_lshl_b64 s[78:79], s[88:89], 12
	s_lshl_b64 s[80:81], s[90:91], 12
	s_lshl_b64 s[6:7], s[6:7], 12
	s_lshl_b64 s[10:11], s[10:11], 12
	s_lshl_b64 s[82:83], s[92:93], 12
	s_lshl_b64 s[84:85], vcc, 12
	s_lshl_b64 s[4:5], s[4:5], 12
	s_lshl_b64 s[48:49], s[48:49], 12
	s_lshl_b64 s[50:51], s[50:51], 12
	s_lshl_b64 s[16:17], s[16:17], 12
	s_lshl_b64 s[0:1], s[0:1], 12
	s_lshl_b64 s[12:13], s[12:13], 12
	s_lshl_b64 s[52:53], s[52:53], 12
	s_lshl_b64 s[18:19], s[18:19], 12
	s_lshl_b64 s[54:55], s[54:55], 12
	s_lshl_b64 s[56:57], s[56:57], 12
	s_lshl_b64 s[44:45], s[44:45], 12
	v_lshl_add_u64 v[64:65], v[6:7], 0, s[14:15]
	v_lshl_add_u64 v[66:67], v[6:7], 0, s[20:21]
	v_lshl_add_u64 v[68:69], v[6:7], 0, s[22:23]
	v_lshl_add_u64 v[70:71], v[6:7], 0, s[24:25]
	v_lshl_add_u64 v[72:73], v[6:7], 0, s[26:27]
	v_lshl_add_u64 v[74:75], v[6:7], 0, s[28:29]
	v_lshl_add_u64 v[76:77], v[6:7], 0, s[30:31]
	v_lshl_add_u64 v[78:79], v[6:7], 0, s[34:35]
	v_lshl_add_u64 v[80:81], v[6:7], 0, s[36:37]
	v_lshl_add_u64 v[82:83], v[6:7], 0, s[38:39]
	v_lshl_add_u64 v[84:85], v[6:7], 0, s[40:41]
	v_lshl_add_u64 v[86:87], v[6:7], 0, s[42:43]
	v_lshl_add_u64 v[88:89], v[6:7], 0, s[58:59]
	v_lshl_add_u64 v[90:91], v[6:7], 0, s[60:61]
	v_lshl_add_u64 v[92:93], v[6:7], 0, s[62:63]
	v_lshl_add_u64 v[94:95], v[6:7], 0, s[64:65]
	v_lshl_add_u64 v[96:97], v[6:7], 0, s[66:67]
	v_lshl_add_u64 v[98:99], v[6:7], 0, s[68:69]
	v_lshl_add_u64 v[100:101], v[6:7], 0, s[70:71]
	v_lshl_add_u64 v[102:103], v[6:7], 0, s[72:73]
	v_lshl_add_u64 v[104:105], v[6:7], 0, s[74:75]
	v_lshl_add_u64 v[106:107], v[6:7], 0, s[76:77]
	v_lshl_add_u64 v[108:109], v[6:7], 0, s[78:79]
	v_lshl_add_u64 v[110:111], v[6:7], 0, s[80:81]
	v_lshl_add_u64 v[112:113], v[6:7], 0, s[6:7]
	v_lshl_add_u64 v[114:115], v[6:7], 0, s[10:11]
	v_lshl_add_u64 v[116:117], v[6:7], 0, s[82:83]
	v_lshl_add_u64 v[118:119], v[6:7], 0, s[84:85]
	v_lshl_add_u64 v[120:121], v[6:7], 0, s[4:5]
	v_lshl_add_u64 v[122:123], v[6:7], 0, s[48:49]
	v_lshl_add_u64 v[124:125], v[6:7], 0, s[50:51]
	v_lshl_add_u64 v[126:127], v[6:7], 0, s[16:17]
	v_lshl_add_u64 v[128:129], v[6:7], 0, s[0:1]
	v_lshl_add_u64 v[130:131], v[6:7], 0, s[12:13]
	v_lshl_add_u64 v[132:133], v[6:7], 0, s[52:53]
	v_lshl_add_u64 v[134:135], v[6:7], 0, s[18:19]
	v_lshl_add_u64 v[140:141], v[6:7], 0, s[54:55]
	v_lshl_add_u64 v[142:143], v[6:7], 0, s[56:57]
	v_lshl_add_u64 v[6:7], v[6:7], 0, s[44:45]
	global_load_dwordx2 v[144:145], v[4:5], off nt
	global_load_dwordx2 v[146:147], v[8:9], off nt
	global_load_dwordx2 v[150:151], v[10:11], off nt
	global_load_dwordx2 v[152:153], v[12:13], off nt
	global_load_dwordx2 v[154:155], v[18:19], off nt
	global_load_dwordx2 v[156:157], v[20:21], off nt
	global_load_dwordx2 v[158:159], v[22:23], off nt
	global_load_dwordx2 v[160:161], v[24:25], off nt
	global_load_dwordx2 v[162:163], v[26:27], off nt
	global_load_dwordx2 v[164:165], v[28:29], off nt
	global_load_dwordx2 v[166:167], v[30:31], off nt
	global_load_dwordx2 v[168:169], v[32:33], off nt
	global_load_dwordx2 v[170:171], v[34:35], off nt
	global_load_dwordx2 v[172:173], v[36:37], off nt
	global_load_dwordx2 v[174:175], v[38:39], off nt
	global_load_dwordx2 v[176:177], v[40:41], off nt
	global_load_dwordx2 v[178:179], v[42:43], off nt
	global_load_dwordx2 v[180:181], v[44:45], off nt
	s_nop 0
	global_load_dwordx2 v[46:47], v[46:47], off nt
	s_nop 0
	global_load_dwordx2 v[48:49], v[48:49], off nt
	s_nop 0
	global_load_dwordx2 v[50:51], v[50:51], off nt
	s_nop 0
	global_load_dwordx2 v[52:53], v[52:53], off nt
	s_nop 0
	global_load_dwordx2 v[54:55], v[54:55], off nt
	s_nop 0
	global_load_dwordx2 v[58:59], v[58:59], off nt
	s_nop 0
	global_load_dwordx2 v[60:61], v[60:61], off nt
	s_nop 0
	global_load_dwordx2 v[64:65], v[64:65], off nt
	s_nop 0
	global_load_dwordx2 v[66:67], v[66:67], off nt
	s_nop 0
	global_load_dwordx2 v[68:69], v[68:69], off nt
	s_nop 0
	global_load_dwordx2 v[70:71], v[70:71], off nt
	s_nop 0
	global_load_dwordx2 v[72:73], v[72:73], off nt
	s_nop 0
	global_load_dwordx2 v[74:75], v[74:75], off nt
	s_nop 0
	global_load_dwordx2 v[76:77], v[76:77], off nt
	s_nop 0
	global_load_dwordx2 v[78:79], v[78:79], off nt
	s_nop 0
	global_load_dwordx2 v[80:81], v[80:81], off nt
	s_nop 0
	global_load_dwordx2 v[82:83], v[82:83], off nt
	s_nop 0
	global_load_dwordx2 v[84:85], v[84:85], off nt
	s_nop 0
	global_load_dwordx2 v[86:87], v[86:87], off nt
	s_nop 0
	global_load_dwordx2 v[88:89], v[88:89], off nt
	s_nop 0
	global_load_dwordx2 v[90:91], v[90:91], off nt
	s_nop 0
	global_load_dwordx2 v[92:93], v[92:93], off nt
	s_nop 0
	global_load_dwordx2 v[94:95], v[94:95], off nt
	s_nop 0
	global_load_dwordx2 v[96:97], v[96:97], off nt
	s_nop 0
	global_load_dwordx2 v[98:99], v[98:99], off nt
	s_nop 0
	global_load_dwordx2 v[100:101], v[100:101], off nt
	s_nop 0
	global_load_dwordx2 v[102:103], v[102:103], off nt
	s_nop 0
	global_load_dwordx2 v[104:105], v[104:105], off nt
	s_nop 0
	global_load_dwordx2 v[106:107], v[106:107], off nt
	s_nop 0
	global_load_dwordx2 v[108:109], v[108:109], off nt
	s_nop 0
	global_load_dwordx2 v[110:111], v[110:111], off nt
	s_nop 0
	global_load_dwordx2 v[112:113], v[112:113], off nt
	s_nop 0
	global_load_dwordx2 v[114:115], v[114:115], off nt
	s_nop 0
	global_load_dwordx2 v[116:117], v[116:117], off nt
	s_nop 0
	global_load_dwordx2 v[118:119], v[118:119], off nt
	s_nop 0
	global_load_dwordx2 v[120:121], v[120:121], off nt
	s_nop 0
	global_load_dwordx2 v[122:123], v[122:123], off nt
	s_nop 0
	global_load_dwordx2 v[124:125], v[124:125], off nt
	s_nop 0
	global_load_dwordx2 v[126:127], v[126:127], off nt
	s_nop 0
	global_load_dwordx2 v[128:129], v[128:129], off nt
	s_nop 0
	global_load_dwordx2 v[130:131], v[130:131], off nt
	s_nop 0
	global_load_dwordx2 v[132:133], v[132:133], off nt
	s_nop 0
	global_load_dwordx2 v[134:135], v[134:135], off nt
	s_nop 0
	global_load_dwordx2 v[140:141], v[140:141], off nt
	s_nop 0
	global_load_dwordx2 v[142:143], v[142:143], off nt
	s_nop 0
	global_load_dwordx2 v[182:183], v[6:7], off nt
	v_add_u32_e32 v62, 1, v2
	v_readlane_b32 s40, v250, 58
	s_add_u32 s0, s33, s8
	v_lshlrev_b64 v[2:3], 11, v[2:3]
	v_ashrrev_i32_e32 v63, 31, v62
	s_addc_u32 s1, s96, s9
	s_add_i32 s3, s3, s40
	v_lshlrev_b64 v[62:63], 11, v[62:63]
	v_lshl_add_u64 v[184:185], s[0:1], 0, v[2:3]
	s_cmpk_lt_i32 s3, 0x80
	v_readlane_b32 s41, v250, 59
	v_lshl_add_u64 v[186:187], s[0:1], 0, v[62:63]
	s_waitcnt vmcnt(62)
	v_cvt_pk_bf16_f32 v2, v144, v146
	v_cvt_pk_bf16_f32 v34, v145, v147
	s_waitcnt vmcnt(60)
	v_cvt_pk_bf16_f32 v3, v150, v152
	v_cvt_pk_bf16_f32 v35, v151, v153
	s_waitcnt vmcnt(58)
	v_cvt_pk_bf16_f32 v4, v154, v156
	v_cvt_pk_bf16_f32 v36, v155, v157
	s_waitcnt vmcnt(56)
	v_cvt_pk_bf16_f32 v5, v158, v160
	v_cvt_pk_bf16_f32 v37, v159, v161
	s_waitcnt vmcnt(54)
	v_cvt_pk_bf16_f32 v6, v162, v164
	v_cvt_pk_bf16_f32 v42, v163, v165
	s_waitcnt vmcnt(52)
	v_cvt_pk_bf16_f32 v7, v166, v168
	v_cvt_pk_bf16_f32 v43, v167, v169
	s_waitcnt vmcnt(50)
	v_cvt_pk_bf16_f32 v8, v170, v172
	v_cvt_pk_bf16_f32 v44, v171, v173
	s_waitcnt vmcnt(48)
	v_cvt_pk_bf16_f32 v9, v174, v176
	v_cvt_pk_bf16_f32 v45, v175, v177
	s_waitcnt vmcnt(46)
	v_cvt_pk_bf16_f32 v10, v178, v180
	s_waitcnt vmcnt(44)
	v_cvt_pk_bf16_f32 v11, v46, v48
	v_cvt_pk_bf16_f32 v46, v179, v181
	s_waitcnt vmcnt(42)
	v_cvt_pk_bf16_f32 v12, v50, v52
	v_cvt_pk_bf16_f32 v47, v47, v49
	s_waitcnt vmcnt(40)
	v_cvt_pk_bf16_f32 v13, v54, v58
	v_cvt_pk_bf16_f32 v48, v51, v53
	s_waitcnt vmcnt(38)
	v_cvt_pk_bf16_f32 v18, v60, v64
	v_cvt_pk_bf16_f32 v49, v55, v59
	s_waitcnt vmcnt(36)
	v_cvt_pk_bf16_f32 v19, v66, v68
	v_cvt_pk_bf16_f32 v50, v61, v65
	s_waitcnt vmcnt(34)
	v_cvt_pk_bf16_f32 v20, v70, v72
	v_cvt_pk_bf16_f32 v51, v67, v69
	s_waitcnt vmcnt(32)
	v_cvt_pk_bf16_f32 v21, v74, v76
	v_cvt_pk_bf16_f32 v52, v71, v73
	s_waitcnt vmcnt(30)
	v_cvt_pk_bf16_f32 v22, v78, v80
	v_cvt_pk_bf16_f32 v53, v75, v77
	s_waitcnt vmcnt(28)
	v_cvt_pk_bf16_f32 v23, v82, v84
	v_cvt_pk_bf16_f32 v58, v79, v81
	s_waitcnt vmcnt(26)
	v_cvt_pk_bf16_f32 v24, v86, v88
	v_cvt_pk_bf16_f32 v59, v83, v85
	s_waitcnt vmcnt(24)
	v_cvt_pk_bf16_f32 v25, v90, v92
	v_cvt_pk_bf16_f32 v60, v87, v89
	s_waitcnt vmcnt(22)
	v_cvt_pk_bf16_f32 v26, v94, v96
	v_cvt_pk_bf16_f32 v61, v91, v93
	s_waitcnt vmcnt(20)
	v_cvt_pk_bf16_f32 v27, v98, v100
	v_cvt_pk_bf16_f32 v62, v95, v97
	s_waitcnt vmcnt(18)
	v_cvt_pk_bf16_f32 v28, v102, v104
	v_cvt_pk_bf16_f32 v63, v99, v101
	s_waitcnt vmcnt(16)
	v_cvt_pk_bf16_f32 v29, v106, v108
	v_cvt_pk_bf16_f32 v64, v103, v105
	s_waitcnt vmcnt(14)
	v_cvt_pk_bf16_f32 v30, v110, v112
	v_cvt_pk_bf16_f32 v65, v107, v109
	s_waitcnt vmcnt(12)
	v_cvt_pk_bf16_f32 v31, v114, v116
	v_cvt_pk_bf16_f32 v66, v111, v113
	s_waitcnt vmcnt(10)
	v_cvt_pk_bf16_f32 v32, v118, v120
	v_cvt_pk_bf16_f32 v67, v115, v117
	s_waitcnt vmcnt(8)
	v_cvt_pk_bf16_f32 v33, v122, v124
	v_cvt_pk_bf16_f32 v68, v119, v121
	s_waitcnt vmcnt(6)
	v_cvt_pk_bf16_f32 v38, v126, v128
	v_cvt_pk_bf16_f32 v69, v123, v125
	s_waitcnt vmcnt(4)
	v_cvt_pk_bf16_f32 v39, v130, v132
	v_cvt_pk_bf16_f32 v70, v127, v129
	s_waitcnt vmcnt(2)
	v_cvt_pk_bf16_f32 v40, v134, v140
	v_cvt_pk_bf16_f32 v71, v131, v133
	s_waitcnt vmcnt(0)
	v_cvt_pk_bf16_f32 v41, v142, v182
	v_cvt_pk_bf16_f32 v72, v135, v141
	v_cvt_pk_bf16_f32 v73, v143, v183
	global_store_dwordx4 v[184:185], v[2:5], off
	global_store_dwordx4 v[184:185], v[6:9], off offset:16
	global_store_dwordx4 v[184:185], v[10:13], off offset:32
	global_store_dwordx4 v[184:185], v[18:21], off offset:48
	global_store_dwordx4 v[184:185], v[22:25], off offset:64
	global_store_dwordx4 v[184:185], v[26:29], off offset:80
	global_store_dwordx4 v[184:185], v[30:33], off offset:96
	global_store_dwordx4 v[184:185], v[38:41], off offset:112
	global_store_dwordx4 v[186:187], v[34:37], off
	global_store_dwordx4 v[186:187], v[42:45], off offset:16
	global_store_dwordx4 v[186:187], v[46:49], off offset:32
	global_store_dwordx4 v[186:187], v[50:53], off offset:48
	global_store_dwordx4 v[186:187], v[58:61], off offset:64
	global_store_dwordx4 v[186:187], v[62:65], off offset:80
	global_store_dwordx4 v[186:187], v[66:69], off offset:96
	global_store_dwordx4 v[186:187], v[70:73], off offset:112
	s_cbranch_scc1 .LBB0_54
	v_readlane_b32 s38, v251, 12
	v_readlane_b32 s70, v250, 56
	v_readlane_b32 s48, v250, 60
	v_readlane_b32 s76, v250, 3
	v_readlane_b32 s39, v251, 13
	v_readlane_b32 s16, v250, 38
	v_readlane_b32 s10, v251, 20
	v_readlane_b32 s34, v251, 30
	v_readlane_b32 s72, v250, 54
	v_readlane_b32 s71, v250, 57
	v_readlane_b32 s56, v251, 4
	v_readlane_b32 s57, v251, 5
	v_readlane_b32 s58, v251, 6
	v_readlane_b32 s59, v251, 7
	v_readlane_b32 s60, v251, 8
	v_readlane_b32 s61, v251, 9
	v_readlane_b32 s62, v251, 10
	v_readlane_b32 s63, v251, 11
	v_readlane_b32 s80, v250, 7
	v_readlane_b32 s81, v250, 8
	v_readlane_b32 s84, v250, 11
	v_readlane_b32 s85, v250, 12
	v_readlane_b32 s86, v250, 13
	v_readlane_b32 s87, v250, 14
	v_readlane_b32 s88, v250, 15
	v_readlane_b32 s89, v250, 16
	v_readlane_b32 s17, v250, 39
	v_readlane_b32 s18, v250, 40
	v_readlane_b32 s19, v250, 41
	v_readlane_b32 s26, v250, 48
	v_readlane_b32 s27, v250, 49
	v_readlane_b32 s39, v251, 14
	v_readlane_b32 s41, v251, 16
	v_readlane_b32 s11, v251, 21
	v_readlane_b32 s35, v251, 31
	v_readlane_b32 s73, v250, 55
	v_readlane_b32 s49, v250, 61
	v_readlane_b32 s50, v250, 62
	v_readlane_b32 s51, v250, 63
	v_readlane_b32 s52, v251, 0
	v_readlane_b32 s53, v251, 1
	v_readlane_b32 s54, v251, 2
	v_readlane_b32 s55, v251, 3
	v_readlane_b32 s77, v250, 4
	v_readlane_b32 s78, v250, 5
	v_readlane_b32 s79, v250, 6
	v_readlane_b32 s82, v250, 9
	v_readlane_b32 s83, v250, 10
	v_readlane_b32 s90, v250, 17
	v_readlane_b32 s91, v250, 18
	v_readlane_b32 s20, v250, 42
	v_readlane_b32 s21, v250, 43
	v_readlane_b32 s22, v250, 44
	v_readlane_b32 s23, v250, 45
	v_readlane_b32 s24, v250, 46
	v_readlane_b32 s25, v250, 47
	v_readlane_b32 s28, v250, 50
	v_readlane_b32 s29, v250, 51
	v_readlane_b32 s30, v250, 52
	v_readlane_b32 s31, v250, 53
	s_branch .LBB0_37

.LBB0_59:
	s_ashr_i32 s4, s3, 31
	s_lshr_b32 s4, s4, 28
	s_add_i32 s4, s3, s4
	s_ashr_i32 s4, s4, 4
	s_lshl_b32 s5, s4, 11
	v_subrev_u32_e32 v2, s5, v17
	s_lshl_b32 s4, s4, 6
	v_ashrrev_i32_e32 v3, 31, v2
	s_ashr_i32 s5, s4, 31
	v_lshl_add_u64 v[128:129], v[2:3], 2, s[86:87]
	s_lshl_b64 s[6:7], s[4:5], 13
	v_lshl_add_u64 v[4:5], v[128:129], 0, s[6:7]
	s_or_b32 s6, s4, 1
	s_ashr_i32 s7, s6, 31
	s_lshl_b64 s[6:7], s[6:7], 13
	v_lshl_add_u64 v[6:7], v[128:129], 0, s[6:7]
	s_or_b32 s6, s4, 2
	s_ashr_i32 s7, s6, 31
	s_lshl_b64 s[6:7], s[6:7], 13
	v_lshl_add_u64 v[10:11], v[128:129], 0, s[6:7]
	s_or_b32 s6, s4, 3
	s_ashr_i32 s7, s6, 31
	s_lshl_b64 s[6:7], s[6:7], 13
	v_lshl_add_u64 v[12:13], v[128:129], 0, s[6:7]
	s_or_b32 s6, s4, 4
	s_ashr_i32 s7, s6, 31
	s_lshl_b64 s[6:7], s[6:7], 13
	global_load_dwordx2 v[4:5], v[4:5], off nt
	s_nop 0
	global_load_dwordx2 v[8:9], v[6:7], off nt
	s_nop 0
	global_load_dwordx2 v[6:7], v[10:11], off nt
	s_nop 0
	global_load_dwordx2 v[10:11], v[12:13], off nt
	v_lshl_add_u64 v[12:13], v[128:129], 0, s[6:7]
	s_or_b32 s6, s4, 5
	s_ashr_i32 s7, s6, 31
	s_lshl_b64 s[6:7], s[6:7], 13
	v_lshl_add_u64 v[18:19], v[128:129], 0, s[6:7]
	s_or_b32 s6, s4, 6
	s_ashr_i32 s7, s6, 31
	s_lshl_b64 s[6:7], s[6:7], 13
	v_lshl_add_u64 v[22:23], v[128:129], 0, s[6:7]
	s_or_b32 s6, s4, 7
	s_ashr_i32 s7, s6, 31
	s_lshl_b64 s[6:7], s[6:7], 13
	v_lshl_add_u64 v[24:25], v[128:129], 0, s[6:7]
	s_or_b32 s6, s4, 8
	s_ashr_i32 s7, s6, 31
	s_lshl_b64 s[6:7], s[6:7], 13
	global_load_dwordx2 v[12:13], v[12:13], off nt
	s_nop 0
	global_load_dwordx2 v[20:21], v[18:19], off nt
	s_nop 0
	global_load_dwordx2 v[18:19], v[22:23], off nt
	s_nop 0
	global_load_dwordx2 v[22:23], v[24:25], off nt
	v_lshl_add_u64 v[24:25], v[128:129], 0, s[6:7]
	s_or_b32 s6, s4, 9
	s_ashr_i32 s7, s6, 31
	s_lshl_b64 s[6:7], s[6:7], 13
	v_lshl_add_u64 v[26:27], v[128:129], 0, s[6:7]
	s_or_b32 s6, s4, 10
	s_ashr_i32 s7, s6, 31
	s_lshl_b64 s[6:7], s[6:7], 13
	v_lshl_add_u64 v[30:31], v[128:129], 0, s[6:7]
	s_or_b32 s6, s4, 11
	s_ashr_i32 s7, s6, 31
	s_lshl_b64 s[6:7], s[6:7], 13
	v_lshl_add_u64 v[32:33], v[128:129], 0, s[6:7]
	s_or_b32 s6, s4, 12
	s_ashr_i32 s7, s6, 31
	s_lshl_b64 s[6:7], s[6:7], 13
	global_load_dwordx2 v[24:25], v[24:25], off nt
	s_nop 0
	global_load_dwordx2 v[28:29], v[26:27], off nt
	s_nop 0
	global_load_dwordx2 v[26:27], v[30:31], off nt
	s_nop 0
	global_load_dwordx2 v[30:31], v[32:33], off nt
	v_lshl_add_u64 v[32:33], v[128:129], 0, s[6:7]
	s_or_b32 s6, s4, 13
	s_ashr_i32 s7, s6, 31
	s_lshl_b64 s[6:7], s[6:7], 13
	v_lshl_add_u64 v[34:35], v[128:129], 0, s[6:7]
	s_or_b32 s6, s4, 14
	s_ashr_i32 s7, s6, 31
	s_lshl_b64 s[6:7], s[6:7], 13
	v_lshl_add_u64 v[38:39], v[128:129], 0, s[6:7]
	s_or_b32 s6, s4, 15
	s_ashr_i32 s7, s6, 31
	s_lshl_b64 s[6:7], s[6:7], 13
	v_lshl_add_u64 v[40:41], v[128:129], 0, s[6:7]
	s_or_b32 s6, s4, 16
	s_ashr_i32 s7, s6, 31
	s_lshl_b64 s[6:7], s[6:7], 13
	global_load_dwordx2 v[32:33], v[32:33], off nt
	s_nop 0
	global_load_dwordx2 v[36:37], v[34:35], off nt
	s_nop 0
	global_load_dwordx2 v[34:35], v[38:39], off nt
	s_nop 0
	global_load_dwordx2 v[38:39], v[40:41], off nt
	v_lshl_add_u64 v[40:41], v[128:129], 0, s[6:7]
	s_or_b32 s6, s4, 17
	s_ashr_i32 s7, s6, 31
	s_lshl_b64 s[6:7], s[6:7], 13
	v_lshl_add_u64 v[42:43], v[128:129], 0, s[6:7]
	s_or_b32 s6, s4, 18
	s_ashr_i32 s7, s6, 31
	s_lshl_b64 s[6:7], s[6:7], 13
	v_lshl_add_u64 v[46:47], v[128:129], 0, s[6:7]
	s_or_b32 s6, s4, 19
	s_ashr_i32 s7, s6, 31
	s_lshl_b64 s[6:7], s[6:7], 13
	v_lshl_add_u64 v[48:49], v[128:129], 0, s[6:7]
	s_or_b32 s6, s4, 20
	s_ashr_i32 s7, s6, 31
	s_lshl_b64 s[6:7], s[6:7], 13
	global_load_dwordx2 v[40:41], v[40:41], off nt
	s_nop 0
	global_load_dwordx2 v[44:45], v[42:43], off nt
	s_nop 0
	global_load_dwordx2 v[42:43], v[46:47], off nt
	s_nop 0
	global_load_dwordx2 v[46:47], v[48:49], off nt
	v_lshl_add_u64 v[48:49], v[128:129], 0, s[6:7]
	s_or_b32 s6, s4, 21
	s_ashr_i32 s7, s6, 31
	s_lshl_b64 s[6:7], s[6:7], 13
	v_lshl_add_u64 v[50:51], v[128:129], 0, s[6:7]
	s_or_b32 s6, s4, 22
	s_ashr_i32 s7, s6, 31
	s_lshl_b64 s[6:7], s[6:7], 13
	v_lshl_add_u64 v[54:55], v[128:129], 0, s[6:7]
	s_or_b32 s6, s4, 23
	s_ashr_i32 s7, s6, 31
	s_lshl_b64 s[6:7], s[6:7], 13
	v_lshl_add_u64 v[56:57], v[128:129], 0, s[6:7]
	s_or_b32 s6, s4, 24
	s_ashr_i32 s7, s6, 31
	s_lshl_b64 s[6:7], s[6:7], 13
	global_load_dwordx2 v[48:49], v[48:49], off nt
	s_nop 0
	global_load_dwordx2 v[52:53], v[50:51], off nt
	s_nop 0
	global_load_dwordx2 v[50:51], v[54:55], off nt
	s_nop 0
	global_load_dwordx2 v[54:55], v[56:57], off nt
	v_lshl_add_u64 v[56:57], v[128:129], 0, s[6:7]
	s_or_b32 s6, s4, 25
	s_ashr_i32 s7, s6, 31
	s_lshl_b64 s[6:7], s[6:7], 13
	v_lshl_add_u64 v[58:59], v[128:129], 0, s[6:7]
	s_or_b32 s6, s4, 26
	s_ashr_i32 s7, s6, 31
	s_lshl_b64 s[6:7], s[6:7], 13
	v_lshl_add_u64 v[62:63], v[128:129], 0, s[6:7]
	s_or_b32 s6, s4, 27
	s_ashr_i32 s7, s6, 31
	s_lshl_b64 s[6:7], s[6:7], 13
	v_lshl_add_u64 v[64:65], v[128:129], 0, s[6:7]
	s_or_b32 s6, s4, 28
	s_ashr_i32 s7, s6, 31
	s_lshl_b64 s[6:7], s[6:7], 13
	global_load_dwordx2 v[56:57], v[56:57], off nt
	s_nop 0
	global_load_dwordx2 v[60:61], v[58:59], off nt
	s_nop 0
	global_load_dwordx2 v[58:59], v[62:63], off nt
	s_nop 0
	global_load_dwordx2 v[62:63], v[64:65], off nt
	v_lshl_add_u64 v[64:65], v[128:129], 0, s[6:7]
	s_or_b32 s6, s4, 29
	s_ashr_i32 s7, s6, 31
	s_lshl_b64 s[6:7], s[6:7], 13
	v_lshl_add_u64 v[66:67], v[128:129], 0, s[6:7]
	s_or_b32 s6, s4, 30
	s_ashr_i32 s7, s6, 31
	s_lshl_b64 s[6:7], s[6:7], 13
	v_lshl_add_u64 v[70:71], v[128:129], 0, s[6:7]
	s_or_b32 s6, s4, 31
	s_ashr_i32 s7, s6, 31
	s_lshl_b64 s[6:7], s[6:7], 13
	v_lshl_add_u64 v[72:73], v[128:129], 0, s[6:7]
	s_or_b32 s6, s4, 32
	s_ashr_i32 s7, s6, 31
	s_lshl_b64 s[6:7], s[6:7], 13
	global_load_dwordx2 v[64:65], v[64:65], off nt
	s_nop 0
	global_load_dwordx2 v[68:69], v[66:67], off nt
	s_nop 0
	global_load_dwordx2 v[66:67], v[70:71], off nt
	s_nop 0
	global_load_dwordx2 v[70:71], v[72:73], off nt
	v_lshl_add_u64 v[72:73], v[128:129], 0, s[6:7]
	s_or_b32 s6, s4, 33
	s_ashr_i32 s7, s6, 31
	s_lshl_b64 s[6:7], s[6:7], 13
	v_lshl_add_u64 v[74:75], v[128:129], 0, s[6:7]
	s_or_b32 s6, s4, 34
	s_ashr_i32 s7, s6, 31
	s_lshl_b64 s[6:7], s[6:7], 13
	v_lshl_add_u64 v[78:79], v[128:129], 0, s[6:7]
	s_or_b32 s6, s4, 35
	s_ashr_i32 s7, s6, 31
	s_lshl_b64 s[6:7], s[6:7], 13
	v_lshl_add_u64 v[80:81], v[128:129], 0, s[6:7]
	s_or_b32 s6, s4, 36
	s_ashr_i32 s7, s6, 31
	s_lshl_b64 s[6:7], s[6:7], 13
	global_load_dwordx2 v[72:73], v[72:73], off nt
	s_nop 0
	global_load_dwordx2 v[76:77], v[74:75], off nt
	s_nop 0
	global_load_dwordx2 v[74:75], v[78:79], off nt
	s_nop 0
	global_load_dwordx2 v[78:79], v[80:81], off nt
	v_lshl_add_u64 v[80:81], v[128:129], 0, s[6:7]
	s_or_b32 s6, s4, 37
	s_ashr_i32 s7, s6, 31
	s_lshl_b64 s[6:7], s[6:7], 13
	v_lshl_add_u64 v[82:83], v[128:129], 0, s[6:7]
	s_or_b32 s6, s4, 38
	s_ashr_i32 s7, s6, 31
	s_lshl_b64 s[6:7], s[6:7], 13
	v_lshl_add_u64 v[86:87], v[128:129], 0, s[6:7]
	s_or_b32 s6, s4, 39
	s_ashr_i32 s7, s6, 31
	s_lshl_b64 s[6:7], s[6:7], 13
	v_lshl_add_u64 v[88:89], v[128:129], 0, s[6:7]
	s_or_b32 s6, s4, 40
	s_ashr_i32 s7, s6, 31
	s_lshl_b64 s[6:7], s[6:7], 13
	global_load_dwordx2 v[80:81], v[80:81], off nt
	s_nop 0
	global_load_dwordx2 v[84:85], v[82:83], off nt
	s_nop 0
	global_load_dwordx2 v[82:83], v[86:87], off nt
	s_nop 0
	global_load_dwordx2 v[86:87], v[88:89], off nt
	v_lshl_add_u64 v[88:89], v[128:129], 0, s[6:7]
	s_or_b32 s6, s4, 41
	s_ashr_i32 s7, s6, 31
	s_lshl_b64 s[6:7], s[6:7], 13
	v_lshl_add_u64 v[90:91], v[128:129], 0, s[6:7]
	s_or_b32 s6, s4, 42
	s_ashr_i32 s7, s6, 31
	s_lshl_b64 s[6:7], s[6:7], 13
	v_lshl_add_u64 v[94:95], v[128:129], 0, s[6:7]
	s_or_b32 s6, s4, 43
	s_ashr_i32 s7, s6, 31
	s_lshl_b64 s[6:7], s[6:7], 13
	v_lshl_add_u64 v[96:97], v[128:129], 0, s[6:7]
	s_or_b32 s6, s4, 44
	s_ashr_i32 s7, s6, 31
	s_lshl_b64 s[6:7], s[6:7], 13
	global_load_dwordx2 v[88:89], v[88:89], off nt
	s_nop 0
	global_load_dwordx2 v[92:93], v[90:91], off nt
	s_nop 0
	global_load_dwordx2 v[90:91], v[94:95], off nt
	s_nop 0
	global_load_dwordx2 v[94:95], v[96:97], off nt
	v_lshl_add_u64 v[96:97], v[128:129], 0, s[6:7]
	s_or_b32 s6, s4, 45
	s_ashr_i32 s7, s6, 31
	s_lshl_b64 s[6:7], s[6:7], 13
	v_lshl_add_u64 v[98:99], v[128:129], 0, s[6:7]
	s_or_b32 s6, s4, 46
	s_ashr_i32 s7, s6, 31
	s_lshl_b64 s[6:7], s[6:7], 13
	v_lshl_add_u64 v[102:103], v[128:129], 0, s[6:7]
	s_or_b32 s6, s4, 47
	s_ashr_i32 s7, s6, 31
	s_lshl_b64 s[6:7], s[6:7], 13
	v_lshl_add_u64 v[104:105], v[128:129], 0, s[6:7]
	s_or_b32 s6, s4, 48
	s_ashr_i32 s7, s6, 31
	s_lshl_b64 s[6:7], s[6:7], 13
	global_load_dwordx2 v[96:97], v[96:97], off nt
	s_nop 0
	global_load_dwordx2 v[100:101], v[98:99], off nt
	s_nop 0
	global_load_dwordx2 v[98:99], v[102:103], off nt
	s_nop 0
	global_load_dwordx2 v[102:103], v[104:105], off nt
	v_lshl_add_u64 v[104:105], v[128:129], 0, s[6:7]
	s_or_b32 s6, s4, 49
	s_ashr_i32 s7, s6, 31
	s_lshl_b64 s[6:7], s[6:7], 13
	v_lshl_add_u64 v[106:107], v[128:129], 0, s[6:7]
	s_or_b32 s6, s4, 50
	s_ashr_i32 s7, s6, 31
	s_lshl_b64 s[6:7], s[6:7], 13
	v_lshl_add_u64 v[110:111], v[128:129], 0, s[6:7]
	s_or_b32 s6, s4, 51
	s_ashr_i32 s7, s6, 31
	s_lshl_b64 s[6:7], s[6:7], 13
	v_lshl_add_u64 v[112:113], v[128:129], 0, s[6:7]
	s_or_b32 s6, s4, 52
	s_ashr_i32 s7, s6, 31
	s_lshl_b64 s[6:7], s[6:7], 13
	global_load_dwordx2 v[104:105], v[104:105], off nt
	s_nop 0
	global_load_dwordx2 v[108:109], v[106:107], off nt
	s_nop 0
	global_load_dwordx2 v[106:107], v[110:111], off nt
	s_nop 0
	global_load_dwordx2 v[110:111], v[112:113], off nt
	v_lshl_add_u64 v[112:113], v[128:129], 0, s[6:7]
	s_or_b32 s6, s4, 53
	s_ashr_i32 s7, s6, 31
	s_lshl_b64 s[6:7], s[6:7], 13
	v_lshl_add_u64 v[114:115], v[128:129], 0, s[6:7]
	s_or_b32 s6, s4, 54
	s_ashr_i32 s7, s6, 31
	s_lshl_b64 s[6:7], s[6:7], 13
	v_lshl_add_u64 v[118:119], v[128:129], 0, s[6:7]
	s_or_b32 s6, s4, 55
	s_ashr_i32 s7, s6, 31
	s_lshl_b64 s[6:7], s[6:7], 13
	v_lshl_add_u64 v[120:121], v[128:129], 0, s[6:7]
	s_or_b32 s6, s4, 56
	s_ashr_i32 s7, s6, 31
	s_lshl_b64 s[6:7], s[6:7], 13
	global_load_dwordx2 v[112:113], v[112:113], off nt
	s_nop 0
	global_load_dwordx2 v[116:117], v[114:115], off nt
	s_nop 0
	global_load_dwordx2 v[114:115], v[118:119], off nt
	s_nop 0
	global_load_dwordx2 v[118:119], v[120:121], off nt
	v_lshl_add_u64 v[120:121], v[128:129], 0, s[6:7]
	s_or_b32 s6, s4, 57
	s_ashr_i32 s7, s6, 31
	s_lshl_b64 s[6:7], s[6:7], 13
	v_lshl_add_u64 v[122:123], v[128:129], 0, s[6:7]
	s_or_b32 s6, s4, 58
	s_ashr_i32 s7, s6, 31
	s_lshl_b64 s[6:7], s[6:7], 13
	v_lshl_add_u64 v[126:127], v[128:129], 0, s[6:7]
	s_or_b32 s6, s4, 59
	s_ashr_i32 s7, s6, 31
	s_lshl_b64 s[6:7], s[6:7], 13
	v_lshl_add_u64 v[130:131], v[128:129], 0, s[6:7]
	s_or_b32 s6, s4, 60
	s_ashr_i32 s7, s6, 31
	s_lshl_b64 s[6:7], s[6:7], 13
	global_load_dwordx2 v[120:121], v[120:121], off nt
	s_nop 0
	global_load_dwordx2 v[124:125], v[122:123], off nt
	s_nop 0
	global_load_dwordx2 v[122:123], v[126:127], off nt
	s_nop 0
	global_load_dwordx2 v[126:127], v[130:131], off nt
	v_lshl_add_u64 v[130:131], v[128:129], 0, s[6:7]
	s_or_b32 s6, s4, 61
	s_ashr_i32 s7, s6, 31
	s_lshl_b64 s[6:7], s[6:7], 13
	v_lshl_add_u64 v[132:133], v[128:129], 0, s[6:7]
	s_or_b32 s6, s4, 62
	s_ashr_i32 s7, s6, 31
	s_lshl_b64 s[6:7], s[6:7], 13
	v_lshl_add_u64 v[134:135], v[128:129], 0, s[6:7]
	s_or_b32 s6, s4, 63
	s_ashr_i32 s7, s6, 31
	s_lshl_b64 s[6:7], s[6:7], 13
	v_lshl_add_u64 v[138:139], v[128:129], 0, s[6:7]
	global_load_dwordx2 v[128:129], v[130:131], off nt
	s_nop 0
	global_load_dwordx2 v[132:133], v[132:133], off nt
	s_nop 0
	global_load_dwordx2 v[130:131], v[134:135], off nt
	s_nop 0
	global_load_dwordx2 v[134:135], v[138:139], off nt
	s_and_b64 vcc, exec, s[0:1]
	s_cbranch_vccnz .LBB0_58
	s_lshl_b64 s[6:7], s[4:5], 2
	s_add_u32 s6, s84, s6
	s_addc_u32 s7, s85, s7
	global_load_dwordx4 v[138:141], v136, s[6:7]
	global_load_dwordx4 v[142:145], v136, s[6:7] offset:16
	global_load_dwordx4 v[146:149], v136, s[6:7] offset:32
	global_load_dwordx4 v[150:153], v136, s[6:7] offset:48
	global_load_dwordx4 v[154:157], v136, s[6:7] offset:64
	global_load_dwordx4 v[158:161], v136, s[6:7] offset:80
	global_load_dwordx4 v[162:165], v136, s[6:7] offset:96
	global_load_dwordx4 v[166:169], v136, s[6:7] offset:112
	global_load_dwordx4 v[170:173], v136, s[6:7] offset:128
	global_load_dwordx4 v[174:177], v136, s[6:7] offset:144
	global_load_dwordx4 v[178:181], v136, s[6:7] offset:160
	global_load_dwordx4 v[182:185], v136, s[6:7] offset:176
	global_load_dwordx4 v[186:189], v136, s[6:7] offset:192
	global_load_dwordx4 v[190:193], v136, s[6:7] offset:208
	global_load_dwordx4 v[194:197], v136, s[6:7] offset:224
	global_load_dwordx4 v[198:201], v136, s[6:7] offset:240
	s_waitcnt vmcnt(15)
	v_pk_mul_f32 v[4:5], v[4:5], v[138:139] op_sel_hi:[1,0]
	v_pk_mul_f32 v[8:9], v[8:9], v[138:139] op_sel:[0,1]
	v_mov_b32_e32 v138, v141
	v_pk_mul_f32 v[10:11], v[10:11], v[138:139] op_sel_hi:[1,0]
	v_pk_mul_f32 v[6:7], v[6:7], v[140:141] op_sel_hi:[1,0]
	s_waitcnt vmcnt(14)
	v_pk_mul_f32 v[12:13], v[12:13], v[142:143] op_sel_hi:[1,0]
	v_pk_mul_f32 v[20:21], v[20:21], v[142:143] op_sel:[0,1]
	v_pk_mul_f32 v[18:19], v[18:19], v[144:145] op_sel_hi:[1,0]
	v_mov_b32_e32 v140, v145
	s_waitcnt vmcnt(13)
	v_pk_mul_f32 v[24:25], v[24:25], v[146:147] op_sel_hi:[1,0]
	v_pk_mul_f32 v[28:29], v[28:29], v[146:147] op_sel:[0,1]
	v_pk_mul_f32 v[26:27], v[26:27], v[148:149] op_sel_hi:[1,0]
	v_mov_b32_e32 v142, v149
	s_waitcnt vmcnt(2)
	v_mov_b32_e32 v138, v193
	v_pk_mul_f32 v[118:119], v[118:119], v[138:139] op_sel_hi:[1,0]
	s_waitcnt vmcnt(1)
	v_mov_b32_e32 v138, v197
	v_pk_mul_f32 v[32:33], v[32:33], v[150:151] op_sel_hi:[1,0]
	v_pk_mul_f32 v[36:37], v[36:37], v[150:151] op_sel:[0,1]
	v_pk_mul_f32 v[34:35], v[34:35], v[152:153] op_sel_hi:[1,0]
	v_mov_b32_e32 v144, v153
	v_pk_mul_f32 v[40:41], v[40:41], v[154:155] op_sel_hi:[1,0]
	v_pk_mul_f32 v[44:45], v[44:45], v[154:155] op_sel:[0,1]
	v_pk_mul_f32 v[42:43], v[42:43], v[156:157] op_sel_hi:[1,0]
	v_mov_b32_e32 v146, v157
	v_pk_mul_f32 v[48:49], v[48:49], v[158:159] op_sel_hi:[1,0]
	v_pk_mul_f32 v[52:53], v[52:53], v[158:159] op_sel:[0,1]
	v_pk_mul_f32 v[50:51], v[50:51], v[160:161] op_sel_hi:[1,0]
	v_mov_b32_e32 v148, v161
	v_pk_mul_f32 v[56:57], v[56:57], v[162:163] op_sel_hi:[1,0]
	v_pk_mul_f32 v[60:61], v[60:61], v[162:163] op_sel:[0,1]
	v_mov_b32_e32 v150, v165
	v_mov_b32_e32 v152, v169
	v_mov_b32_e32 v154, v173
	v_mov_b32_e32 v156, v177
	v_mov_b32_e32 v158, v181
	v_mov_b32_e32 v160, v185
	v_mov_b32_e32 v162, v189
	v_pk_mul_f32 v[126:127], v[126:127], v[138:139] op_sel_hi:[1,0]
	s_waitcnt vmcnt(0)
	v_mov_b32_e32 v138, v201
	v_pk_mul_f32 v[58:59], v[58:59], v[164:165] op_sel_hi:[1,0]
	v_pk_mul_f32 v[64:65], v[64:65], v[166:167] op_sel_hi:[1,0]
	v_pk_mul_f32 v[68:69], v[68:69], v[166:167] op_sel:[0,1]
	v_pk_mul_f32 v[66:67], v[66:67], v[168:169] op_sel_hi:[1,0]
	v_pk_mul_f32 v[72:73], v[72:73], v[170:171] op_sel_hi:[1,0]
	v_pk_mul_f32 v[76:77], v[76:77], v[170:171] op_sel:[0,1]
	v_pk_mul_f32 v[74:75], v[74:75], v[172:173] op_sel_hi:[1,0]
	v_pk_mul_f32 v[80:81], v[80:81], v[174:175] op_sel_hi:[1,0]
	v_pk_mul_f32 v[84:85], v[84:85], v[174:175] op_sel:[0,1]
	v_pk_mul_f32 v[82:83], v[82:83], v[176:177] op_sel_hi:[1,0]
	v_pk_mul_f32 v[88:89], v[88:89], v[178:179] op_sel_hi:[1,0]
	v_pk_mul_f32 v[92:93], v[92:93], v[178:179] op_sel:[0,1]
	v_pk_mul_f32 v[90:91], v[90:91], v[180:181] op_sel_hi:[1,0]
	v_pk_mul_f32 v[96:97], v[96:97], v[182:183] op_sel_hi:[1,0]
	v_pk_mul_f32 v[100:101], v[100:101], v[182:183] op_sel:[0,1]
	v_pk_mul_f32 v[98:99], v[98:99], v[184:185] op_sel_hi:[1,0]
	v_pk_mul_f32 v[104:105], v[104:105], v[186:187] op_sel_hi:[1,0]
	v_pk_mul_f32 v[108:109], v[108:109], v[186:187] op_sel:[0,1]
	v_pk_mul_f32 v[106:107], v[106:107], v[188:189] op_sel_hi:[1,0]
	v_pk_mul_f32 v[112:113], v[112:113], v[190:191] op_sel_hi:[1,0]
	v_pk_mul_f32 v[22:23], v[22:23], v[140:141] op_sel_hi:[1,0]
	v_pk_mul_f32 v[30:31], v[30:31], v[142:143] op_sel_hi:[1,0]
	v_pk_mul_f32 v[38:39], v[38:39], v[144:145] op_sel_hi:[1,0]
	v_pk_mul_f32 v[46:47], v[46:47], v[146:147] op_sel_hi:[1,0]
	v_pk_mul_f32 v[54:55], v[54:55], v[148:149] op_sel_hi:[1,0]
	v_pk_mul_f32 v[62:63], v[62:63], v[150:151] op_sel_hi:[1,0]
	v_pk_mul_f32 v[70:71], v[70:71], v[152:153] op_sel_hi:[1,0]
	v_pk_mul_f32 v[78:79], v[78:79], v[154:155] op_sel_hi:[1,0]
	v_pk_mul_f32 v[86:87], v[86:87], v[156:157] op_sel_hi:[1,0]
	v_pk_mul_f32 v[94:95], v[94:95], v[158:159] op_sel_hi:[1,0]
	v_pk_mul_f32 v[102:103], v[102:103], v[160:161] op_sel_hi:[1,0]
	v_pk_mul_f32 v[110:111], v[110:111], v[162:163] op_sel_hi:[1,0]
	v_pk_mul_f32 v[116:117], v[116:117], v[190:191] op_sel:[0,1]
	v_pk_mul_f32 v[114:115], v[114:115], v[192:193] op_sel_hi:[1,0]
	v_pk_mul_f32 v[120:121], v[120:121], v[194:195] op_sel_hi:[1,0]
	v_pk_mul_f32 v[124:125], v[124:125], v[194:195] op_sel:[0,1]
	v_pk_mul_f32 v[122:123], v[122:123], v[196:197] op_sel_hi:[1,0]
	v_pk_mul_f32 v[128:129], v[128:129], v[198:199] op_sel_hi:[1,0]
	v_pk_mul_f32 v[132:133], v[132:133], v[198:199] op_sel:[0,1]
	v_pk_mul_f32 v[130:131], v[130:131], v[200:201] op_sel_hi:[1,0]
	v_pk_mul_f32 v[134:135], v[134:135], v[138:139] op_sel_hi:[1,0]
	s_branch .LBB0_58

.LBB0_64:
	s_waitcnt lgkmcnt(0)
	global_load_dwordx4 v[16:19], v[6:7], off offset:-2048 nt
	global_load_dwordx4 v[30:33], v[6:7], off offset:-1024 nt
	global_load_dwordx4 v[34:37], v[6:7], off nt
	global_load_dwordx4 v[38:41], v[6:7], off offset:1024 nt
	v_lshl_add_u64 v[20:21], s[46:47], 0, v[4:5]
	v_add_co_u32_e32 v20, vcc, 0xe200000, v20
	s_waitcnt vmcnt(3)
	v_cvt_pk_bf16_f32 v22, v16, v17
	v_addc_co_u32_e32 v21, vcc, 0, v21, vcc
	v_cvt_pk_bf16_f32 v23, v18, v19
	global_store_dwordx2 v[20:21], v[22:23], off
	v_lshlrev_b32_e32 v28, 16, v22
	v_and_b32_e32 v22, 0xffff0000, v22
	v_lshlrev_b32_e32 v29, 16, v23
	v_and_b32_e32 v23, 0xffff0000, v23
	v_mul_f32_e32 v22, v22, v22
	v_mul_f32_e32 v23, v23, v23
	v_fmac_f32_e32 v22, v28, v28
	v_fmac_f32_e32 v23, v29, v29
	v_add_f32_e32 v22, v22, v23
	s_waitcnt vmcnt(3)
	v_cvt_pk_bf16_f32 v24, v30, v31
	v_cvt_pk_bf16_f32 v25, v32, v33
	global_store_dwordx2 v[20:21], v[24:25], off offset:512
	v_lshlrev_b32_e32 v23, 16, v24
	v_and_b32_e32 v24, 0xffff0000, v24
	v_lshlrev_b32_e32 v28, 16, v25
	v_and_b32_e32 v25, 0xffff0000, v25
	v_mul_f32_e32 v24, v24, v24
	v_mul_f32_e32 v25, v25, v25
	v_fmac_f32_e32 v24, v23, v23
	v_fmac_f32_e32 v25, v28, v28
	v_add_f32_e32 v23, v24, v25
	v_add_f32_e32 v22, v22, v23
	s_waitcnt vmcnt(3)
	v_cvt_pk_bf16_f32 v26, v34, v35
	v_cvt_pk_bf16_f32 v27, v36, v37
	global_store_dwordx2 v[20:21], v[26:27], off offset:1024
	v_lshlrev_b32_e32 v23, 16, v26
	v_and_b32_e32 v24, 0xffff0000, v26
	v_and_b32_e32 v26, 0xffff0000, v27
	v_lshlrev_b32_e32 v25, 16, v27
	v_mul_f32_e32 v24, v24, v24
	v_mul_f32_e32 v26, v26, v26
	v_fmac_f32_e32 v24, v23, v23
	v_fmac_f32_e32 v26, v25, v25
	v_add_f32_e32 v23, v24, v26
	v_add_f32_e32 v24, v22, v23
	s_waitcnt vmcnt(3)
	v_cvt_pk_bf16_f32 v22, v38, v39
	v_cvt_pk_bf16_f32 v23, v40, v41
	v_and_b32_e32 v17, 0xffff0000, v22
	v_and_b32_e32 v19, 0xffff0000, v23
	v_lshlrev_b32_e32 v16, 16, v22
	v_lshlrev_b32_e32 v18, 16, v23
	v_mul_f32_e32 v17, v17, v17
	v_mul_f32_e32 v19, v19, v19
	v_fmac_f32_e32 v17, v16, v16
	v_fmac_f32_e32 v19, v18, v18
	v_add_f32_e32 v16, v17, v19
	v_add_f32_e32 v16, v24, v16
	ds_bpermute_b32 v17, v8, v16
	global_store_dwordx2 v[20:21], v[22:23], off offset:1536
	s_waitcnt lgkmcnt(0)
	v_add_f32_e32 v16, v16, v17
	ds_bpermute_b32 v17, v9, v16
	s_waitcnt lgkmcnt(0)
	v_add_f32_e32 v16, v16, v17
	ds_bpermute_b32 v17, v10, v16
	s_waitcnt lgkmcnt(0)
	v_add_f32_e32 v16, v16, v17
	ds_bpermute_b32 v17, v11, v16
	s_waitcnt lgkmcnt(0)
	v_add_f32_e32 v16, v16, v17
	ds_bpermute_b32 v17, v12, v16
	s_waitcnt lgkmcnt(0)
	v_add_f32_e32 v16, v16, v17
	ds_bpermute_b32 v17, v13, v16
	s_and_saveexec_b64 s[12:13], s[0:1]
	s_cbranch_execz .LBB0_63
	s_waitcnt lgkmcnt(0)
	v_add_f32_e32 v16, v16, v17
	v_lshl_add_u64 v[18:19], s[46:47], 0, v[2:3]
	v_cndmask_b32_e64 v16, 0, v16, s[4:5]
	global_store_dword v[18:19], v16, off
	s_branch .LBB0_63

.Lp8_loop:
	v_lshl_add_u64 v[200:201], v[2:3], 0, s[100:101]
	v_cmp_ge_u64_e32 vcc, s[12:13], v[200:201]
	s_nop 1
	s_and_b64 exec, s[10:11], vcc
	s_cbranch_execz .Lp8_done
	global_load_dwordx4 v[204:207], v[6:7], off nt
	v_lshl_add_u64 v[6:7], v[6:7], 0, s[8:9]
	global_load_dwordx4 v[208:211], v[6:7], off nt
	v_lshl_add_u64 v[6:7], v[6:7], 0, s[8:9]
	global_load_dwordx4 v[212:215], v[6:7], off nt
	v_lshl_add_u64 v[6:7], v[6:7], 0, s[8:9]
	global_load_dwordx4 v[216:219], v[6:7], off nt
	v_lshl_add_u64 v[6:7], v[6:7], 0, s[8:9]
	global_load_dwordx4 v[220:223], v[6:7], off nt
	v_lshl_add_u64 v[6:7], v[6:7], 0, s[8:9]
	global_load_dwordx4 v[224:227], v[6:7], off nt
	v_lshl_add_u64 v[6:7], v[6:7], 0, s[8:9]
	global_load_dwordx4 v[228:231], v[6:7], off nt
	v_lshl_add_u64 v[6:7], v[6:7], 0, s[8:9]
	global_load_dwordx4 v[232:235], v[6:7], off nt
	v_lshl_add_u64 v[6:7], v[6:7], 0, s[8:9]
	v_lshl_add_u64 v[2:3], v[200:201], 0, s[4:5]
	s_waitcnt vmcnt(7)
	v_cvt_pk_bf16_f32 v204, v204, v205
	v_cvt_pk_bf16_f32 v205, v206, v207
	global_store_dwordx2 v[4:5], v[204:205], off
	v_lshl_add_u64 v[4:5], v[4:5], 0, s[6:7]
	s_waitcnt vmcnt(7)
	v_cvt_pk_bf16_f32 v208, v208, v209
	v_cvt_pk_bf16_f32 v209, v210, v211
	global_store_dwordx2 v[4:5], v[208:209], off
	v_lshl_add_u64 v[4:5], v[4:5], 0, s[6:7]
	s_waitcnt vmcnt(7)
	v_cvt_pk_bf16_f32 v212, v212, v213
	v_cvt_pk_bf16_f32 v213, v214, v215
	global_store_dwordx2 v[4:5], v[212:213], off
	v_lshl_add_u64 v[4:5], v[4:5], 0, s[6:7]
	s_waitcnt vmcnt(7)
	v_cvt_pk_bf16_f32 v216, v216, v217
	v_cvt_pk_bf16_f32 v217, v218, v219
	global_store_dwordx2 v[4:5], v[216:217], off
	v_lshl_add_u64 v[4:5], v[4:5], 0, s[6:7]
	s_waitcnt vmcnt(7)
	v_cvt_pk_bf16_f32 v220, v220, v221
	v_cvt_pk_bf16_f32 v221, v222, v223
	global_store_dwordx2 v[4:5], v[220:221], off
	v_lshl_add_u64 v[4:5], v[4:5], 0, s[6:7]
	s_waitcnt vmcnt(7)
	v_cvt_pk_bf16_f32 v224, v224, v225
	v_cvt_pk_bf16_f32 v225, v226, v227
	global_store_dwordx2 v[4:5], v[224:225], off
	v_lshl_add_u64 v[4:5], v[4:5], 0, s[6:7]
	s_waitcnt vmcnt(7)
	v_cvt_pk_bf16_f32 v228, v228, v229
	v_cvt_pk_bf16_f32 v229, v230, v231
	global_store_dwordx2 v[4:5], v[228:229], off
	v_lshl_add_u64 v[4:5], v[4:5], 0, s[6:7]
	s_waitcnt vmcnt(7)
	v_cvt_pk_bf16_f32 v232, v232, v233
	v_cvt_pk_bf16_f32 v233, v234, v235
	global_store_dwordx2 v[4:5], v[232:233], off
	v_lshl_add_u64 v[4:5], v[4:5], 0, s[6:7]
	s_branch .Lp8_loop

.LBB0_68:
	global_load_dwordx4 v[8:11], v[6:7], off nt
	v_lshl_add_u64 v[2:3], v[2:3], 0, s[4:5]
	v_cmp_lt_u64_e32 vcc, s[12:13], v[2:3]
	v_lshl_add_u64 v[6:7], v[6:7], 0, s[8:9]
	s_or_b64 s[10:11], vcc, s[10:11]
	s_waitcnt vmcnt(0)
	v_cvt_pk_bf16_f32 v8, v8, v9
	v_cvt_pk_bf16_f32 v9, v10, v11
	global_store_dwordx2 v[4:5], v[8:9], off
	v_lshl_add_u64 v[4:5], v[4:5], 0, s[6:7]
	s_andn2_b64 exec, exec, s[10:11]
	s_cbranch_execnz .LBB0_68
